# GEMM epilogues: row-scale shuffle-adds via v_permlane16/32_swap instead of ds_bpermute with per-use lane-id rebuild
# speedup vs baseline: 1.0177x; 1.0037x over previous
.LBB0_406:
	s_mov_b32 s7, s33
	v_lshl_or_b32 v190, s17, 7, v175
	v_mov_b32_e32 v130, s7
	ds_read2_b32 v[130:131], v130 offset1:1
	s_ashr_i32 s17, s16, 31
	s_lshl_b64 s[16:17], s[16:17], 8
	v_lshl_add_u64 v[170:171], s[16:17], 0, v[158:159]
	v_lshlrev_b64 v[132:133], 6, v[170:171]
	s_waitcnt lgkmcnt(0)
	v_readfirstlane_b32 s7, v130
	v_readfirstlane_b32 s9, v131
	v_mov_b32_e32 v186, s7
	s_mov_b32 s7, s33
	v_mov_b32_e32 v187, s9
	v_mov_b32_e32 v130, s7
	ds_read2_b32 v[130:131], v130 offset1:1
	v_ashrrev_i32_e32 v191, 31, v190
	v_mov_b64_e32 v[218:219], v[230:231]
	s_waitcnt lgkmcnt(0)
	v_readfirstlane_b32 s18, v130
	v_readfirstlane_b32 s19, v131
	s_nop 1
	v_lshl_add_u64 v[130:131], s[18:19], 0, v[0:1]
	v_lshl_add_u64 v[130:131], v[130:131], 0, v[132:133]
	v_add_co_u32_e32 v134, vcc, s58, v130
	s_mov_b64 s[18:19], 0x10380000
	s_nop 0
	v_addc_co_u32_e32 v135, vcc, 0, v131, vcc
	v_lshl_add_u64 v[132:133], v[130:131], 0, s[18:19]
	global_load_dwordx4 v[192:195], v[134:135], off
	global_load_dwordx4 v[196:199], v[132:133], off offset:1024
	global_load_dwordx4 v[200:203], v[132:133], off offset:2048
	global_load_dwordx4 v[146:149], v[132:133], off offset:3072
	v_add_co_u32_e32 v130, vcc, s59, v130
	s_mov_b64 s[18:19], 0xaa00000
	s_nop 0
	v_addc_co_u32_e32 v131, vcc, 0, v131, vcc
	global_load_dwordx4 v[142:145], v[130:131], off
	global_load_dwordx4 v[138:141], v[130:131], off offset:1024
	global_load_dwordx4 v[134:137], v[130:131], off offset:2048
	s_nop 0
	global_load_dwordx4 v[130:133], v[130:131], off offset:3072
	s_andn2_b64 vcc, exec, s[0:1]
	s_waitcnt vmcnt(0)
	v_mov_b32_e32 v176, v193
	v_mov_b32_e32 v177, v194
	v_mov_b32_e32 v193, v195
	v_pk_add_f32 v[176:177], v[176:177], v[192:193]
	s_nop 0
	v_add_f32_e32 v172, v176, v177
	v_mov_b32_e32 v174, v172
	s_nop 1
	v_permlane16_swap_b32_e32 v174, v172
	v_mov_b32_e32 v176, v197
	v_mov_b32_e32 v177, v198
	v_mov_b32_e32 v197, v199
	v_pk_add_f32 v[176:177], v[176:177], v[196:197]
	s_waitcnt lgkmcnt(0)
	v_add_f32_e32 v172, v172, v174
	s_nop 0
	v_mov_b32_e32 v174, v172
	s_nop 1
	v_permlane32_swap_b32_e32 v174, v172
	s_waitcnt lgkmcnt(0)
	v_add_f32_e32 v172, v172, v174
	v_fmamk_f32 v172, v172, 0x3a800000, v228
	v_rsq_f32_e32 v188, v172
	v_add_f32_e32 v172, v176, v177
	v_mov_b32_e32 v174, v172
	s_nop 1
	v_permlane16_swap_b32_e32 v174, v172
	v_mov_b32_e32 v176, v201
	v_mov_b32_e32 v177, v202
	v_mov_b32_e32 v201, v203
	v_pk_add_f32 v[176:177], v[176:177], v[200:201]
	s_waitcnt lgkmcnt(0)
	v_add_f32_e32 v172, v172, v174
	v_pk_mul_f32 v[126:127], v[126:127], v[188:189] op_sel_hi:[1,0]
	v_mov_b32_e32 v174, v172
	s_nop 1
	v_permlane32_swap_b32_e32 v174, v172
	v_pk_mul_f32 v[122:123], v[122:123], v[188:189] op_sel_hi:[1,0]
	v_pk_mul_f32 v[124:125], v[124:125], v[188:189] op_sel_hi:[1,0]
	v_pk_mul_f32 v[118:119], v[118:119], v[188:189] op_sel_hi:[1,0]
	v_pk_mul_f32 v[114:115], v[114:115], v[188:189] op_sel_hi:[1,0]
	s_waitcnt lgkmcnt(0)
	v_add_f32_e32 v172, v172, v174
	v_fmamk_f32 v172, v172, 0x3a800000, v228
	v_rsq_f32_e32 v174, v172
	v_add_f32_e32 v172, v176, v177
	v_mov_b32_e32 v177, v148
	v_mov_b32_e32 v176, v172
	s_nop 1
	v_permlane16_swap_b32_e32 v176, v172
	v_mov_b32_e32 v148, v143
	v_mov_b32_e32 v143, v145
	v_mov_b32_e32 v145, v140
	v_mov_b32_e32 v140, v135
	s_waitcnt lgkmcnt(0)
	v_add_f32_e32 v172, v172, v176
	v_mov_b32_e32 v135, v137
	v_mov_b32_e32 v176, v172
	s_nop 1
	v_permlane32_swap_b32_e32 v176, v172
	v_mov_b32_e32 v137, v132
	v_pk_mul_f32 v[116:117], v[116:117], v[188:189] op_sel_hi:[1,0]
	v_pk_mul_f32 v[110:111], v[110:111], v[174:175] op_sel_hi:[1,0]
	v_pk_mul_f32 v[106:107], v[106:107], v[174:175] op_sel_hi:[1,0]
	s_waitcnt lgkmcnt(0)
	v_add_f32_e32 v172, v172, v176
	v_mov_b32_e32 v176, v147
	v_mov_b32_e32 v147, v149
	v_pk_add_f32 v[146:147], v[176:177], v[146:147]
	v_mov_b32_e32 v149, v144
	v_add_f32_e32 v146, v146, v147
	v_pk_add_f32 v[142:143], v[148:149], v[142:143]
	v_mov_b32_e32 v147, v146
	s_nop 1
	v_permlane16_swap_b32_e32 v147, v146
	v_add_f32_e32 v142, v142, v143
	v_mov_b32_e32 v144, v139
	v_mov_b32_e32 v139, v141
	s_waitcnt lgkmcnt(0)
	v_add_f32_e32 v146, v146, v147
	v_mov_b32_e32 v147, v1
	v_mov_b32_e32 v141, v136
	v_mov_b32_e32 v143, v142
	s_nop 1
	v_permlane16_swap_b32_e32 v143, v142
	v_mov_b32_e32 v136, v131
	v_mov_b32_e32 v131, v133
	v_mul_f32_e32 v133, 0xbfb8aa3b, v126
	v_exp_f32_e32 v133, v133
	v_pk_add_f32 v[138:139], v[144:145], v[138:139]
	s_waitcnt lgkmcnt(0)
	v_add_f32_e32 v142, v142, v143
	v_mov_b32_e32 v143, v1
	v_add_f32_e32 v138, v138, v139
	v_add_f32_e32 v133, 1.0, v133
	v_pk_add_f32 v[130:131], v[136:137], v[130:131]
	v_rcp_f32_e32 v136, v133
	v_mul_f32_e32 v133, 0xbfb8aa3b, v127
	v_exp_f32_e32 v133, v133
	v_mov_b32_e32 v139, v138
	s_nop 1
	v_permlane16_swap_b32_e32 v139, v138
	v_add_f32_e32 v133, 1.0, v133
	v_rcp_f32_e32 v137, v133
	v_pk_add_f32 v[134:135], v[140:141], v[134:135]
	v_add_f32_e32 v130, v130, v131
	s_waitcnt lgkmcnt(0)
	v_add_f32_e32 v138, v138, v139
	v_mov_b32_e32 v139, v1
	v_add_f32_e32 v134, v134, v135
	v_pk_mul_f32 v[126:127], v[126:127], v[136:137]
	v_pk_mul_f32 v[122:123], v[122:123], v[126:127]
	v_pk_mul_f32 v[126:127], v[128:129], v[188:189] op_sel_hi:[1,0]
	v_mul_f32_e32 v128, 0xbfb8aa3b, v126
	v_mul_f32_e32 v129, 0xbfb8aa3b, v127
	v_exp_f32_e32 v128, v128
	v_exp_f32_e32 v129, v129
	v_mov_b32_e32 v135, v134
	s_nop 1
	v_permlane16_swap_b32_e32 v135, v134
	v_add_f32_e32 v128, 1.0, v128
	v_add_f32_e32 v129, 1.0, v129
	v_rcp_f32_e32 v128, v128
	v_rcp_f32_e32 v129, v129
	s_waitcnt lgkmcnt(0)
	v_add_f32_e32 v134, v134, v135
	v_mov_b32_e32 v135, v1
	v_pk_mul_f32 v[126:127], v[126:127], v[128:129]
	v_pk_mul_f32 v[124:125], v[124:125], v[126:127]
	v_mul_f32_e32 v126, 0xbfb8aa3b, v118
	v_mul_f32_e32 v127, 0xbfb8aa3b, v119
	v_exp_f32_e32 v126, v126
	v_exp_f32_e32 v127, v127
	v_mov_b32_e32 v131, v130
	s_nop 1
	v_permlane16_swap_b32_e32 v131, v130
	v_add_f32_e32 v126, 1.0, v126
	v_add_f32_e32 v127, 1.0, v127
	v_rcp_f32_e32 v126, v126
	v_rcp_f32_e32 v127, v127
	s_waitcnt lgkmcnt(0)
	v_add_f32_e32 v130, v130, v131
	v_pk_mul_f32 v[118:119], v[118:119], v[126:127]
	v_pk_mul_f32 v[118:119], v[114:115], v[118:119]
	v_pk_mul_f32 v[114:115], v[120:121], v[188:189] op_sel_hi:[1,0]
	v_mul_f32_e32 v120, 0xbfb8aa3b, v114
	v_mul_f32_e32 v121, 0xbfb8aa3b, v115
	v_exp_f32_e32 v120, v120
	v_exp_f32_e32 v121, v121
	v_mov_b32_e32 v131, v130
	s_nop 1
	v_permlane32_swap_b32_e32 v131, v130
	v_pk_mul_f32 v[108:109], v[108:109], v[174:175] op_sel_hi:[1,0]
	v_add_f32_e32 v120, 1.0, v120
	v_add_f32_e32 v121, 1.0, v121
	v_rcp_f32_e32 v120, v120
	v_rcp_f32_e32 v121, v121
	s_waitcnt lgkmcnt(0)
	v_add_f32_e32 v130, v130, v131
	v_fmamk_f32 v130, v130, 0x3a800000, v228
	v_rsq_f32_e32 v132, v130
	v_lshl_add_u64 v[130:131], v[190:191], 1, v[186:187]
	v_lshl_add_u64 v[130:131], v[130:131], 0, s[18:19]
	v_pk_mul_f32 v[114:115], v[114:115], v[120:121]
	v_pk_mul_f32 v[102:103], v[102:103], v[174:175] op_sel_hi:[1,0]
	v_pk_mul_f32 v[120:121], v[116:117], v[114:115]
	v_cvt_pk_bf16_f32 v116, v118, v119
	v_mad_u64_u32 v[118:119], s[18:19], v170, s89, v[130:131]
	v_cvt_pk_bf16_f32 v117, v120, v121
	v_mov_b32_e32 v120, v119
	v_mad_u64_u32 v[120:121], s[18:19], v171, s89, v[120:121]
	v_cvt_pk_bf16_f32 v114, v122, v123
	v_cvt_pk_bf16_f32 v115, v124, v125
	v_mov_b32_e32 v119, v120
	global_store_dwordx4 v[118:119], v[114:117], off sc1
	v_pk_mul_f32 v[98:99], v[98:99], v[174:175] op_sel_hi:[1,0]
	v_fmamk_f32 v172, v172, 0x3a800000, v228
	v_mul_f32_e32 v114, 0xbfb8aa3b, v110
	v_mul_f32_e32 v115, 0xbfb8aa3b, v111
	v_exp_f32_e32 v114, v114
	v_exp_f32_e32 v115, v115
	v_rsq_f32_e32 v172, v172
	v_pk_mul_f32 v[100:101], v[100:101], v[174:175] op_sel_hi:[1,0]
	v_add_f32_e32 v114, 1.0, v114
	v_add_f32_e32 v115, 1.0, v115
	v_rcp_f32_e32 v114, v114
	v_rcp_f32_e32 v115, v115
	v_pk_mul_f32 v[94:95], v[94:95], v[172:173] op_sel_hi:[1,0]
	v_pk_mul_f32 v[90:91], v[90:91], v[172:173] op_sel_hi:[1,0]
	v_pk_mul_f32 v[92:93], v[92:93], v[172:173] op_sel_hi:[1,0]
	v_pk_mul_f32 v[110:111], v[110:111], v[114:115]
	v_pk_mul_f32 v[86:87], v[86:87], v[172:173] op_sel_hi:[1,0]
	v_pk_mul_f32 v[106:107], v[106:107], v[110:111]
	v_pk_mul_f32 v[110:111], v[112:113], v[174:175] op_sel_hi:[1,0]
	v_pk_mul_f32 v[82:83], v[82:83], v[172:173] op_sel_hi:[1,0]
	v_mul_f32_e32 v112, 0xbfb8aa3b, v110
	v_mul_f32_e32 v113, 0xbfb8aa3b, v111
	v_exp_f32_e32 v112, v112
	v_exp_f32_e32 v113, v113
	v_mbcnt_lo_u32_b32 v147, -1, v147
	v_mbcnt_hi_u32_b32 v147, -1, v147
	v_add_f32_e32 v112, 1.0, v112
	v_add_f32_e32 v113, 1.0, v113
	v_rcp_f32_e32 v112, v112
	v_rcp_f32_e32 v113, v113
	v_lshlrev_b32_e32 v147, 2, v147
	v_xor_b32_e32 v147, 0x80, v147
	ds_bpermute_b32 v147, v147, v146
	v_pk_mul_f32 v[110:111], v[110:111], v[112:113]
	v_pk_mul_f32 v[84:85], v[84:85], v[172:173] op_sel_hi:[1,0]
	v_pk_mul_f32 v[108:109], v[108:109], v[110:111]
	v_mul_f32_e32 v110, 0xbfb8aa3b, v102
	v_mul_f32_e32 v111, 0xbfb8aa3b, v103
	v_exp_f32_e32 v110, v110
	v_exp_f32_e32 v111, v111
	s_waitcnt lgkmcnt(0)
	v_add_f32_e32 v146, v146, v147
	v_fmamk_f32 v146, v146, 0x3a800000, v228
	v_add_f32_e32 v110, 1.0, v110
	v_add_f32_e32 v111, 1.0, v111
	v_rcp_f32_e32 v110, v110
	v_rcp_f32_e32 v111, v111
	v_rsq_f32_e32 v146, v146
	v_mbcnt_lo_u32_b32 v143, -1, v143
	v_mbcnt_hi_u32_b32 v143, -1, v143
	v_pk_mul_f32 v[102:103], v[102:103], v[110:111]
	v_lshl_add_u64 v[110:111], v[160:161], 0, s[16:17]
	v_pk_mul_f32 v[102:103], v[98:99], v[102:103]
	v_pk_mul_f32 v[98:99], v[104:105], v[174:175] op_sel_hi:[1,0]
	v_pk_mul_f32 v[78:79], v[78:79], v[146:147] op_sel_hi:[1,0]
	v_mul_f32_e32 v104, 0xbfb8aa3b, v98
	v_mul_f32_e32 v105, 0xbfb8aa3b, v99
	v_exp_f32_e32 v104, v104
	v_exp_f32_e32 v105, v105
	v_pk_mul_f32 v[74:75], v[74:75], v[146:147] op_sel_hi:[1,0]
	v_pk_mul_f32 v[76:77], v[76:77], v[146:147] op_sel_hi:[1,0]
	v_add_f32_e32 v104, 1.0, v104
	v_add_f32_e32 v105, 1.0, v105
	v_rcp_f32_e32 v104, v104
	v_rcp_f32_e32 v105, v105
	v_pk_mul_f32 v[70:71], v[70:71], v[146:147] op_sel_hi:[1,0]
	v_pk_mul_f32 v[66:67], v[66:67], v[146:147] op_sel_hi:[1,0]
	v_lshlrev_b32_e32 v143, 2, v143
	v_pk_mul_f32 v[98:99], v[98:99], v[104:105]
	v_xor_b32_e32 v143, 0x80, v143
	v_pk_mul_f32 v[104:105], v[100:101], v[98:99]
	v_cvt_pk_bf16_f32 v100, v102, v103
	v_mad_u64_u32 v[102:103], s[18:19], v110, s89, v[130:131]
	v_cvt_pk_bf16_f32 v101, v104, v105
	v_mov_b32_e32 v104, v103
	v_mad_u64_u32 v[104:105], s[18:19], v111, s89, v[104:105]
	v_cvt_pk_bf16_f32 v98, v106, v107
	v_cvt_pk_bf16_f32 v99, v108, v109
	v_mov_b32_e32 v103, v104
	global_store_dwordx4 v[102:103], v[98:101], off sc1
	ds_bpermute_b32 v143, v143, v142
	v_pk_mul_f32 v[68:69], v[68:69], v[146:147] op_sel_hi:[1,0]
	v_mul_f32_e32 v98, 0xbfb8aa3b, v94
	v_mul_f32_e32 v99, 0xbfb8aa3b, v95
	v_exp_f32_e32 v98, v98
	v_exp_f32_e32 v99, v99
	s_waitcnt lgkmcnt(0)
	v_add_f32_e32 v142, v142, v143
	v_fmamk_f32 v142, v142, 0x3a800000, v228
	v_add_f32_e32 v98, 1.0, v98
	v_add_f32_e32 v99, 1.0, v99
	v_rcp_f32_e32 v98, v98
	v_rcp_f32_e32 v99, v99
	v_rsq_f32_e32 v142, v142
	v_mbcnt_lo_u32_b32 v139, -1, v139
	v_mbcnt_hi_u32_b32 v139, -1, v139
	v_pk_mul_f32 v[94:95], v[94:95], v[98:99]
	v_pk_mul_f32 v[62:63], v[62:63], v[142:143] op_sel_hi:[1,0]
	v_pk_mul_f32 v[90:91], v[90:91], v[94:95]
	v_pk_mul_f32 v[94:95], v[96:97], v[172:173] op_sel_hi:[1,0]
	v_pk_mul_f32 v[58:59], v[58:59], v[142:143] op_sel_hi:[1,0]
	v_mul_f32_e32 v96, 0xbfb8aa3b, v94
	v_mul_f32_e32 v97, 0xbfb8aa3b, v95
	v_exp_f32_e32 v96, v96
	v_exp_f32_e32 v97, v97
	v_pk_mul_f32 v[60:61], v[60:61], v[142:143] op_sel_hi:[1,0]
	v_pk_mul_f32 v[54:55], v[54:55], v[142:143] op_sel_hi:[1,0]
	v_add_f32_e32 v96, 1.0, v96
	v_add_f32_e32 v97, 1.0, v97
	v_rcp_f32_e32 v96, v96
	v_rcp_f32_e32 v97, v97
	v_pk_mul_f32 v[50:51], v[50:51], v[142:143] op_sel_hi:[1,0]
	v_lshlrev_b32_e32 v139, 2, v139
	v_xor_b32_e32 v139, 0x80, v139
	v_pk_mul_f32 v[94:95], v[94:95], v[96:97]
	ds_bpermute_b32 v139, v139, v138
	v_pk_mul_f32 v[92:93], v[92:93], v[94:95]
	v_mul_f32_e32 v94, 0xbfb8aa3b, v86
	v_mul_f32_e32 v95, 0xbfb8aa3b, v87
	v_exp_f32_e32 v94, v94
	v_exp_f32_e32 v95, v95
	s_waitcnt lgkmcnt(0)
	v_add_f32_e32 v138, v138, v139
	v_fmamk_f32 v138, v138, 0x3a800000, v228
	v_add_f32_e32 v94, 1.0, v94
	v_add_f32_e32 v95, 1.0, v95
	v_rcp_f32_e32 v94, v94
	v_rcp_f32_e32 v95, v95
	v_rsq_f32_e32 v138, v138
	v_pk_mul_f32 v[52:53], v[52:53], v[142:143] op_sel_hi:[1,0]
	v_mbcnt_lo_u32_b32 v135, -1, v135
	v_pk_mul_f32 v[86:87], v[86:87], v[94:95]
	v_lshl_add_u64 v[94:95], v[162:163], 0, s[16:17]
	v_pk_mul_f32 v[86:87], v[82:83], v[86:87]
	v_pk_mul_f32 v[82:83], v[88:89], v[172:173] op_sel_hi:[1,0]
	v_pk_mul_f32 v[46:47], v[46:47], v[138:139] op_sel_hi:[1,0]
	v_mul_f32_e32 v88, 0xbfb8aa3b, v82
	v_mul_f32_e32 v89, 0xbfb8aa3b, v83
	v_exp_f32_e32 v88, v88
	v_exp_f32_e32 v89, v89
	v_pk_mul_f32 v[42:43], v[42:43], v[138:139] op_sel_hi:[1,0]
	v_pk_mul_f32 v[44:45], v[44:45], v[138:139] op_sel_hi:[1,0]
	v_add_f32_e32 v88, 1.0, v88
	v_add_f32_e32 v89, 1.0, v89
	v_rcp_f32_e32 v88, v88
	v_rcp_f32_e32 v89, v89
	v_pk_mul_f32 v[38:39], v[38:39], v[138:139] op_sel_hi:[1,0]
	v_pk_mul_f32 v[34:35], v[34:35], v[138:139] op_sel_hi:[1,0]
	v_mbcnt_hi_u32_b32 v135, -1, v135
	v_pk_mul_f32 v[82:83], v[82:83], v[88:89]
	v_lshlrev_b32_e32 v135, 2, v135
	v_pk_mul_f32 v[88:89], v[84:85], v[82:83]
	v_cvt_pk_bf16_f32 v84, v86, v87
	v_mad_u64_u32 v[86:87], s[18:19], v94, s89, v[130:131]
	v_cvt_pk_bf16_f32 v85, v88, v89
	v_mov_b32_e32 v88, v87
	v_mad_u64_u32 v[88:89], s[18:19], v95, s89, v[88:89]
	v_cvt_pk_bf16_f32 v82, v90, v91
	v_cvt_pk_bf16_f32 v83, v92, v93
	v_mov_b32_e32 v87, v88
	global_store_dwordx4 v[86:87], v[82:85], off sc1
	v_xor_b32_e32 v135, 0x80, v135
	ds_bpermute_b32 v135, v135, v134
	v_mul_f32_e32 v82, 0xbfb8aa3b, v78
	v_mul_f32_e32 v83, 0xbfb8aa3b, v79
	v_exp_f32_e32 v82, v82
	v_exp_f32_e32 v83, v83
	s_waitcnt lgkmcnt(0)
	v_add_f32_e32 v134, v134, v135
	v_fmamk_f32 v134, v134, 0x3a800000, v228
	v_add_f32_e32 v82, 1.0, v82
	v_add_f32_e32 v83, 1.0, v83
	v_rcp_f32_e32 v82, v82
	v_rcp_f32_e32 v83, v83
	v_rsq_f32_e32 v134, v134
	v_pk_mul_f32 v[36:37], v[36:37], v[138:139] op_sel_hi:[1,0]
	v_pk_mul_f32 v[14:15], v[14:15], v[132:133] op_sel_hi:[1,0]
	v_pk_mul_f32 v[78:79], v[78:79], v[82:83]
	v_pk_mul_f32 v[30:31], v[30:31], v[134:135] op_sel_hi:[1,0]
	v_pk_mul_f32 v[74:75], v[74:75], v[78:79]
	v_pk_mul_f32 v[78:79], v[80:81], v[146:147] op_sel_hi:[1,0]
	v_pk_mul_f32 v[26:27], v[26:27], v[134:135] op_sel_hi:[1,0]
	v_mul_f32_e32 v80, 0xbfb8aa3b, v78
	v_mul_f32_e32 v81, 0xbfb8aa3b, v79
	v_exp_f32_e32 v80, v80
	v_exp_f32_e32 v81, v81
	v_pk_mul_f32 v[28:29], v[28:29], v[134:135] op_sel_hi:[1,0]
	v_pk_mul_f32 v[22:23], v[22:23], v[134:135] op_sel_hi:[1,0]
	v_add_f32_e32 v80, 1.0, v80
	v_add_f32_e32 v81, 1.0, v81
	v_rcp_f32_e32 v80, v80
	v_rcp_f32_e32 v81, v81
	v_pk_mul_f32 v[18:19], v[18:19], v[134:135] op_sel_hi:[1,0]
	v_pk_mul_f32 v[20:21], v[20:21], v[134:135] op_sel_hi:[1,0]
	v_pk_mul_f32 v[10:11], v[10:11], v[132:133] op_sel_hi:[1,0]
	v_pk_mul_f32 v[78:79], v[78:79], v[80:81]
	v_pk_mul_f32 v[12:13], v[12:13], v[132:133] op_sel_hi:[1,0]
	v_pk_mul_f32 v[76:77], v[76:77], v[78:79]
	v_mul_f32_e32 v78, 0xbfb8aa3b, v70
	v_mul_f32_e32 v79, 0xbfb8aa3b, v71
	v_exp_f32_e32 v78, v78
	v_exp_f32_e32 v79, v79
	v_pk_mul_f32 v[6:7], v[6:7], v[132:133] op_sel_hi:[1,0]
	v_pk_mul_f32 v[2:3], v[2:3], v[132:133] op_sel_hi:[1,0]
	v_add_f32_e32 v78, 1.0, v78
	v_add_f32_e32 v79, 1.0, v79
	v_rcp_f32_e32 v78, v78
	v_rcp_f32_e32 v79, v79
	v_pk_mul_f32 v[4:5], v[4:5], v[132:133] op_sel_hi:[1,0]
	v_pk_mul_f32 v[70:71], v[70:71], v[78:79]
	s_nop 0
	v_pk_mul_f32 v[70:71], v[66:67], v[70:71]
	v_pk_mul_f32 v[66:67], v[72:73], v[146:147] op_sel_hi:[1,0]
	v_lshl_add_u64 v[78:79], v[164:165], 0, s[16:17]
	v_mul_f32_e32 v72, 0xbfb8aa3b, v66
	v_mul_f32_e32 v73, 0xbfb8aa3b, v67
	v_exp_f32_e32 v72, v72
	v_exp_f32_e32 v73, v73
	v_add_f32_e32 v72, 1.0, v72
	v_add_f32_e32 v73, 1.0, v73
	v_rcp_f32_e32 v72, v72
	v_rcp_f32_e32 v73, v73
	s_nop 0
	v_pk_mul_f32 v[66:67], v[66:67], v[72:73]
	s_nop 0
	v_pk_mul_f32 v[72:73], v[68:69], v[66:67]
	v_cvt_pk_bf16_f32 v68, v70, v71
	v_mad_u64_u32 v[70:71], s[16:17], v78, s89, v[130:131]
	v_cvt_pk_bf16_f32 v69, v72, v73
	v_mov_b32_e32 v72, v71
	v_mad_u64_u32 v[72:73], s[16:17], v79, s89, v[72:73]
	v_cvt_pk_bf16_f32 v66, v74, v75
	v_cvt_pk_bf16_f32 v67, v76, v77
	v_mov_b32_e32 v71, v72
	global_store_dwordx4 v[70:71], v[66:69], off sc1
	s_nop 1
	v_mul_f32_e32 v66, 0xbfb8aa3b, v62
	v_mul_f32_e32 v67, 0xbfb8aa3b, v63
	v_exp_f32_e32 v66, v66
	v_exp_f32_e32 v67, v67
	v_add_f32_e32 v66, 1.0, v66
	v_add_f32_e32 v67, 1.0, v67
	v_rcp_f32_e32 v66, v66
	v_rcp_f32_e32 v67, v67
	s_nop 0
	v_pk_mul_f32 v[62:63], v[62:63], v[66:67]
	s_nop 0
	v_pk_mul_f32 v[58:59], v[58:59], v[62:63]
	v_pk_mul_f32 v[62:63], v[64:65], v[142:143] op_sel_hi:[1,0]
	s_nop 0
	v_mul_f32_e32 v64, 0xbfb8aa3b, v62
	v_mul_f32_e32 v65, 0xbfb8aa3b, v63
	v_exp_f32_e32 v64, v64
	v_exp_f32_e32 v65, v65
	v_add_f32_e32 v64, 1.0, v64
	v_add_f32_e32 v65, 1.0, v65
	v_rcp_f32_e32 v64, v64
	v_rcp_f32_e32 v65, v65
	s_nop 0
	v_pk_mul_f32 v[62:63], v[62:63], v[64:65]
	s_nop 0
	v_pk_mul_f32 v[60:61], v[60:61], v[62:63]
	v_mul_f32_e32 v62, 0xbfb8aa3b, v54
	v_mul_f32_e32 v63, 0xbfb8aa3b, v55
	v_exp_f32_e32 v62, v62
	v_exp_f32_e32 v63, v63
	v_add_f32_e32 v62, 1.0, v62
	v_add_f32_e32 v63, 1.0, v63
	v_rcp_f32_e32 v62, v62
	v_rcp_f32_e32 v63, v63
	s_nop 0
	v_pk_mul_f32 v[54:55], v[54:55], v[62:63]
	s_nop 0
	v_pk_mul_f32 v[54:55], v[50:51], v[54:55]
	v_pk_mul_f32 v[50:51], v[56:57], v[142:143] op_sel_hi:[1,0]
	v_lshl_add_u64 v[62:63], v[170:171], 0, s[96:97]
	v_mul_f32_e32 v56, 0xbfb8aa3b, v50
	v_mul_f32_e32 v57, 0xbfb8aa3b, v51
	v_exp_f32_e32 v56, v56
	v_exp_f32_e32 v57, v57
	v_add_f32_e32 v56, 1.0, v56
	v_add_f32_e32 v57, 1.0, v57
	v_rcp_f32_e32 v56, v56
	v_rcp_f32_e32 v57, v57
	s_nop 0
	v_pk_mul_f32 v[50:51], v[50:51], v[56:57]
	s_nop 0
	v_pk_mul_f32 v[56:57], v[52:53], v[50:51]
	v_cvt_pk_bf16_f32 v52, v54, v55
	v_mad_u64_u32 v[54:55], s[16:17], v62, s89, v[130:131]
	v_cvt_pk_bf16_f32 v53, v56, v57
	v_mov_b32_e32 v56, v55
	v_mad_u64_u32 v[56:57], s[16:17], v63, s89, v[56:57]
	v_cvt_pk_bf16_f32 v50, v58, v59
	v_cvt_pk_bf16_f32 v51, v60, v61
	v_mov_b32_e32 v55, v56
	global_store_dwordx4 v[54:55], v[50:53], off sc1
	s_mov_b64 s[16:17], 0x90
	s_nop 0
	v_mul_f32_e32 v50, 0xbfb8aa3b, v46
	v_mul_f32_e32 v51, 0xbfb8aa3b, v47
	v_exp_f32_e32 v50, v50
	v_exp_f32_e32 v51, v51
	v_add_f32_e32 v50, 1.0, v50
	v_add_f32_e32 v51, 1.0, v51
	v_rcp_f32_e32 v50, v50
	v_rcp_f32_e32 v51, v51
	s_nop 0
	v_pk_mul_f32 v[46:47], v[46:47], v[50:51]
	s_nop 0
	v_pk_mul_f32 v[42:43], v[42:43], v[46:47]
	v_pk_mul_f32 v[46:47], v[48:49], v[138:139] op_sel_hi:[1,0]
	s_nop 0
	v_mul_f32_e32 v48, 0xbfb8aa3b, v46
	v_mul_f32_e32 v49, 0xbfb8aa3b, v47
	v_exp_f32_e32 v48, v48
	v_exp_f32_e32 v49, v49
	v_add_f32_e32 v48, 1.0, v48
	v_add_f32_e32 v49, 1.0, v49
	v_rcp_f32_e32 v48, v48
	v_rcp_f32_e32 v49, v49
	s_nop 0
	v_pk_mul_f32 v[46:47], v[46:47], v[48:49]
	s_nop 0
	v_pk_mul_f32 v[44:45], v[44:45], v[46:47]
	v_mul_f32_e32 v46, 0xbfb8aa3b, v38
	v_mul_f32_e32 v47, 0xbfb8aa3b, v39
	v_exp_f32_e32 v46, v46
	v_exp_f32_e32 v47, v47
	v_add_f32_e32 v46, 1.0, v46
	v_add_f32_e32 v47, 1.0, v47
	v_rcp_f32_e32 v46, v46
	v_rcp_f32_e32 v47, v47
	s_nop 0
	v_pk_mul_f32 v[38:39], v[38:39], v[46:47]
	s_nop 0
	v_pk_mul_f32 v[38:39], v[34:35], v[38:39]
	v_pk_mul_f32 v[34:35], v[40:41], v[138:139] op_sel_hi:[1,0]
	v_lshl_add_u64 v[46:47], v[170:171], 0, s[16:17]
	v_mul_f32_e32 v40, 0xbfb8aa3b, v34
	v_mul_f32_e32 v41, 0xbfb8aa3b, v35
	v_exp_f32_e32 v40, v40
	v_exp_f32_e32 v41, v41
	v_add_f32_e32 v40, 1.0, v40
	v_add_f32_e32 v41, 1.0, v41
	v_rcp_f32_e32 v40, v40
	v_rcp_f32_e32 v41, v41
	s_nop 0
	v_pk_mul_f32 v[34:35], v[34:35], v[40:41]
	s_nop 0
	v_pk_mul_f32 v[40:41], v[36:37], v[34:35]
	v_cvt_pk_bf16_f32 v36, v38, v39
	v_mad_u64_u32 v[38:39], s[16:17], v46, s89, v[130:131]
	v_cvt_pk_bf16_f32 v37, v40, v41
	v_mov_b32_e32 v40, v39
	v_mad_u64_u32 v[40:41], s[16:17], v47, s89, v[40:41]
	v_cvt_pk_bf16_f32 v34, v42, v43
	v_cvt_pk_bf16_f32 v35, v44, v45
	v_mov_b32_e32 v39, v40
	global_store_dwordx4 v[38:39], v[34:37], off sc1
	s_mov_b64 s[16:17], 0xa0
	s_nop 0
	v_mul_f32_e32 v34, 0xbfb8aa3b, v30
	v_mul_f32_e32 v35, 0xbfb8aa3b, v31
	v_exp_f32_e32 v34, v34
	v_exp_f32_e32 v35, v35
	v_add_f32_e32 v34, 1.0, v34
	v_add_f32_e32 v35, 1.0, v35
	v_rcp_f32_e32 v34, v34
	v_rcp_f32_e32 v35, v35
	s_nop 0
	v_pk_mul_f32 v[30:31], v[30:31], v[34:35]
	s_nop 0
	v_pk_mul_f32 v[26:27], v[26:27], v[30:31]
	v_pk_mul_f32 v[30:31], v[32:33], v[134:135] op_sel_hi:[1,0]
	s_nop 0
	v_mul_f32_e32 v32, 0xbfb8aa3b, v30
	v_mul_f32_e32 v33, 0xbfb8aa3b, v31
	v_exp_f32_e32 v32, v32
	v_exp_f32_e32 v33, v33
	v_add_f32_e32 v32, 1.0, v32
	v_add_f32_e32 v33, 1.0, v33
	v_rcp_f32_e32 v32, v32
	v_rcp_f32_e32 v33, v33
	s_nop 0
	v_pk_mul_f32 v[30:31], v[30:31], v[32:33]
	s_nop 0
	v_pk_mul_f32 v[28:29], v[28:29], v[30:31]
	v_mul_f32_e32 v30, 0xbfb8aa3b, v22
	v_mul_f32_e32 v31, 0xbfb8aa3b, v23
	v_exp_f32_e32 v30, v30
	v_exp_f32_e32 v31, v31
	v_add_f32_e32 v30, 1.0, v30
	v_add_f32_e32 v31, 1.0, v31
	v_rcp_f32_e32 v30, v30
	v_rcp_f32_e32 v31, v31
	s_nop 0
	v_pk_mul_f32 v[22:23], v[22:23], v[30:31]
	s_nop 0
	v_pk_mul_f32 v[22:23], v[18:19], v[22:23]
	v_pk_mul_f32 v[18:19], v[24:25], v[134:135] op_sel_hi:[1,0]
	v_lshl_add_u64 v[30:31], v[170:171], 0, s[16:17]
	v_mul_f32_e32 v24, 0xbfb8aa3b, v18
	v_mul_f32_e32 v25, 0xbfb8aa3b, v19
	v_exp_f32_e32 v24, v24
	v_exp_f32_e32 v25, v25
	v_add_f32_e32 v24, 1.0, v24
	v_add_f32_e32 v25, 1.0, v25
	v_rcp_f32_e32 v24, v24
	v_rcp_f32_e32 v25, v25
	s_nop 0
	v_pk_mul_f32 v[18:19], v[18:19], v[24:25]
	s_nop 0
	v_pk_mul_f32 v[24:25], v[20:21], v[18:19]
	v_cvt_pk_bf16_f32 v20, v22, v23
	v_mad_u64_u32 v[22:23], s[16:17], v30, s89, v[130:131]
	v_cvt_pk_bf16_f32 v21, v24, v25
	v_mov_b32_e32 v24, v23
	v_mad_u64_u32 v[24:25], s[16:17], v31, s89, v[24:25]
	v_cvt_pk_bf16_f32 v18, v26, v27
	v_cvt_pk_bf16_f32 v19, v28, v29
	v_mov_b32_e32 v23, v24
	global_store_dwordx4 v[22:23], v[18:21], off sc1
	s_mov_b64 s[16:17], 0xb0
	s_nop 0
	v_mul_f32_e32 v18, 0xbfb8aa3b, v14
	v_mul_f32_e32 v19, 0xbfb8aa3b, v15
	v_exp_f32_e32 v18, v18
	v_exp_f32_e32 v19, v19
	v_add_f32_e32 v18, 1.0, v18
	v_add_f32_e32 v19, 1.0, v19
	v_rcp_f32_e32 v18, v18
	v_rcp_f32_e32 v19, v19
	s_nop 0
	v_pk_mul_f32 v[14:15], v[14:15], v[18:19]
	s_nop 0
	v_pk_mul_f32 v[10:11], v[10:11], v[14:15]
	v_pk_mul_f32 v[14:15], v[16:17], v[132:133] op_sel_hi:[1,0]
	s_nop 0
	v_mul_f32_e32 v16, 0xbfb8aa3b, v14
	v_mul_f32_e32 v17, 0xbfb8aa3b, v15
	v_exp_f32_e32 v16, v16
	v_exp_f32_e32 v17, v17
	v_add_f32_e32 v16, 1.0, v16
	v_add_f32_e32 v17, 1.0, v17
	v_rcp_f32_e32 v16, v16
	v_rcp_f32_e32 v17, v17
	s_nop 0
	v_pk_mul_f32 v[14:15], v[14:15], v[16:17]
	s_nop 0
	v_pk_mul_f32 v[12:13], v[12:13], v[14:15]
	v_mul_f32_e32 v14, 0xbfb8aa3b, v6
	v_mul_f32_e32 v15, 0xbfb8aa3b, v7
	v_exp_f32_e32 v14, v14
	v_exp_f32_e32 v15, v15
	v_add_f32_e32 v14, 1.0, v14
	v_add_f32_e32 v15, 1.0, v15
	v_rcp_f32_e32 v14, v14
	v_rcp_f32_e32 v15, v15
	s_nop 0
	v_pk_mul_f32 v[6:7], v[6:7], v[14:15]
	s_nop 0
	v_pk_mul_f32 v[6:7], v[2:3], v[6:7]
	v_pk_mul_f32 v[2:3], v[8:9], v[132:133] op_sel_hi:[1,0]
	v_lshl_add_u64 v[14:15], v[170:171], 0, s[16:17]
	v_mul_f32_e32 v8, 0xbfb8aa3b, v2
	v_mul_f32_e32 v9, 0xbfb8aa3b, v3
	v_exp_f32_e32 v8, v8
	v_exp_f32_e32 v9, v9
	v_add_f32_e32 v8, 1.0, v8
	v_add_f32_e32 v9, 1.0, v9
	v_rcp_f32_e32 v8, v8
	v_rcp_f32_e32 v9, v9
	s_nop 0
	v_pk_mul_f32 v[2:3], v[2:3], v[8:9]
	s_nop 0
	v_pk_mul_f32 v[8:9], v[4:5], v[2:3]
	v_cvt_pk_bf16_f32 v4, v6, v7
	v_mad_u64_u32 v[6:7], s[16:17], v14, s89, v[130:131]
	v_cvt_pk_bf16_f32 v5, v8, v9
	v_mov_b32_e32 v8, v7
	v_mad_u64_u32 v[8:9], s[16:17], v15, s89, v[8:9]
	v_cvt_pk_bf16_f32 v2, v10, v11
	v_cvt_pk_bf16_f32 v3, v12, v13
	v_mov_b32_e32 v7, v8
	s_mov_b64 s[16:17], -1
	global_store_dwordx4 v[6:7], v[2:5], off sc1
	s_cbranch_vccnz .LBB0_399
	s_andn2_b64 vcc, exec, s[2:3]
	s_cbranch_vccnz .LBB0_398
	s_barrier
	s_branch .LBB0_398

.LBB0_801:
	s_mov_b32 s15, s93
	s_mov_b32 s18, s33
	v_mov_b32_e32 v138, s15
	ds_read2_b32 v[138:139], v138 offset1:1
	s_mov_b32 s15, s92
	s_ashr_i32 s15, s14, 31
	s_lshl_b64 s[14:15], s[14:15], 8
	s_waitcnt lgkmcnt(0)
	v_readfirstlane_b32 s16, v138
	v_lshl_or_b32 v138, s43, 8, v155
	v_lshl_add_u64 v[140:141], s[14:15], 0, v[132:133]
	v_readfirstlane_b32 s17, v139
	v_ashrrev_i32_e32 v139, 31, v138
	v_lshlrev_b64 v[144:145], 11, v[140:141]
	v_lshl_add_u64 v[142:143], s[16:17], 0, v[144:145]
	v_lshlrev_b64 v[146:147], 1, v[138:139]
	s_mov_b32 s18, s33
	v_lshl_add_u64 v[158:159], v[142:143], 0, v[146:147]
	global_load_dwordx2 v[160:161], v[158:159], off
	global_load_dwordx2 v[162:163], v[158:159], off offset:32
	global_load_dwordx2 v[164:165], v[158:159], off offset:256
	global_load_dwordx2 v[166:167], v[158:159], off offset:288
	v_mov_b32_e32 v142, s18
	ds_read2_b32 v[148:149], v142 offset1:1
	v_lshl_add_u64 v[142:143], s[16:17], 0, v[146:147]
	v_lshl_add_u64 v[144:145], v[142:143], 0, v[144:145]
	v_add_co_u32_e32 v146, vcc, s50, v144
	s_waitcnt lgkmcnt(0)
	v_readfirstlane_b32 s18, v148
	v_addc_co_u32_e32 v147, vcc, 0, v145, vcc
	v_readfirstlane_b32 s19, v149
	global_load_dwordx2 v[152:153], v[146:147], off
	global_load_dwordx2 v[150:151], v[146:147], off offset:32
	global_load_dwordx2 v[148:149], v[146:147], off offset:256
	s_nop 0
	global_load_dwordx2 v[146:147], v[146:147], off offset:288
	s_lshl_b32 s14, s43, 2
	s_ashr_i32 s15, s14, 31
	s_lshl_b64 s[14:15], s[14:15], 2
	s_add_u32 s14, s18, s14
	s_addc_u32 s15, s19, s15
	s_add_u32 s14, s14, s40
	s_addc_u32 s15, s15, 0
	s_add_u32 s14, s14, 0x10380000
	s_addc_u32 s15, s15, 0
	s_waitcnt vmcnt(0)
	v_cvt_f32_f16_e32 v168, v160
	v_cvt_f32_f16_sdwa v169, v160 dst_sel:DWORD dst_unused:UNUSED_PAD src0_sel:WORD_1
	v_cvt_f32_f16_e32 v160, v161
	v_cvt_f32_f16_sdwa v161, v161 dst_sel:DWORD dst_unused:UNUSED_PAD src0_sel:WORD_1
	v_cvt_f32_f16_e32 v170, v162
	v_cvt_f32_f16_sdwa v171, v162 dst_sel:DWORD dst_unused:UNUSED_PAD src0_sel:WORD_1
	v_cvt_f32_f16_e32 v162, v163
	v_cvt_f32_f16_sdwa v163, v163 dst_sel:DWORD dst_unused:UNUSED_PAD src0_sel:WORD_1
	v_cvt_f32_f16_e32 v172, v164
	v_cvt_f32_f16_sdwa v173, v164 dst_sel:DWORD dst_unused:UNUSED_PAD src0_sel:WORD_1
	v_cvt_f32_f16_e32 v164, v165
	v_cvt_f32_f16_sdwa v165, v165 dst_sel:DWORD dst_unused:UNUSED_PAD src0_sel:WORD_1
	v_cvt_f32_f16_e32 v174, v166
	v_cvt_f32_f16_sdwa v175, v166 dst_sel:DWORD dst_unused:UNUSED_PAD src0_sel:WORD_1
	v_cvt_f32_f16_e32 v166, v167
	v_cvt_f32_f16_sdwa v167, v167 dst_sel:DWORD dst_unused:UNUSED_PAD src0_sel:WORD_1
	v_pk_fma_f32 v[128:129], v[128:129], 0.5, v[160:161] op_sel_hi:[1,0,1]
	v_pk_fma_f32 v[126:127], v[126:127], 0.5, v[168:169] op_sel_hi:[1,0,1]
	v_pk_fma_f32 v[122:123], v[122:123], 0.5, v[170:171] op_sel_hi:[1,0,1]
	v_pk_fma_f32 v[124:125], v[124:125], 0.5, v[162:163] op_sel_hi:[1,0,1]
	v_pk_fma_f32 v[120:121], v[120:121], 0.5, v[164:165] op_sel_hi:[1,0,1]
	v_pk_fma_f32 v[118:119], v[118:119], 0.5, v[172:173] op_sel_hi:[1,0,1]
	v_cvt_f16_f32_e32 v157, v126
	v_cvt_f16_f32_sdwa v160, v127 dst_sel:WORD_1 dst_unused:UNUSED_PAD src0_sel:DWORD
	v_cvt_f16_f32_e32 v161, v128
	v_cvt_f16_f32_sdwa v162, v129 dst_sel:WORD_1 dst_unused:UNUSED_PAD src0_sel:DWORD
	v_cvt_f16_f32_e32 v163, v122
	v_cvt_f16_f32_sdwa v164, v123 dst_sel:WORD_1 dst_unused:UNUSED_PAD src0_sel:DWORD
	v_pk_fma_f32 v[116:117], v[116:117], 0.5, v[166:167] op_sel_hi:[1,0,1]
	v_mul_f32_e32 v127, v127, v127
	v_mul_f32_e32 v129, v129, v129
	v_cvt_f16_f32_e32 v165, v124
	v_cvt_f16_f32_sdwa v166, v125 dst_sel:WORD_1 dst_unused:UNUSED_PAD src0_sel:DWORD
	v_mul_f32_e32 v123, v123, v123
	v_mul_f32_e32 v125, v125, v125
	v_cvt_f16_f32_e32 v167, v118
	v_cvt_f16_f32_sdwa v168, v119 dst_sel:WORD_1 dst_unused:UNUSED_PAD src0_sel:DWORD
	v_cvt_f16_f32_e32 v169, v120
	v_cvt_f16_f32_sdwa v170, v121 dst_sel:WORD_1 dst_unused:UNUSED_PAD src0_sel:DWORD
	v_mul_f32_e32 v171, v119, v119
	v_fmac_f32_e32 v127, v126, v126
	v_fmac_f32_e32 v129, v128, v128
	v_fmac_f32_e32 v123, v122, v122
	v_fmac_f32_e32 v125, v124, v124
	v_mul_f32_e32 v172, v121, v121
	v_fmac_f32_e32 v171, v118, v118
	v_add_f32_e32 v118, v127, v129
	v_add_f32_e32 v119, v123, v125
	v_pk_fma_f32 v[114:115], v[114:115], 0.5, v[174:175] op_sel_hi:[1,0,1]
	v_fmac_f32_e32 v172, v120, v120
	v_add_f32_e32 v124, v118, v119
	v_or_b32_e32 v118, v160, v157
	v_or_b32_e32 v119, v162, v161
	v_or_b32_e32 v120, v164, v163
	v_cvt_f16_f32_e32 v173, v114
	v_cvt_f16_f32_sdwa v174, v115 dst_sel:WORD_1 dst_unused:UNUSED_PAD src0_sel:DWORD
	v_or_b32_e32 v121, v166, v165
	v_or_b32_e32 v122, v168, v167
	v_or_b32_e32 v123, v170, v169
	global_store_dwordx2 v[158:159], v[118:119], off
	global_store_dwordx2 v[158:159], v[120:121], off offset:32
	global_store_dwordx2 v[158:159], v[122:123], off offset:256
	v_cvt_f16_f32_e32 v119, v116
	v_cvt_f16_f32_sdwa v120, v117 dst_sel:WORD_1 dst_unused:UNUSED_PAD src0_sel:DWORD
	v_mul_f32_e32 v115, v115, v115
	v_fmac_f32_e32 v115, v114, v114
	v_mul_f32_e32 v114, v117, v117
	v_add_f32_e32 v118, v171, v172
	v_fmac_f32_e32 v114, v116, v116
	v_add_f32_e32 v121, v124, v118
	v_or_b32_e32 v118, v174, v173
	v_or_b32_e32 v119, v120, v119
	v_add_f32_e32 v114, v115, v114
	global_store_dwordx2 v[158:159], v[118:119], off offset:288
	v_add_f32_e32 v114, v121, v114
	v_mov_b32_e32 v115, v114
	s_nop 1
	v_permlane16_swap_b32_e32 v115, v114
	s_waitcnt lgkmcnt(0)
	v_add_f32_e32 v114, v114, v115
	v_mov_b32_e32 v115, v1
	s_nop 0
	v_mbcnt_lo_u32_b32 v115, -1, v115
	v_mbcnt_hi_u32_b32 v115, -1, v115
	v_lshlrev_b32_e32 v115, 2, v115
	v_xor_b32_e32 v115, 0x80, v115
	ds_bpermute_b32 v115, v115, v114
	s_and_saveexec_b64 s[18:19], s[0:1]
	s_cbranch_execz .LBB0_803
	v_lshlrev_b64 v[116:117], 6, v[140:141]
	v_lshl_add_u64 v[116:117], s[14:15], 0, v[116:117]
	s_waitcnt lgkmcnt(0)
	v_add_f32_e32 v114, v114, v115
	global_store_dword v[116:117], v114, off
.LBB0_803:
	s_or_b64 exec, exec, s[18:19]
	v_cvt_f32_f16_sdwa v117, v152 dst_sel:DWORD dst_unused:UNUSED_PAD src0_sel:WORD_1
	v_cvt_f32_f16_e32 v116, v152
	v_cvt_f32_f16_sdwa v119, v153 dst_sel:DWORD dst_unused:UNUSED_PAD src0_sel:WORD_1
	v_cvt_f32_f16_e32 v118, v153
	s_mov_b32 s18, 0x10000
	v_cvt_f32_f16_sdwa v129, v146 dst_sel:DWORD dst_unused:UNUSED_PAD src0_sel:WORD_1
	v_cvt_f32_f16_e32 v128, v146
	v_add_co_u32_e32 v146, vcc, s18, v144
	v_cvt_f32_f16_sdwa v125, v148 dst_sel:DWORD dst_unused:UNUSED_PAD src0_sel:WORD_1
	v_cvt_f32_f16_e32 v124, v148
	v_cvt_f32_f16_sdwa v127, v149 dst_sel:DWORD dst_unused:UNUSED_PAD src0_sel:WORD_1
	v_cvt_f32_f16_e32 v126, v149
	v_cvt_f32_f16_sdwa v149, v147 dst_sel:DWORD dst_unused:UNUSED_PAD src0_sel:WORD_1
	v_cvt_f32_f16_e32 v148, v147
	v_addc_co_u32_e32 v147, vcc, 0, v145, vcc
	v_cvt_f32_f16_sdwa v121, v150 dst_sel:DWORD dst_unused:UNUSED_PAD src0_sel:WORD_1
	v_cvt_f32_f16_e32 v120, v150
	v_cvt_f32_f16_sdwa v123, v151 dst_sel:DWORD dst_unused:UNUSED_PAD src0_sel:WORD_1
	v_cvt_f32_f16_e32 v122, v151
	v_pk_fma_f32 v[150:151], v[112:113], 0.5, v[118:119] op_sel_hi:[1,0,1]
	v_pk_fma_f32 v[152:153], v[110:111], 0.5, v[116:117] op_sel_hi:[1,0,1]
	global_load_dwordx2 v[118:119], v[146:147], off
	global_load_dwordx2 v[116:117], v[146:147], off offset:32
	global_load_dwordx2 v[112:113], v[146:147], off offset:256
	global_load_dwordx2 v[110:111], v[146:147], off offset:288
	v_cvt_f16_f32_e32 v157, v152
	v_cvt_f16_f32_sdwa v158, v153 dst_sel:WORD_1 dst_unused:UNUSED_PAD src0_sel:DWORD
	v_cvt_f16_f32_e32 v159, v150
	v_cvt_f16_f32_sdwa v160, v151 dst_sel:WORD_1 dst_unused:UNUSED_PAD src0_sel:DWORD
	v_pk_fma_f32 v[108:109], v[108:109], 0.5, v[122:123] op_sel_hi:[1,0,1]
	v_pk_fma_f32 v[106:107], v[106:107], 0.5, v[120:121] op_sel_hi:[1,0,1]
	v_cvt_f16_f32_e32 v122, v108
	v_cvt_f16_f32_e32 v120, v106
	v_cvt_f16_f32_sdwa v121, v107 dst_sel:WORD_1 dst_unused:UNUSED_PAD src0_sel:DWORD
	v_cvt_f16_f32_sdwa v123, v109 dst_sel:WORD_1 dst_unused:UNUSED_PAD src0_sel:DWORD
	v_or_b32_e32 v114, 16, v140
	s_waitcnt lgkmcnt(0)
	v_mov_b32_e32 v115, v141
	v_or_b32_e32 v146, v158, v157
	v_or_b32_e32 v147, v160, v159
	v_lshlrev_b64 v[158:159], 11, v[114:115]
	v_lshl_add_u64 v[158:159], s[16:17], 0, v[158:159]
	v_mul_f32_e32 v107, v107, v107
	v_lshl_add_u64 v[158:159], v[138:139], 1, v[158:159]
	v_or_b32_e32 v120, v121, v120
	v_or_b32_e32 v121, v123, v122
	v_fmac_f32_e32 v107, v106, v106
	v_mul_f32_e32 v106, v109, v109
	v_pk_fma_f32 v[104:105], v[104:105], 0.5, v[126:127] op_sel_hi:[1,0,1]
	v_pk_fma_f32 v[102:103], v[102:103], 0.5, v[124:125] op_sel_hi:[1,0,1]
	global_store_dwordx2 v[158:159], v[120:121], off offset:32
	v_fmac_f32_e32 v106, v108, v108
	v_cvt_f16_f32_e32 v108, v102
	v_cvt_f16_f32_sdwa v109, v103 dst_sel:WORD_1 dst_unused:UNUSED_PAD src0_sel:DWORD
	v_cvt_f16_f32_e32 v120, v104
	v_cvt_f16_f32_sdwa v121, v105 dst_sel:WORD_1 dst_unused:UNUSED_PAD src0_sel:DWORD
	global_store_dwordx2 v[158:159], v[146:147], off
	v_mul_f32_e32 v146, v153, v153
	v_mul_f32_e32 v147, v151, v151
	v_fmac_f32_e32 v146, v152, v152
	v_fmac_f32_e32 v147, v150, v150
	v_add_f32_e32 v146, v146, v147
	v_add_f32_e32 v106, v107, v106
	v_mul_f32_e32 v103, v103, v103
	v_add_f32_e32 v122, v146, v106
	v_or_b32_e32 v106, v109, v108
	v_or_b32_e32 v107, v121, v120
	v_fmac_f32_e32 v103, v102, v102
	v_mul_f32_e32 v102, v105, v105
	v_pk_fma_f32 v[100:101], v[100:101], 0.5, v[148:149] op_sel_hi:[1,0,1]
	v_pk_fma_f32 v[98:99], v[98:99], 0.5, v[128:129] op_sel_hi:[1,0,1]
	global_store_dwordx2 v[158:159], v[106:107], off offset:256
	v_fmac_f32_e32 v102, v104, v104
	v_cvt_f16_f32_e32 v104, v98
	v_cvt_f16_f32_sdwa v105, v99 dst_sel:WORD_1 dst_unused:UNUSED_PAD src0_sel:DWORD
	v_cvt_f16_f32_e32 v106, v100
	v_cvt_f16_f32_sdwa v107, v101 dst_sel:WORD_1 dst_unused:UNUSED_PAD src0_sel:DWORD
	v_mul_f32_e32 v99, v99, v99
	v_fmac_f32_e32 v99, v98, v98
	v_mul_f32_e32 v98, v101, v101
	v_add_f32_e32 v102, v103, v102
	v_fmac_f32_e32 v98, v100, v100
	v_add_f32_e32 v108, v122, v102
	v_or_b32_e32 v102, v105, v104
	v_or_b32_e32 v103, v107, v106
	v_add_f32_e32 v98, v99, v98
	global_store_dwordx2 v[158:159], v[102:103], off offset:288
	v_add_f32_e32 v98, v108, v98
	v_mov_b32_e32 v99, v98
	s_nop 1
	v_permlane16_swap_b32_e32 v99, v98
	s_waitcnt lgkmcnt(0)
	v_add_f32_e32 v98, v98, v99
	v_mov_b32_e32 v99, v1
	s_nop 0
	v_mbcnt_lo_u32_b32 v99, -1, v99
	v_mbcnt_hi_u32_b32 v99, -1, v99
	v_lshlrev_b32_e32 v99, 2, v99
	v_xor_b32_e32 v99, 0x80, v99
	ds_bpermute_b32 v99, v99, v98
	s_and_saveexec_b64 s[18:19], s[0:1]
	s_cbranch_execz .LBB0_805
	v_lshlrev_b64 v[100:101], 6, v[114:115]
	v_lshl_add_u64 v[100:101], s[14:15], 0, v[100:101]
	s_waitcnt lgkmcnt(0)
	v_add_f32_e32 v98, v98, v99
	global_store_dword v[100:101], v98, off
.LBB0_805:
	s_or_b64 exec, exec, s[18:19]
	s_waitcnt vmcnt(7)
	v_cvt_f32_f16_sdwa v101, v118 dst_sel:DWORD dst_unused:UNUSED_PAD src0_sel:WORD_1
	v_cvt_f32_f16_e32 v100, v118
	v_cvt_f32_f16_sdwa v103, v119 dst_sel:DWORD dst_unused:UNUSED_PAD src0_sel:WORD_1
	v_cvt_f32_f16_e32 v102, v119
	s_mov_b32 s18, 0x18000
	s_waitcnt vmcnt(5)
	v_cvt_f32_f16_sdwa v109, v112 dst_sel:DWORD dst_unused:UNUSED_PAD src0_sel:WORD_1
	v_cvt_f32_f16_e32 v108, v112
	v_cvt_f32_f16_sdwa v115, v113 dst_sel:DWORD dst_unused:UNUSED_PAD src0_sel:WORD_1
	v_cvt_f32_f16_e32 v114, v113
	s_waitcnt vmcnt(4)
	v_cvt_f32_f16_sdwa v113, v110 dst_sel:DWORD dst_unused:UNUSED_PAD src0_sel:WORD_1
	v_cvt_f32_f16_e32 v112, v110
	v_add_co_u32_e32 v110, vcc, s18, v144
	v_cvt_f32_f16_sdwa v105, v116 dst_sel:DWORD dst_unused:UNUSED_PAD src0_sel:WORD_1
	v_cvt_f32_f16_e32 v104, v116
	v_cvt_f32_f16_sdwa v107, v117 dst_sel:DWORD dst_unused:UNUSED_PAD src0_sel:WORD_1
	v_cvt_f32_f16_e32 v106, v117
	v_cvt_f32_f16_sdwa v117, v111 dst_sel:DWORD dst_unused:UNUSED_PAD src0_sel:WORD_1
	v_cvt_f32_f16_e32 v116, v111
	v_addc_co_u32_e32 v111, vcc, 0, v145, vcc
	v_pk_fma_f32 v[118:119], v[96:97], 0.5, v[102:103] op_sel_hi:[1,0,1]
	v_pk_fma_f32 v[120:121], v[94:95], 0.5, v[100:101] op_sel_hi:[1,0,1]
	global_load_dwordx2 v[102:103], v[110:111], off
	global_load_dwordx2 v[100:101], v[110:111], off offset:32
	global_load_dwordx2 v[96:97], v[110:111], off offset:256
	global_load_dwordx2 v[94:95], v[110:111], off offset:288
	v_cvt_f16_f32_e32 v122, v120
	v_cvt_f16_f32_sdwa v123, v121 dst_sel:WORD_1 dst_unused:UNUSED_PAD src0_sel:DWORD
	v_pk_fma_f32 v[92:93], v[92:93], 0.5, v[106:107] op_sel_hi:[1,0,1]
	v_pk_fma_f32 v[90:91], v[90:91], 0.5, v[104:105] op_sel_hi:[1,0,1]
	v_cvt_f16_f32_e32 v106, v92
	v_cvt_f16_f32_e32 v104, v90
	v_cvt_f16_f32_sdwa v105, v91 dst_sel:WORD_1 dst_unused:UNUSED_PAD src0_sel:DWORD
	v_cvt_f16_f32_sdwa v107, v93 dst_sel:WORD_1 dst_unused:UNUSED_PAD src0_sel:DWORD
	v_or_b32_e32 v98, 32, v140
	s_waitcnt lgkmcnt(0)
	v_mov_b32_e32 v99, v141
	v_cvt_f16_f32_e32 v124, v118
	v_cvt_f16_f32_sdwa v125, v119 dst_sel:WORD_1 dst_unused:UNUSED_PAD src0_sel:DWORD
	v_or_b32_e32 v110, v123, v122
	v_lshlrev_b64 v[122:123], 11, v[98:99]
	v_lshl_add_u64 v[122:123], s[16:17], 0, v[122:123]
	v_mul_f32_e32 v91, v91, v91
	v_lshl_add_u64 v[122:123], v[138:139], 1, v[122:123]
	v_or_b32_e32 v104, v105, v104
	v_or_b32_e32 v105, v107, v106
	v_fmac_f32_e32 v91, v90, v90
	v_mul_f32_e32 v90, v93, v93
	v_pk_fma_f32 v[88:89], v[88:89], 0.5, v[114:115] op_sel_hi:[1,0,1]
	v_pk_fma_f32 v[86:87], v[86:87], 0.5, v[108:109] op_sel_hi:[1,0,1]
	v_or_b32_e32 v111, v125, v124
	global_store_dwordx2 v[122:123], v[104:105], off offset:32
	v_fmac_f32_e32 v90, v92, v92
	v_cvt_f16_f32_e32 v92, v86
	v_cvt_f16_f32_sdwa v93, v87 dst_sel:WORD_1 dst_unused:UNUSED_PAD src0_sel:DWORD
	v_cvt_f16_f32_e32 v104, v88
	v_cvt_f16_f32_sdwa v105, v89 dst_sel:WORD_1 dst_unused:UNUSED_PAD src0_sel:DWORD
	global_store_dwordx2 v[122:123], v[110:111], off
	v_mul_f32_e32 v110, v121, v121
	v_mul_f32_e32 v111, v119, v119
	v_fmac_f32_e32 v110, v120, v120
	v_fmac_f32_e32 v111, v118, v118
	v_add_f32_e32 v110, v110, v111
	v_add_f32_e32 v90, v91, v90
	v_mul_f32_e32 v87, v87, v87
	v_add_f32_e32 v106, v110, v90
	v_or_b32_e32 v90, v93, v92
	v_or_b32_e32 v91, v105, v104
	v_fmac_f32_e32 v87, v86, v86
	v_mul_f32_e32 v86, v89, v89
	v_pk_fma_f32 v[84:85], v[84:85], 0.5, v[116:117] op_sel_hi:[1,0,1]
	v_pk_fma_f32 v[82:83], v[82:83], 0.5, v[112:113] op_sel_hi:[1,0,1]
	global_store_dwordx2 v[122:123], v[90:91], off offset:256
	v_fmac_f32_e32 v86, v88, v88
	v_cvt_f16_f32_e32 v88, v82
	v_cvt_f16_f32_sdwa v89, v83 dst_sel:WORD_1 dst_unused:UNUSED_PAD src0_sel:DWORD
	v_cvt_f16_f32_e32 v90, v84
	v_cvt_f16_f32_sdwa v91, v85 dst_sel:WORD_1 dst_unused:UNUSED_PAD src0_sel:DWORD
	v_mul_f32_e32 v83, v83, v83
	v_fmac_f32_e32 v83, v82, v82
	v_mul_f32_e32 v82, v85, v85
	v_add_f32_e32 v86, v87, v86
	v_fmac_f32_e32 v82, v84, v84
	v_add_f32_e32 v92, v106, v86
	v_or_b32_e32 v86, v89, v88
	v_or_b32_e32 v87, v91, v90
	v_add_f32_e32 v82, v83, v82
	global_store_dwordx2 v[122:123], v[86:87], off offset:288
	v_add_f32_e32 v82, v92, v82
	v_mov_b32_e32 v83, v82
	s_nop 1
	v_permlane16_swap_b32_e32 v83, v82
	s_waitcnt lgkmcnt(0)
	v_add_f32_e32 v82, v82, v83
	v_mov_b32_e32 v83, v1
	s_nop 0
	v_mbcnt_lo_u32_b32 v83, -1, v83
	v_mbcnt_hi_u32_b32 v83, -1, v83
	v_lshlrev_b32_e32 v83, 2, v83
	v_xor_b32_e32 v83, 0x80, v83
	ds_bpermute_b32 v83, v83, v82
	s_and_saveexec_b64 s[18:19], s[0:1]
	s_cbranch_execz .LBB0_807
	v_lshlrev_b64 v[84:85], 6, v[98:99]
	v_lshl_add_u64 v[84:85], s[14:15], 0, v[84:85]
	s_waitcnt lgkmcnt(0)
	v_add_f32_e32 v82, v82, v83
	global_store_dword v[84:85], v82, off
.LBB0_807:
	s_or_b64 exec, exec, s[18:19]
	s_waitcnt vmcnt(7)
	v_cvt_f32_f16_sdwa v85, v102 dst_sel:DWORD dst_unused:UNUSED_PAD src0_sel:WORD_1
	v_cvt_f32_f16_e32 v84, v102
	v_cvt_f32_f16_sdwa v87, v103 dst_sel:DWORD dst_unused:UNUSED_PAD src0_sel:WORD_1
	v_cvt_f32_f16_e32 v86, v103
	s_mov_b32 s18, 0x40000
	s_waitcnt vmcnt(5)
	v_cvt_f32_f16_sdwa v93, v96 dst_sel:DWORD dst_unused:UNUSED_PAD src0_sel:WORD_1
	v_cvt_f32_f16_e32 v92, v96
	v_cvt_f32_f16_sdwa v99, v97 dst_sel:DWORD dst_unused:UNUSED_PAD src0_sel:WORD_1
	v_cvt_f32_f16_e32 v98, v97
	s_waitcnt vmcnt(4)
	v_cvt_f32_f16_sdwa v97, v94 dst_sel:DWORD dst_unused:UNUSED_PAD src0_sel:WORD_1
	v_cvt_f32_f16_e32 v96, v94
	v_add_co_u32_e32 v94, vcc, s18, v144
	v_cvt_f32_f16_sdwa v89, v100 dst_sel:DWORD dst_unused:UNUSED_PAD src0_sel:WORD_1
	v_cvt_f32_f16_e32 v88, v100
	v_cvt_f32_f16_sdwa v91, v101 dst_sel:DWORD dst_unused:UNUSED_PAD src0_sel:WORD_1
	v_cvt_f32_f16_e32 v90, v101
	v_cvt_f32_f16_sdwa v101, v95 dst_sel:DWORD dst_unused:UNUSED_PAD src0_sel:WORD_1
	v_cvt_f32_f16_e32 v100, v95
	v_addc_co_u32_e32 v95, vcc, 0, v145, vcc
	v_pk_fma_f32 v[102:103], v[80:81], 0.5, v[86:87] op_sel_hi:[1,0,1]
	v_pk_fma_f32 v[104:105], v[78:79], 0.5, v[84:85] op_sel_hi:[1,0,1]
	global_load_dwordx2 v[86:87], v[94:95], off
	global_load_dwordx2 v[84:85], v[94:95], off offset:32
	global_load_dwordx2 v[80:81], v[94:95], off offset:256
	global_load_dwordx2 v[78:79], v[94:95], off offset:288
	v_cvt_f16_f32_e32 v106, v104
	v_cvt_f16_f32_sdwa v107, v105 dst_sel:WORD_1 dst_unused:UNUSED_PAD src0_sel:DWORD
	v_pk_fma_f32 v[76:77], v[76:77], 0.5, v[90:91] op_sel_hi:[1,0,1]
	v_pk_fma_f32 v[74:75], v[74:75], 0.5, v[88:89] op_sel_hi:[1,0,1]
	v_cvt_f16_f32_e32 v90, v76
	v_cvt_f16_f32_e32 v88, v74
	v_cvt_f16_f32_sdwa v89, v75 dst_sel:WORD_1 dst_unused:UNUSED_PAD src0_sel:DWORD
	v_cvt_f16_f32_sdwa v91, v77 dst_sel:WORD_1 dst_unused:UNUSED_PAD src0_sel:DWORD
	v_or_b32_e32 v82, 48, v140
	s_waitcnt lgkmcnt(0)
	v_mov_b32_e32 v83, v141
	v_cvt_f16_f32_e32 v108, v102
	v_cvt_f16_f32_sdwa v109, v103 dst_sel:WORD_1 dst_unused:UNUSED_PAD src0_sel:DWORD
	v_or_b32_e32 v94, v107, v106
	v_lshlrev_b64 v[106:107], 11, v[82:83]
	v_lshl_add_u64 v[106:107], s[16:17], 0, v[106:107]
	v_mul_f32_e32 v75, v75, v75
	v_lshl_add_u64 v[106:107], v[138:139], 1, v[106:107]
	v_or_b32_e32 v88, v89, v88
	v_or_b32_e32 v89, v91, v90
	v_fmac_f32_e32 v75, v74, v74
	v_mul_f32_e32 v74, v77, v77
	v_pk_fma_f32 v[72:73], v[72:73], 0.5, v[98:99] op_sel_hi:[1,0,1]
	v_pk_fma_f32 v[70:71], v[70:71], 0.5, v[92:93] op_sel_hi:[1,0,1]
	v_or_b32_e32 v95, v109, v108
	global_store_dwordx2 v[106:107], v[88:89], off offset:32
	v_fmac_f32_e32 v74, v76, v76
	v_cvt_f16_f32_e32 v76, v70
	v_cvt_f16_f32_sdwa v77, v71 dst_sel:WORD_1 dst_unused:UNUSED_PAD src0_sel:DWORD
	v_cvt_f16_f32_e32 v88, v72
	v_cvt_f16_f32_sdwa v89, v73 dst_sel:WORD_1 dst_unused:UNUSED_PAD src0_sel:DWORD
	global_store_dwordx2 v[106:107], v[94:95], off
	v_mul_f32_e32 v94, v105, v105
	v_mul_f32_e32 v95, v103, v103
	v_fmac_f32_e32 v94, v104, v104
	v_fmac_f32_e32 v95, v102, v102
	v_add_f32_e32 v94, v94, v95
	v_add_f32_e32 v74, v75, v74
	v_mul_f32_e32 v71, v71, v71
	v_add_f32_e32 v90, v94, v74
	v_or_b32_e32 v74, v77, v76
	v_or_b32_e32 v75, v89, v88
	v_fmac_f32_e32 v71, v70, v70
	v_mul_f32_e32 v70, v73, v73
	v_pk_fma_f32 v[68:69], v[68:69], 0.5, v[100:101] op_sel_hi:[1,0,1]
	v_pk_fma_f32 v[66:67], v[66:67], 0.5, v[96:97] op_sel_hi:[1,0,1]
	global_store_dwordx2 v[106:107], v[74:75], off offset:256
	v_fmac_f32_e32 v70, v72, v72
	v_cvt_f16_f32_e32 v72, v66
	v_cvt_f16_f32_sdwa v73, v67 dst_sel:WORD_1 dst_unused:UNUSED_PAD src0_sel:DWORD
	v_cvt_f16_f32_e32 v74, v68
	v_cvt_f16_f32_sdwa v75, v69 dst_sel:WORD_1 dst_unused:UNUSED_PAD src0_sel:DWORD
	v_mul_f32_e32 v67, v67, v67
	v_fmac_f32_e32 v67, v66, v66
	v_mul_f32_e32 v66, v69, v69
	v_add_f32_e32 v70, v71, v70
	v_fmac_f32_e32 v66, v68, v68
	v_add_f32_e32 v76, v90, v70
	v_or_b32_e32 v70, v73, v72
	v_or_b32_e32 v71, v75, v74
	v_add_f32_e32 v66, v67, v66
	global_store_dwordx2 v[106:107], v[70:71], off offset:288
	v_add_f32_e32 v66, v76, v66
	v_mov_b32_e32 v67, v66
	s_nop 1
	v_permlane16_swap_b32_e32 v67, v66
	s_waitcnt lgkmcnt(0)
	v_add_f32_e32 v66, v66, v67
	v_mov_b32_e32 v67, v1
	s_nop 0
	v_mbcnt_lo_u32_b32 v67, -1, v67
	v_mbcnt_hi_u32_b32 v67, -1, v67
	v_lshlrev_b32_e32 v67, 2, v67
	v_xor_b32_e32 v67, 0x80, v67
	ds_bpermute_b32 v67, v67, v66
	s_and_saveexec_b64 s[18:19], s[0:1]
	s_cbranch_execz .LBB0_809
	v_lshlrev_b64 v[68:69], 6, v[82:83]
	v_lshl_add_u64 v[68:69], s[14:15], 0, v[68:69]
	s_waitcnt lgkmcnt(0)
	v_add_f32_e32 v66, v66, v67
	global_store_dword v[68:69], v66, off
.LBB0_809:
	s_or_b64 exec, exec, s[18:19]
	s_waitcnt vmcnt(7)
	v_cvt_f32_f16_sdwa v71, v86 dst_sel:DWORD dst_unused:UNUSED_PAD src0_sel:WORD_1
	v_cvt_f32_f16_e32 v70, v86
	v_cvt_f32_f16_sdwa v73, v87 dst_sel:DWORD dst_unused:UNUSED_PAD src0_sel:WORD_1
	v_cvt_f32_f16_e32 v72, v87
	v_lshl_add_u64 v[68:69], v[140:141], 0, s[96:97]
	s_waitcnt lgkmcnt(0)
	v_lshlrev_b64 v[66:67], 11, v[68:69]
	v_or_b32_e32 v88, 0x8000, v66
	v_mov_b32_e32 v89, v67
	v_lshl_add_u64 v[88:89], v[142:143], 0, v[88:89]
	v_pk_fma_f32 v[90:91], v[64:65], 0.5, v[72:73] op_sel_hi:[1,0,1]
	v_pk_fma_f32 v[92:93], v[62:63], 0.5, v[70:71] op_sel_hi:[1,0,1]
	global_load_dwordx2 v[72:73], v[88:89], off
	global_load_dwordx2 v[70:71], v[88:89], off offset:32
	global_load_dwordx2 v[64:65], v[88:89], off offset:256
	global_load_dwordx2 v[62:63], v[88:89], off offset:288
	s_waitcnt vmcnt(10)
	v_cvt_f32_f16_sdwa v75, v84 dst_sel:DWORD dst_unused:UNUSED_PAD src0_sel:WORD_1
	v_cvt_f32_f16_e32 v74, v84
	v_cvt_f32_f16_sdwa v77, v85 dst_sel:DWORD dst_unused:UNUSED_PAD src0_sel:WORD_1
	v_cvt_f32_f16_e32 v76, v85
	s_waitcnt vmcnt(9)
	v_cvt_f32_f16_sdwa v83, v80 dst_sel:DWORD dst_unused:UNUSED_PAD src0_sel:WORD_1
	v_pk_fma_f32 v[58:59], v[58:59], 0.5, v[74:75] op_sel_hi:[1,0,1]
	v_cvt_f32_f16_e32 v82, v80
	v_pk_fma_f32 v[60:61], v[60:61], 0.5, v[76:77] op_sel_hi:[1,0,1]
	v_cvt_f32_f16_sdwa v85, v81 dst_sel:DWORD dst_unused:UNUSED_PAD src0_sel:WORD_1
	v_cvt_f32_f16_e32 v84, v81
	v_cvt_f16_f32_e32 v74, v58
	v_cvt_f16_f32_sdwa v75, v59 dst_sel:WORD_1 dst_unused:UNUSED_PAD src0_sel:DWORD
	v_cvt_f16_f32_e32 v76, v60
	v_cvt_f16_f32_sdwa v77, v61 dst_sel:WORD_1 dst_unused:UNUSED_PAD src0_sel:DWORD
	s_waitcnt vmcnt(8)
	v_cvt_f32_f16_sdwa v81, v78 dst_sel:DWORD dst_unused:UNUSED_PAD src0_sel:WORD_1
	v_cvt_f32_f16_e32 v80, v78
	v_cvt_f16_f32_e32 v78, v92
	v_cvt_f16_f32_sdwa v94, v93 dst_sel:WORD_1 dst_unused:UNUSED_PAD src0_sel:DWORD
	v_cvt_f16_f32_e32 v95, v90
	v_cvt_f16_f32_sdwa v96, v91 dst_sel:WORD_1 dst_unused:UNUSED_PAD src0_sel:DWORD
	v_lshl_add_u64 v[88:89], s[16:17], 0, v[66:67]
	v_mul_f32_e32 v59, v59, v59
	v_lshl_add_u64 v[88:89], v[138:139], 1, v[88:89]
	v_or_b32_e32 v74, v75, v74
	v_or_b32_e32 v75, v77, v76
	v_fmac_f32_e32 v59, v58, v58
	v_mul_f32_e32 v58, v61, v61
	v_pk_fma_f32 v[56:57], v[56:57], 0.5, v[84:85] op_sel_hi:[1,0,1]
	v_pk_fma_f32 v[54:55], v[54:55], 0.5, v[82:83] op_sel_hi:[1,0,1]
	v_cvt_f32_f16_sdwa v87, v79 dst_sel:DWORD dst_unused:UNUSED_PAD src0_sel:WORD_1
	v_cvt_f32_f16_e32 v86, v79
	v_or_b32_e32 v78, v94, v78
	v_or_b32_e32 v79, v96, v95
	global_store_dwordx2 v[88:89], v[74:75], off offset:32
	v_fmac_f32_e32 v58, v60, v60
	v_cvt_f16_f32_e32 v60, v54
	v_cvt_f16_f32_sdwa v61, v55 dst_sel:WORD_1 dst_unused:UNUSED_PAD src0_sel:DWORD
	v_cvt_f16_f32_e32 v74, v56
	v_cvt_f16_f32_sdwa v75, v57 dst_sel:WORD_1 dst_unused:UNUSED_PAD src0_sel:DWORD
	global_store_dwordx2 v[88:89], v[78:79], off
	v_mul_f32_e32 v78, v93, v93
	v_mul_f32_e32 v79, v91, v91
	v_fmac_f32_e32 v78, v92, v92
	v_fmac_f32_e32 v79, v90, v90
	v_add_f32_e32 v78, v78, v79
	v_add_f32_e32 v58, v59, v58
	v_mul_f32_e32 v55, v55, v55
	v_add_f32_e32 v76, v78, v58
	v_or_b32_e32 v58, v61, v60
	v_or_b32_e32 v59, v75, v74
	v_fmac_f32_e32 v55, v54, v54
	v_mul_f32_e32 v54, v57, v57
	v_pk_fma_f32 v[52:53], v[52:53], 0.5, v[86:87] op_sel_hi:[1,0,1]
	v_pk_fma_f32 v[50:51], v[50:51], 0.5, v[80:81] op_sel_hi:[1,0,1]
	global_store_dwordx2 v[88:89], v[58:59], off offset:256
	v_fmac_f32_e32 v54, v56, v56
	v_cvt_f16_f32_e32 v56, v50
	v_cvt_f16_f32_sdwa v57, v51 dst_sel:WORD_1 dst_unused:UNUSED_PAD src0_sel:DWORD
	v_cvt_f16_f32_e32 v58, v52
	v_cvt_f16_f32_sdwa v59, v53 dst_sel:WORD_1 dst_unused:UNUSED_PAD src0_sel:DWORD
	v_mul_f32_e32 v51, v51, v51
	v_fmac_f32_e32 v51, v50, v50
	v_mul_f32_e32 v50, v53, v53
	v_add_f32_e32 v54, v55, v54
	v_fmac_f32_e32 v50, v52, v52
	v_add_f32_e32 v60, v76, v54
	v_or_b32_e32 v54, v57, v56
	v_or_b32_e32 v55, v59, v58
	v_add_f32_e32 v50, v51, v50
	global_store_dwordx2 v[88:89], v[54:55], off offset:288
	v_add_f32_e32 v50, v60, v50
	v_mov_b32_e32 v51, v50
	s_nop 1
	v_permlane16_swap_b32_e32 v51, v50
	s_waitcnt lgkmcnt(0)
	v_add_f32_e32 v50, v50, v51
	v_mov_b32_e32 v51, v1
	s_nop 0
	v_mbcnt_lo_u32_b32 v51, -1, v51
	v_mbcnt_hi_u32_b32 v51, -1, v51
	v_lshlrev_b32_e32 v51, 2, v51
	v_xor_b32_e32 v51, 0x80, v51
	ds_bpermute_b32 v51, v51, v50
	s_and_saveexec_b64 s[18:19], s[0:1]
	s_cbranch_execz .LBB0_811
	v_lshlrev_b64 v[52:53], 6, v[68:69]
	v_lshl_add_u64 v[52:53], s[14:15], 0, v[52:53]
	s_waitcnt lgkmcnt(0)
	v_add_f32_e32 v50, v50, v51
	global_store_dword v[52:53], v50, off
.LBB0_811:
	s_or_b64 exec, exec, s[18:19]
	s_waitcnt vmcnt(7)
	v_cvt_f32_f16_sdwa v53, v72 dst_sel:DWORD dst_unused:UNUSED_PAD src0_sel:WORD_1
	v_cvt_f32_f16_e32 v52, v72
	v_cvt_f32_f16_sdwa v55, v73 dst_sel:DWORD dst_unused:UNUSED_PAD src0_sel:WORD_1
	v_cvt_f32_f16_e32 v54, v73
	s_waitcnt vmcnt(6)
	v_cvt_f32_f16_sdwa v57, v70 dst_sel:DWORD dst_unused:UNUSED_PAD src0_sel:WORD_1
	v_cvt_f32_f16_e32 v56, v70
	v_cvt_f32_f16_sdwa v59, v71 dst_sel:DWORD dst_unused:UNUSED_PAD src0_sel:WORD_1
	v_cvt_f32_f16_e32 v58, v71
	s_waitcnt vmcnt(5)
	v_cvt_f32_f16_sdwa v61, v64 dst_sel:DWORD dst_unused:UNUSED_PAD src0_sel:WORD_1
	v_cvt_f32_f16_e32 v60, v64
	v_cvt_f32_f16_sdwa v69, v65 dst_sel:DWORD dst_unused:UNUSED_PAD src0_sel:WORD_1
	v_cvt_f32_f16_e32 v68, v65
	s_waitcnt vmcnt(4)
	v_cvt_f32_f16_sdwa v65, v62 dst_sel:DWORD dst_unused:UNUSED_PAD src0_sel:WORD_1
	v_cvt_f32_f16_e32 v64, v62
	v_cvt_f32_f16_sdwa v71, v63 dst_sel:DWORD dst_unused:UNUSED_PAD src0_sel:WORD_1
	v_cvt_f32_f16_e32 v70, v63
	v_or_b32_e32 v62, 0x10000, v66
	v_mov_b32_e32 v63, v67
	v_lshl_add_u64 v[62:63], v[142:143], 0, v[62:63]
	v_pk_fma_f32 v[72:73], v[48:49], 0.5, v[54:55] op_sel_hi:[1,0,1]
	v_pk_fma_f32 v[74:75], v[46:47], 0.5, v[52:53] op_sel_hi:[1,0,1]
	global_load_dwordx2 v[54:55], v[62:63], off
	global_load_dwordx2 v[52:53], v[62:63], off offset:32
	global_load_dwordx2 v[48:49], v[62:63], off offset:256
	global_load_dwordx2 v[46:47], v[62:63], off offset:288
	v_cvt_f16_f32_e32 v76, v74
	v_cvt_f16_f32_sdwa v77, v75 dst_sel:WORD_1 dst_unused:UNUSED_PAD src0_sel:DWORD
	v_pk_fma_f32 v[44:45], v[44:45], 0.5, v[58:59] op_sel_hi:[1,0,1]
	v_pk_fma_f32 v[42:43], v[42:43], 0.5, v[56:57] op_sel_hi:[1,0,1]
	s_mov_b64 s[18:19], 0x90
	v_cvt_f16_f32_e32 v56, v42
	v_cvt_f16_f32_sdwa v57, v43 dst_sel:WORD_1 dst_unused:UNUSED_PAD src0_sel:DWORD
	v_cvt_f16_f32_e32 v58, v44
	v_cvt_f16_f32_sdwa v59, v45 dst_sel:WORD_1 dst_unused:UNUSED_PAD src0_sel:DWORD
	s_waitcnt lgkmcnt(0)
	v_lshl_add_u64 v[50:51], v[140:141], 0, s[18:19]
	v_cvt_f16_f32_e32 v78, v72
	v_cvt_f16_f32_sdwa v79, v73 dst_sel:WORD_1 dst_unused:UNUSED_PAD src0_sel:DWORD
	v_or_b32_e32 v62, v77, v76
	v_lshlrev_b64 v[76:77], 11, v[50:51]
	v_lshl_add_u64 v[76:77], s[16:17], 0, v[76:77]
	v_mul_f32_e32 v43, v43, v43
	v_lshl_add_u64 v[76:77], v[138:139], 1, v[76:77]
	v_or_b32_e32 v56, v57, v56
	v_or_b32_e32 v57, v59, v58
	v_fmac_f32_e32 v43, v42, v42
	v_mul_f32_e32 v42, v45, v45
	v_pk_fma_f32 v[40:41], v[40:41], 0.5, v[68:69] op_sel_hi:[1,0,1]
	v_pk_fma_f32 v[38:39], v[38:39], 0.5, v[60:61] op_sel_hi:[1,0,1]
	v_or_b32_e32 v63, v79, v78
	global_store_dwordx2 v[76:77], v[56:57], off offset:32
	v_fmac_f32_e32 v42, v44, v44
	v_cvt_f16_f32_e32 v44, v38
	v_cvt_f16_f32_sdwa v45, v39 dst_sel:WORD_1 dst_unused:UNUSED_PAD src0_sel:DWORD
	v_cvt_f16_f32_e32 v56, v40
	v_cvt_f16_f32_sdwa v57, v41 dst_sel:WORD_1 dst_unused:UNUSED_PAD src0_sel:DWORD
	global_store_dwordx2 v[76:77], v[62:63], off
	v_mul_f32_e32 v62, v75, v75
	v_mul_f32_e32 v63, v73, v73
	v_fmac_f32_e32 v62, v74, v74
	v_fmac_f32_e32 v63, v72, v72
	v_add_f32_e32 v62, v62, v63
	v_add_f32_e32 v42, v43, v42
	v_mul_f32_e32 v39, v39, v39
	v_add_f32_e32 v58, v62, v42
	v_or_b32_e32 v42, v45, v44
	v_or_b32_e32 v43, v57, v56
	v_fmac_f32_e32 v39, v38, v38
	v_mul_f32_e32 v38, v41, v41
	v_pk_fma_f32 v[36:37], v[36:37], 0.5, v[70:71] op_sel_hi:[1,0,1]
	v_pk_fma_f32 v[34:35], v[34:35], 0.5, v[64:65] op_sel_hi:[1,0,1]
	global_store_dwordx2 v[76:77], v[42:43], off offset:256
	v_fmac_f32_e32 v38, v40, v40
	v_cvt_f16_f32_e32 v40, v34
	v_cvt_f16_f32_sdwa v41, v35 dst_sel:WORD_1 dst_unused:UNUSED_PAD src0_sel:DWORD
	v_cvt_f16_f32_e32 v42, v36
	v_cvt_f16_f32_sdwa v43, v37 dst_sel:WORD_1 dst_unused:UNUSED_PAD src0_sel:DWORD
	v_mul_f32_e32 v35, v35, v35
	v_fmac_f32_e32 v35, v34, v34
	v_mul_f32_e32 v34, v37, v37
	v_add_f32_e32 v38, v39, v38
	v_fmac_f32_e32 v34, v36, v36
	v_add_f32_e32 v44, v58, v38
	v_or_b32_e32 v38, v41, v40
	v_or_b32_e32 v39, v43, v42
	v_add_f32_e32 v34, v35, v34
	global_store_dwordx2 v[76:77], v[38:39], off offset:288
	v_add_f32_e32 v34, v44, v34
	v_mov_b32_e32 v35, v34
	s_nop 1
	v_permlane16_swap_b32_e32 v35, v34
	s_waitcnt lgkmcnt(0)
	v_add_f32_e32 v34, v34, v35
	v_mov_b32_e32 v35, v1
	s_nop 0
	v_mbcnt_lo_u32_b32 v35, -1, v35
	v_mbcnt_hi_u32_b32 v35, -1, v35
	v_lshlrev_b32_e32 v35, 2, v35
	v_xor_b32_e32 v35, 0x80, v35
	ds_bpermute_b32 v35, v35, v34
	s_and_saveexec_b64 s[18:19], s[0:1]
	s_cbranch_execz .LBB0_813
	v_lshlrev_b64 v[36:37], 6, v[50:51]
	v_lshl_add_u64 v[36:37], s[14:15], 0, v[36:37]
	s_waitcnt lgkmcnt(0)
	v_add_f32_e32 v34, v34, v35
	global_store_dword v[36:37], v34, off
.LBB0_813:
	s_or_b64 exec, exec, s[18:19]
	s_waitcnt vmcnt(7)
	v_cvt_f32_f16_sdwa v37, v54 dst_sel:DWORD dst_unused:UNUSED_PAD src0_sel:WORD_1
	v_cvt_f32_f16_e32 v36, v54
	v_cvt_f32_f16_sdwa v39, v55 dst_sel:DWORD dst_unused:UNUSED_PAD src0_sel:WORD_1
	v_cvt_f32_f16_e32 v38, v55
	v_or_b32_e32 v66, 0x18000, v66
	s_waitcnt vmcnt(6)
	v_cvt_f32_f16_sdwa v41, v52 dst_sel:DWORD dst_unused:UNUSED_PAD src0_sel:WORD_1
	v_cvt_f32_f16_e32 v40, v52
	v_cvt_f32_f16_sdwa v43, v53 dst_sel:DWORD dst_unused:UNUSED_PAD src0_sel:WORD_1
	v_cvt_f32_f16_e32 v42, v53
	s_waitcnt vmcnt(5)
	v_cvt_f32_f16_sdwa v45, v48 dst_sel:DWORD dst_unused:UNUSED_PAD src0_sel:WORD_1
	v_cvt_f32_f16_e32 v44, v48
	v_cvt_f32_f16_sdwa v51, v49 dst_sel:DWORD dst_unused:UNUSED_PAD src0_sel:WORD_1
	v_cvt_f32_f16_e32 v50, v49
	s_waitcnt vmcnt(4)
	v_cvt_f32_f16_sdwa v49, v46 dst_sel:DWORD dst_unused:UNUSED_PAD src0_sel:WORD_1
	v_cvt_f32_f16_e32 v48, v46
	v_cvt_f32_f16_sdwa v53, v47 dst_sel:DWORD dst_unused:UNUSED_PAD src0_sel:WORD_1
	v_cvt_f32_f16_e32 v52, v47
	v_lshl_add_u64 v[46:47], v[142:143], 0, v[66:67]
	v_pk_fma_f32 v[54:55], v[32:33], 0.5, v[38:39] op_sel_hi:[1,0,1]
	v_pk_fma_f32 v[56:57], v[30:31], 0.5, v[36:37] op_sel_hi:[1,0,1]
	global_load_dwordx2 v[38:39], v[46:47], off
	global_load_dwordx2 v[36:37], v[46:47], off offset:32
	global_load_dwordx2 v[32:33], v[46:47], off offset:256
	global_load_dwordx2 v[30:31], v[46:47], off offset:288
	v_cvt_f16_f32_e32 v58, v56
	v_cvt_f16_f32_sdwa v59, v57 dst_sel:WORD_1 dst_unused:UNUSED_PAD src0_sel:DWORD
	v_pk_fma_f32 v[28:29], v[28:29], 0.5, v[42:43] op_sel_hi:[1,0,1]
	v_pk_fma_f32 v[26:27], v[26:27], 0.5, v[40:41] op_sel_hi:[1,0,1]
	s_mov_b64 s[18:19], 0xa0
	v_cvt_f16_f32_e32 v40, v26
	v_cvt_f16_f32_sdwa v41, v27 dst_sel:WORD_1 dst_unused:UNUSED_PAD src0_sel:DWORD
	v_cvt_f16_f32_e32 v42, v28
	v_cvt_f16_f32_sdwa v43, v29 dst_sel:WORD_1 dst_unused:UNUSED_PAD src0_sel:DWORD
	s_waitcnt lgkmcnt(0)
	v_lshl_add_u64 v[34:35], v[140:141], 0, s[18:19]
	v_cvt_f16_f32_e32 v60, v54
	v_cvt_f16_f32_sdwa v61, v55 dst_sel:WORD_1 dst_unused:UNUSED_PAD src0_sel:DWORD
	v_or_b32_e32 v46, v59, v58
	v_lshlrev_b64 v[58:59], 11, v[34:35]
	v_lshl_add_u64 v[58:59], s[16:17], 0, v[58:59]
	v_mul_f32_e32 v27, v27, v27
	v_lshl_add_u64 v[58:59], v[138:139], 1, v[58:59]
	v_or_b32_e32 v40, v41, v40
	v_or_b32_e32 v41, v43, v42
	v_fmac_f32_e32 v27, v26, v26
	v_mul_f32_e32 v26, v29, v29
	v_pk_fma_f32 v[24:25], v[24:25], 0.5, v[50:51] op_sel_hi:[1,0,1]
	v_pk_fma_f32 v[22:23], v[22:23], 0.5, v[44:45] op_sel_hi:[1,0,1]
	v_or_b32_e32 v47, v61, v60
	global_store_dwordx2 v[58:59], v[40:41], off offset:32
	v_fmac_f32_e32 v26, v28, v28
	v_cvt_f16_f32_e32 v28, v22
	v_cvt_f16_f32_sdwa v29, v23 dst_sel:WORD_1 dst_unused:UNUSED_PAD src0_sel:DWORD
	v_cvt_f16_f32_e32 v40, v24
	v_cvt_f16_f32_sdwa v41, v25 dst_sel:WORD_1 dst_unused:UNUSED_PAD src0_sel:DWORD
	global_store_dwordx2 v[58:59], v[46:47], off
	v_mul_f32_e32 v46, v57, v57
	v_mul_f32_e32 v47, v55, v55
	v_fmac_f32_e32 v46, v56, v56
	v_fmac_f32_e32 v47, v54, v54
	v_add_f32_e32 v46, v46, v47
	v_add_f32_e32 v26, v27, v26
	v_mul_f32_e32 v23, v23, v23
	v_add_f32_e32 v42, v46, v26
	v_or_b32_e32 v26, v29, v28
	v_or_b32_e32 v27, v41, v40
	v_fmac_f32_e32 v23, v22, v22
	v_mul_f32_e32 v22, v25, v25
	v_pk_fma_f32 v[20:21], v[20:21], 0.5, v[52:53] op_sel_hi:[1,0,1]
	v_pk_fma_f32 v[18:19], v[18:19], 0.5, v[48:49] op_sel_hi:[1,0,1]
	global_store_dwordx2 v[58:59], v[26:27], off offset:256
	v_fmac_f32_e32 v22, v24, v24
	v_cvt_f16_f32_e32 v24, v18
	v_cvt_f16_f32_sdwa v25, v19 dst_sel:WORD_1 dst_unused:UNUSED_PAD src0_sel:DWORD
	v_cvt_f16_f32_e32 v26, v20
	v_cvt_f16_f32_sdwa v27, v21 dst_sel:WORD_1 dst_unused:UNUSED_PAD src0_sel:DWORD
	v_mul_f32_e32 v19, v19, v19
	v_fmac_f32_e32 v19, v18, v18
	v_mul_f32_e32 v18, v21, v21
	v_add_f32_e32 v22, v23, v22
	v_fmac_f32_e32 v18, v20, v20
	v_add_f32_e32 v28, v42, v22
	v_or_b32_e32 v22, v25, v24
	v_or_b32_e32 v23, v27, v26
	v_add_f32_e32 v18, v19, v18
	global_store_dwordx2 v[58:59], v[22:23], off offset:288
	v_add_f32_e32 v18, v28, v18
	v_mov_b32_e32 v19, v18
	s_nop 1
	v_permlane16_swap_b32_e32 v19, v18
	s_waitcnt lgkmcnt(0)
	v_add_f32_e32 v18, v18, v19
	v_mov_b32_e32 v19, v1
	s_nop 0
	v_mbcnt_lo_u32_b32 v19, -1, v19
	v_mbcnt_hi_u32_b32 v19, -1, v19
	v_lshlrev_b32_e32 v19, 2, v19
	v_xor_b32_e32 v19, 0x80, v19
	ds_bpermute_b32 v19, v19, v18
	s_and_saveexec_b64 s[18:19], s[0:1]
	s_cbranch_execz .LBB0_815
	v_lshlrev_b64 v[20:21], 6, v[34:35]
	v_lshl_add_u64 v[20:21], s[14:15], 0, v[20:21]
	s_waitcnt lgkmcnt(0)
	v_add_f32_e32 v18, v18, v19
	global_store_dword v[20:21], v18, off
.LBB0_815:
	s_or_b64 exec, exec, s[18:19]
	s_waitcnt vmcnt(7)
	v_cvt_f32_f16_sdwa v21, v38 dst_sel:DWORD dst_unused:UNUSED_PAD src0_sel:WORD_1
	v_cvt_f32_f16_e32 v20, v38
	v_cvt_f32_f16_sdwa v23, v39 dst_sel:DWORD dst_unused:UNUSED_PAD src0_sel:WORD_1
	v_cvt_f32_f16_e32 v22, v39
	s_waitcnt vmcnt(6)
	v_cvt_f32_f16_sdwa v25, v36 dst_sel:DWORD dst_unused:UNUSED_PAD src0_sel:WORD_1
	v_cvt_f32_f16_e32 v24, v36
	v_pk_fma_f32 v[14:15], v[14:15], 0.5, v[20:21] op_sel_hi:[1,0,1]
	v_cvt_f32_f16_sdwa v27, v37 dst_sel:DWORD dst_unused:UNUSED_PAD src0_sel:WORD_1
	v_cvt_f32_f16_e32 v26, v37
	v_cvt_f16_f32_e32 v20, v14
	v_cvt_f16_f32_sdwa v21, v15 dst_sel:WORD_1 dst_unused:UNUSED_PAD src0_sel:DWORD
	v_pk_fma_f32 v[16:17], v[16:17], 0.5, v[22:23] op_sel_hi:[1,0,1]
	v_mul_f32_e32 v15, v15, v15
	v_fmac_f32_e32 v15, v14, v14
	v_mul_f32_e32 v14, v17, v17
	s_waitcnt vmcnt(5)
	v_cvt_f32_f16_sdwa v29, v32 dst_sel:DWORD dst_unused:UNUSED_PAD src0_sel:WORD_1
	v_cvt_f32_f16_e32 v28, v32
	v_fmac_f32_e32 v14, v16, v16
	v_pk_fma_f32 v[10:11], v[10:11], 0.5, v[24:25] op_sel_hi:[1,0,1]
	v_cvt_f32_f16_sdwa v35, v33 dst_sel:DWORD dst_unused:UNUSED_PAD src0_sel:WORD_1
	v_cvt_f32_f16_e32 v34, v33
	v_or_b32_e32 v20, v21, v20
	v_cvt_f16_f32_e32 v21, v16
	v_add_f32_e32 v16, v15, v14
	v_pk_fma_f32 v[12:13], v[12:13], 0.5, v[26:27] op_sel_hi:[1,0,1]
	v_cvt_f16_f32_e32 v14, v10
	v_cvt_f16_f32_sdwa v15, v11 dst_sel:WORD_1 dst_unused:UNUSED_PAD src0_sel:DWORD
	v_mul_f32_e32 v11, v11, v11
	v_fmac_f32_e32 v11, v10, v10
	v_mul_f32_e32 v10, v13, v13
	v_fmac_f32_e32 v10, v12, v12
	s_waitcnt vmcnt(4)
	v_cvt_f32_f16_sdwa v33, v30 dst_sel:DWORD dst_unused:UNUSED_PAD src0_sel:WORD_1
	v_cvt_f32_f16_e32 v32, v30
	v_add_f32_e32 v10, v11, v10
	v_pk_fma_f32 v[6:7], v[6:7], 0.5, v[28:29] op_sel_hi:[1,0,1]
	v_or_b32_e32 v14, v15, v14
	v_cvt_f16_f32_e32 v15, v12
	v_add_f32_e32 v12, v16, v10
	v_pk_fma_f32 v[8:9], v[8:9], 0.5, v[34:35] op_sel_hi:[1,0,1]
	v_cvt_f16_f32_e32 v10, v6
	v_cvt_f16_f32_sdwa v11, v7 dst_sel:WORD_1 dst_unused:UNUSED_PAD src0_sel:DWORD
	v_mul_f32_e32 v7, v7, v7
	v_fmac_f32_e32 v7, v6, v6
	v_mul_f32_e32 v6, v9, v9
	v_fmac_f32_e32 v6, v8, v8
	v_cvt_f32_f16_sdwa v37, v31 dst_sel:DWORD dst_unused:UNUSED_PAD src0_sel:WORD_1
	v_cvt_f32_f16_e32 v36, v31
	v_add_f32_e32 v6, v7, v6
	v_pk_fma_f32 v[2:3], v[2:3], 0.5, v[32:33] op_sel_hi:[1,0,1]
	v_or_b32_e32 v10, v11, v10
	v_cvt_f16_f32_e32 v11, v8
	v_add_f32_e32 v8, v12, v6
	v_cvt_f16_f32_e32 v6, v2
	v_cvt_f16_f32_sdwa v7, v3 dst_sel:WORD_1 dst_unused:UNUSED_PAD src0_sel:DWORD
	v_cvt_f16_f32_sdwa v22, v17 dst_sel:WORD_1 dst_unused:UNUSED_PAD src0_sel:DWORD
	v_pk_fma_f32 v[4:5], v[4:5], 0.5, v[36:37] op_sel_hi:[1,0,1]
	s_mov_b64 s[18:19], 0xb0
	v_cvt_f16_f32_sdwa v17, v13 dst_sel:WORD_1 dst_unused:UNUSED_PAD src0_sel:DWORD
	v_cvt_f16_f32_sdwa v13, v9 dst_sel:WORD_1 dst_unused:UNUSED_PAD src0_sel:DWORD
	v_or_b32_e32 v6, v7, v6
	v_cvt_f16_f32_e32 v7, v4
	v_cvt_f16_f32_sdwa v9, v5 dst_sel:WORD_1 dst_unused:UNUSED_PAD src0_sel:DWORD
	s_waitcnt lgkmcnt(0)
	v_lshl_add_u64 v[18:19], v[140:141], 0, s[18:19]
	v_mul_f32_e32 v3, v3, v3
	v_or_b32_e32 v21, v22, v21
	v_lshlrev_b64 v[22:23], 11, v[18:19]
	v_fmac_f32_e32 v3, v2, v2
	v_mul_f32_e32 v2, v5, v5
	v_lshl_add_u64 v[22:23], s[16:17], 0, v[22:23]
	v_fmac_f32_e32 v2, v4, v4
	v_lshl_add_u64 v[22:23], v[138:139], 1, v[22:23]
	v_or_b32_e32 v15, v17, v15
	v_or_b32_e32 v11, v13, v11
	v_or_b32_e32 v7, v9, v7
	v_add_f32_e32 v2, v3, v2
	global_store_dwordx2 v[22:23], v[20:21], off
	global_store_dwordx2 v[22:23], v[14:15], off offset:32
	global_store_dwordx2 v[22:23], v[10:11], off offset:256
	global_store_dwordx2 v[22:23], v[6:7], off offset:288
	v_add_f32_e32 v2, v8, v2
	v_mov_b32_e32 v3, v2
	s_nop 1
	v_permlane16_swap_b32_e32 v3, v2
	s_waitcnt lgkmcnt(0)
	v_add_f32_e32 v2, v2, v3
	v_mov_b32_e32 v3, v1
	s_nop 0
	v_mbcnt_lo_u32_b32 v3, -1, v3
	v_mbcnt_hi_u32_b32 v3, -1, v3
	v_lshlrev_b32_e32 v3, 2, v3
	v_xor_b32_e32 v3, 0x80, v3
	ds_bpermute_b32 v3, v3, v2
	s_and_saveexec_b64 s[16:17], s[0:1]
	s_cbranch_execz .LBB0_817
	v_lshlrev_b64 v[4:5], 6, v[18:19]
	v_lshl_add_u64 v[4:5], s[14:15], 0, v[4:5]
	s_waitcnt lgkmcnt(0)
	v_add_f32_e32 v2, v2, v3
	global_store_dword v[4:5], v2, off

.LBB0_935:
	s_and_b64 s[78:79], s[8:9], exec
	s_cselect_b32 s7, 0, 32
	v_or_b32_e32 v130, s7, v174
	s_ashr_i32 s7, s6, 31
	s_lshl_b64 s[6:7], s[6:7], 8
	v_lshl_add_u64 v[198:199], s[6:7], 0, v[186:187]
	v_lshl_add_u64 v[146:147], s[48:49], 0, v[0:1]
	v_lshlrev_b64 v[196:197], 6, v[198:199]
	v_lshl_add_u64 v[146:147], v[146:147], 0, v[196:197]
	v_add_co_u32_e32 v150, vcc, s82, v146
	v_lshlrev_b32_e32 v194, 2, v174
	v_lshlrev_b32_e32 v134, 2, v130
	s_mov_b64 s[6:7], 0x10380000
	v_addc_co_u32_e32 v151, vcc, 0, v147, vcc
	global_load_dwordx4 v[138:141], v194, s[50:51] offset:16
	global_load_dwordx4 v[142:145], v194, s[50:51]
	global_load_dwordx4 v[130:133], v134, s[50:51] offset:16
	s_nop 0
	global_load_dwordx4 v[134:137], v134, s[50:51]
	v_lshl_add_u64 v[148:149], v[146:147], 0, s[6:7]
	global_load_dwordx4 v[202:205], v[150:151], off
	global_load_dwordx4 v[206:209], v[148:149], off offset:1024
	global_load_dwordx4 v[212:215], v[148:149], off offset:2048
	global_load_dwordx4 v[162:165], v[148:149], off offset:3072
	v_add_co_u32_e32 v146, vcc, s55, v146
	s_or_b64 s[42:43], s[42:43], s[40:41]
	s_nop 0
	v_addc_co_u32_e32 v147, vcc, 0, v147, vcc
	global_load_dwordx4 v[158:161], v[146:147], off
	global_load_dwordx4 v[154:157], v[146:147], off offset:1024
	global_load_dwordx4 v[150:153], v[146:147], off offset:2048
	s_nop 0
	global_load_dwordx4 v[146:149], v[146:147], off offset:3072
	s_andn2_b64 vcc, exec, s[42:43]
	s_waitcnt vmcnt(0)
	v_mov_b32_e32 v176, v203
	v_mov_b32_e32 v177, v204
	v_mov_b32_e32 v203, v205
	v_pk_add_f32 v[176:177], v[176:177], v[202:203]
	v_add_f32_e32 v162, v162, v163
	v_add_f32_e32 v176, v176, v177
	v_add_f32_e32 v163, v164, v165
	v_mov_b32_e32 v177, v176
	s_nop 1
	v_permlane16_swap_b32_e32 v177, v176
	v_add_f32_e32 v162, v162, v163
	v_mov_b32_e32 v163, v1
	v_add_f32_e32 v158, v158, v159
	v_add_f32_e32 v159, v160, v161
	s_waitcnt lgkmcnt(0)
	v_add_f32_e32 v176, v176, v177
	v_add_f32_e32 v158, v158, v159
	v_mov_b32_e32 v177, v176
	s_nop 1
	v_permlane32_swap_b32_e32 v177, v176
	v_mov_b32_e32 v159, v1
	v_add_f32_e32 v154, v154, v155
	v_add_f32_e32 v155, v156, v157
	v_add_f32_e32 v154, v154, v155
	s_waitcnt lgkmcnt(0)
	v_add_f32_e32 v176, v176, v177
	v_fmamk_f32 v176, v176, 0x3a800000, v228
	v_rsq_f32_e32 v200, v176
	v_add_f32_e32 v176, v206, v207
	v_add_f32_e32 v177, v208, v209
	v_add_f32_e32 v176, v176, v177
	v_mov_b32_e32 v177, v1
	v_mov_b32_e32 v155, v1
	v_mbcnt_lo_u32_b32 v177, -1, v177
	v_mbcnt_hi_u32_b32 v177, -1, v177
	v_lshlrev_b32_e32 v177, 2, v177
	v_xor_b32_e32 v177, 64, v177
	ds_bpermute_b32 v177, v177, v176
	v_add_f32_e32 v150, v150, v151
	v_add_f32_e32 v151, v152, v153
	v_add_f32_e32 v150, v150, v151
	v_mov_b32_e32 v151, v1
	s_waitcnt lgkmcnt(0)
	v_add_f32_e32 v193, v176, v177
	v_mov_b32_e32 v176, v1
	v_add_f32_e32 v177, v214, v215
	v_mbcnt_lo_u32_b32 v176, -1, v176
	v_mbcnt_hi_u32_b32 v176, -1, v176
	v_lshlrev_b32_e32 v176, 2, v176
	v_xor_b32_e32 v176, 0x80, v176
	ds_bpermute_b32 v210, v176, v193
	v_add_f32_e32 v176, v212, v213
	v_add_f32_e32 v176, v176, v177
	v_mov_b32_e32 v177, v1
	v_add_f32_e32 v146, v146, v147
	v_mbcnt_lo_u32_b32 v177, -1, v177
	v_mbcnt_hi_u32_b32 v177, -1, v177
	v_lshlrev_b32_e32 v177, 2, v177
	v_xor_b32_e32 v177, 64, v177
	ds_bpermute_b32 v177, v177, v176
	v_add_f32_e32 v147, v148, v149
	v_add_f32_e32 v146, v146, v147
	v_mov_b32_e32 v147, v1
	v_pk_mul_f32 v[152:153], v[114:115], v[200:201] op_sel_hi:[1,0]
	s_waitcnt lgkmcnt(0)
	v_add_f32_e32 v208, v176, v177
	v_mov_b32_e32 v176, v1
	v_cndmask_b32_e64 v114, 0, 1, s[42:43]
	v_mbcnt_lo_u32_b32 v163, -1, v163
	v_mbcnt_hi_u32_b32 v163, -1, v163
	v_lshlrev_b32_e32 v163, 2, v163
	v_xor_b32_e32 v163, 64, v163
	ds_bpermute_b32 v163, v163, v162
	v_mbcnt_lo_u32_b32 v176, -1, v176
	v_mbcnt_hi_u32_b32 v176, -1, v176
	v_lshlrev_b32_e32 v176, 2, v176
	v_xor_b32_e32 v176, 0x80, v176
	s_waitcnt lgkmcnt(0)
	v_add_f32_e32 v206, v162, v163
	v_mov_b32_e32 v162, v1
	ds_bpermute_b32 v209, v176, v208
	v_mbcnt_lo_u32_b32 v159, -1, v159
	v_mbcnt_hi_u32_b32 v159, -1, v159
	v_lshlrev_b32_e32 v159, 2, v159
	v_xor_b32_e32 v159, 64, v159
	ds_bpermute_b32 v159, v159, v158
	v_mbcnt_lo_u32_b32 v162, -1, v162
	v_mbcnt_hi_u32_b32 v162, -1, v162
	v_lshlrev_b32_e32 v162, 2, v162
	v_xor_b32_e32 v162, 0x80, v162
	s_waitcnt lgkmcnt(0)
	v_add_f32_e32 v204, v158, v159
	v_mov_b32_e32 v158, v1
	ds_bpermute_b32 v207, v162, v206
	v_mbcnt_lo_u32_b32 v155, -1, v155
	v_mbcnt_hi_u32_b32 v155, -1, v155
	v_lshlrev_b32_e32 v155, 2, v155
	v_xor_b32_e32 v155, 64, v155
	ds_bpermute_b32 v155, v155, v154
	v_mbcnt_lo_u32_b32 v158, -1, v158
	v_mbcnt_hi_u32_b32 v158, -1, v158
	v_lshlrev_b32_e32 v158, 2, v158
	v_xor_b32_e32 v158, 0x80, v158
	s_waitcnt lgkmcnt(0)
	v_add_f32_e32 v202, v154, v155
	v_mov_b32_e32 v154, v1
	ds_bpermute_b32 v205, v158, v204
	v_mbcnt_lo_u32_b32 v151, -1, v151
	v_mbcnt_hi_u32_b32 v151, -1, v151
	v_lshlrev_b32_e32 v151, 2, v151
	v_xor_b32_e32 v151, 64, v151
	ds_bpermute_b32 v151, v151, v150
	v_mbcnt_lo_u32_b32 v154, -1, v154
	v_mbcnt_hi_u32_b32 v154, -1, v154
	v_lshlrev_b32_e32 v154, 2, v154
	v_xor_b32_e32 v154, 0x80, v154
	s_waitcnt lgkmcnt(0)
	v_add_f32_e32 v164, v150, v151
	v_mov_b32_e32 v150, v1
	ds_bpermute_b32 v203, v154, v202
	v_mbcnt_lo_u32_b32 v147, -1, v147
	v_mbcnt_hi_u32_b32 v147, -1, v147
	v_lshlrev_b32_e32 v147, 2, v147
	v_xor_b32_e32 v147, 64, v147
	ds_bpermute_b32 v147, v147, v146
	v_mbcnt_lo_u32_b32 v150, -1, v150
	v_mbcnt_hi_u32_b32 v150, -1, v150
	v_lshlrev_b32_e32 v150, 2, v150
	v_xor_b32_e32 v150, 0x80, v150
	s_waitcnt lgkmcnt(0)
	v_add_f32_e32 v162, v146, v147
	v_mov_b32_e32 v146, v1
	ds_bpermute_b32 v165, v150, v164
	v_mbcnt_lo_u32_b32 v146, -1, v146
	v_mbcnt_hi_u32_b32 v146, -1, v146
	v_lshlrev_b32_e32 v146, 2, v146
	v_xor_b32_e32 v146, 0x80, v146
	ds_bpermute_b32 v163, v146, v162
	v_pk_mul_f32 v[148:149], v[126:127], v[200:201] op_sel_hi:[1,0]
	v_pk_mul_f32 v[158:159], v[128:129], v[200:201] op_sel_hi:[1,0]
	v_pk_mul_f32 v[156:157], v[122:123], v[200:201] op_sel_hi:[1,0]
	v_pk_mul_f32 v[160:161], v[124:125], v[200:201] op_sel_hi:[1,0]
	v_pk_mul_f32 v[146:147], v[118:119], v[200:201] op_sel_hi:[1,0]
	v_pk_mul_f32 v[154:155], v[120:121], v[200:201] op_sel_hi:[1,0]
	v_pk_mul_f32 v[150:151], v[116:117], v[200:201] op_sel_hi:[1,0]
	v_cmp_ne_u32_e64 s[6:7], 1, v114
	s_cbranch_vccnz .LBB0_937
	v_mul_f32_e32 v114, 0x3d372713, v148
	v_mul_f32_e32 v115, 0x3d372713, v149
	v_mul_f32_e32 v114, v148, v114
	v_mul_f32_e32 v115, v149, v115
	v_fma_f32 v114, v148, v114, v148
	v_fma_f32 v115, v149, v115, v149
	v_mul_f32_e32 v114, 0x3f4c422a, v114
	v_mul_f32_e32 v115, 0x3f4c422a, v115
	v_mul_f32_e32 v114, 0xc038aa3b, v114
	v_mul_f32_e32 v115, 0xc038aa3b, v115
	v_exp_f32_e32 v114, v114
	v_exp_f32_e32 v115, v115
	v_add_f32_e32 v114, 1.0, v114
	v_add_f32_e32 v115, 1.0, v115
	v_rcp_f32_e32 v114, v114
	v_rcp_f32_e32 v115, v115
	s_nop 0
	v_pk_mul_f32 v[148:149], v[148:149], v[114:115]
	v_mul_f32_e32 v114, 0x3d372713, v158
	v_mul_f32_e32 v115, 0x3d372713, v159
	v_mul_f32_e32 v114, v158, v114
	v_mul_f32_e32 v115, v159, v115
	v_fma_f32 v114, v158, v114, v158
	v_fma_f32 v115, v159, v115, v159
	v_mul_f32_e32 v114, 0x3f4c422a, v114
	v_mul_f32_e32 v115, 0x3f4c422a, v115
	v_mul_f32_e32 v114, 0xc038aa3b, v114
	v_mul_f32_e32 v115, 0xc038aa3b, v115
	v_exp_f32_e32 v114, v114
	v_exp_f32_e32 v115, v115
	v_add_f32_e32 v114, 1.0, v114
	v_add_f32_e32 v115, 1.0, v115
	v_rcp_f32_e32 v114, v114
	v_rcp_f32_e32 v115, v115
	s_nop 0
	v_pk_mul_f32 v[158:159], v[158:159], v[114:115]
	v_mul_f32_e32 v114, 0x3d372713, v156
	v_mul_f32_e32 v115, 0x3d372713, v157
	v_mul_f32_e32 v114, v156, v114
	v_mul_f32_e32 v115, v157, v115
	v_fma_f32 v114, v156, v114, v156
	v_fma_f32 v115, v157, v115, v157
	v_mul_f32_e32 v114, 0x3f4c422a, v114
	v_mul_f32_e32 v115, 0x3f4c422a, v115
	v_mul_f32_e32 v114, 0xc038aa3b, v114
	v_mul_f32_e32 v115, 0xc038aa3b, v115
	v_exp_f32_e32 v114, v114
	v_exp_f32_e32 v115, v115
	v_add_f32_e32 v114, 1.0, v114
	v_add_f32_e32 v115, 1.0, v115
	v_rcp_f32_e32 v114, v114
	v_rcp_f32_e32 v115, v115
	s_nop 0
	v_pk_mul_f32 v[156:157], v[156:157], v[114:115]
	v_mul_f32_e32 v114, 0x3d372713, v160
	v_mul_f32_e32 v115, 0x3d372713, v161
	v_mul_f32_e32 v114, v160, v114
	v_mul_f32_e32 v115, v161, v115
	v_fma_f32 v114, v160, v114, v160
	v_fma_f32 v115, v161, v115, v161
	v_mul_f32_e32 v114, 0x3f4c422a, v114
	v_mul_f32_e32 v115, 0x3f4c422a, v115
	v_mul_f32_e32 v114, 0xc038aa3b, v114
	v_mul_f32_e32 v115, 0xc038aa3b, v115
	v_exp_f32_e32 v114, v114
	v_exp_f32_e32 v115, v115
	v_add_f32_e32 v114, 1.0, v114
	v_add_f32_e32 v115, 1.0, v115
	v_rcp_f32_e32 v114, v114
	v_rcp_f32_e32 v115, v115
	s_nop 0
	v_pk_mul_f32 v[160:161], v[160:161], v[114:115]
	v_mul_f32_e32 v114, 0x3d372713, v146
	v_mul_f32_e32 v115, 0x3d372713, v147
	v_mul_f32_e32 v114, v146, v114
	v_mul_f32_e32 v115, v147, v115
	v_fma_f32 v114, v146, v114, v146
	v_fma_f32 v115, v147, v115, v147
	v_mul_f32_e32 v114, 0x3f4c422a, v114
	v_mul_f32_e32 v115, 0x3f4c422a, v115
	v_mul_f32_e32 v114, 0xc038aa3b, v114
	v_mul_f32_e32 v115, 0xc038aa3b, v115
	v_exp_f32_e32 v114, v114
	v_exp_f32_e32 v115, v115
	v_add_f32_e32 v114, 1.0, v114
	v_add_f32_e32 v115, 1.0, v115
	v_rcp_f32_e32 v114, v114
	v_rcp_f32_e32 v115, v115
	s_nop 0
	v_pk_mul_f32 v[146:147], v[146:147], v[114:115]
	v_mul_f32_e32 v114, 0x3d372713, v154
	v_mul_f32_e32 v115, 0x3d372713, v155
	v_mul_f32_e32 v114, v154, v114
	v_mul_f32_e32 v115, v155, v115
	v_fma_f32 v114, v154, v114, v154
	v_fma_f32 v115, v155, v115, v155
	v_mul_f32_e32 v114, 0x3f4c422a, v114
	v_mul_f32_e32 v115, 0x3f4c422a, v115
	v_mul_f32_e32 v114, 0xc038aa3b, v114
	v_mul_f32_e32 v115, 0xc038aa3b, v115
	v_exp_f32_e32 v114, v114
	v_exp_f32_e32 v115, v115
	v_add_f32_e32 v114, 1.0, v114
	v_add_f32_e32 v115, 1.0, v115
	v_rcp_f32_e32 v114, v114
	v_rcp_f32_e32 v115, v115
	s_nop 0
	v_pk_mul_f32 v[154:155], v[154:155], v[114:115]
	v_mul_f32_e32 v114, 0x3d372713, v152
	v_mul_f32_e32 v115, 0x3d372713, v153
	v_mul_f32_e32 v114, v152, v114
	v_mul_f32_e32 v115, v153, v115
	v_fma_f32 v114, v152, v114, v152
	v_fma_f32 v115, v153, v115, v153
	v_mul_f32_e32 v114, 0x3f4c422a, v114
	v_mul_f32_e32 v115, 0x3f4c422a, v115
	v_mul_f32_e32 v114, 0xc038aa3b, v114
	v_mul_f32_e32 v115, 0xc038aa3b, v115
	v_exp_f32_e32 v114, v114
	v_exp_f32_e32 v115, v115
	v_add_f32_e32 v114, 1.0, v114
	v_add_f32_e32 v115, 1.0, v115
	v_rcp_f32_e32 v114, v114
	v_rcp_f32_e32 v115, v115
	s_nop 0
	v_pk_mul_f32 v[152:153], v[152:153], v[114:115]
	v_mul_f32_e32 v114, 0x3d372713, v150
	v_mul_f32_e32 v115, 0x3d372713, v151
	v_mul_f32_e32 v114, v150, v114
	v_mul_f32_e32 v115, v151, v115
	v_fma_f32 v114, v150, v114, v150
	v_fma_f32 v115, v151, v115, v151
	v_mul_f32_e32 v114, 0x3f4c422a, v114
	v_mul_f32_e32 v115, 0x3f4c422a, v115
	v_mul_f32_e32 v114, 0xc038aa3b, v114
	v_mul_f32_e32 v115, 0xc038aa3b, v115
	v_exp_f32_e32 v114, v114
	v_exp_f32_e32 v115, v115
	v_add_f32_e32 v114, 1.0, v114
	v_add_f32_e32 v115, 1.0, v115
	v_rcp_f32_e32 v114, v114
	v_rcp_f32_e32 v115, v115
	s_nop 0
	v_pk_mul_f32 v[150:151], v[150:151], v[114:115]
.LBB0_937:
	v_pk_mul_f32 v[114:115], s[44:45], v[142:143] op_sel_hi:[0,1]
	v_cndmask_b32_e64 v121, v115, 1.0, s[46:47]
	v_cndmask_b32_e64 v120, v114, 1.0, s[46:47]
	v_pk_mul_f32 v[114:115], s[44:45], v[138:139] op_sel_hi:[0,1]
	v_cndmask_b32_e64 v119, v115, 1.0, s[46:47]
	v_cndmask_b32_e64 v118, v114, 1.0, s[46:47]
	v_pk_mul_f32 v[114:115], s[44:45], v[134:135] op_sel_hi:[0,1]
	v_cndmask_b32_e64 v125, v115, 1.0, s[46:47]
	v_cndmask_b32_e64 v124, v114, 1.0, s[46:47]
	v_pk_mul_f32 v[114:115], s[44:45], v[130:131] op_sel_hi:[0,1]
	v_cndmask_b32_e64 v123, v115, 1.0, s[46:47]
	v_cndmask_b32_e64 v122, v114, 1.0, s[46:47]
	v_pk_mul_f32 v[114:115], s[44:45], v[144:145] op_sel_hi:[0,1]
	v_cndmask_b32_e64 v129, v115, 1.0, s[46:47]
	v_cndmask_b32_e64 v128, v114, 1.0, s[46:47]
	v_pk_mul_f32 v[114:115], s[44:45], v[140:141] op_sel_hi:[0,1]
	s_xor_b64 s[42:43], s[8:9], -1
	v_cndmask_b32_e64 v127, v115, 1.0, s[46:47]
	v_cndmask_b32_e64 v126, v114, 1.0, s[46:47]
	v_pk_mul_f32 v[114:115], s[44:45], v[136:137] op_sel_hi:[0,1]
	s_or_b64 s[8:9], s[8:9], s[36:37]
	v_cndmask_b32_e64 v135, v115, 1.0, s[46:47]
	v_cndmask_b32_e64 v134, v114, 1.0, s[46:47]
	v_pk_mul_f32 v[114:115], s[44:45], v[132:133] op_sel_hi:[0,1]
	s_or_b64 s[36:37], s[40:41], s[8:9]
	v_cndmask_b32_e64 v130, v114, 1.0, s[46:47]
	v_cndmask_b32_e64 v114, 0, 1, s[36:37]
	v_cndmask_b32_e64 v131, v115, 1.0, s[46:47]
	v_cmp_ne_u32_e64 s[8:9], 1, v114
	s_andn2_b64 vcc, exec, s[36:37]
	s_cbranch_vccnz .LBB0_943
	v_pk_mul_f32 v[114:115], v[148:149], v[148:149]
	v_pk_mul_f32 v[116:117], v[158:159], v[158:159]
	v_add_f32_e32 v114, v115, v114
	v_add_f32_e32 v114, v116, v114
	v_pk_mul_f32 v[132:133], v[156:157], v[156:157]
	v_add_f32_e32 v114, v117, v114
	v_add_f32_e32 v114, v132, v114
	v_pk_mul_f32 v[136:137], v[160:161], v[160:161]
	v_add_f32_e32 v114, v133, v114
	v_add_f32_e32 v114, v136, v114
	v_add_f32_e32 v114, v137, v114
	v_mov_b32_e32 v115, v114
	s_nop 1
	v_permlane16_swap_b32_e32 v115, v114
	v_pk_mul_f32 v[116:117], v[146:147], v[146:147]
	v_pk_mul_f32 v[132:133], v[154:155], v[154:155]
	v_pk_mul_f32 v[136:137], v[152:153], v[152:153]
	v_pk_mul_f32 v[138:139], v[150:151], v[150:151]
	s_waitcnt lgkmcnt(0)
	v_add_f32_e32 v114, v114, v115
	v_mov_b32_e32 v115, v1
	s_mov_b64 s[36:37], -1
	v_mbcnt_lo_u32_b32 v115, -1, v115
	v_mbcnt_hi_u32_b32 v115, -1, v115
	v_lshlrev_b32_e32 v115, 2, v115
	v_xor_b32_e32 v115, 0x80, v115
	ds_bpermute_b32 v115, v115, v114
	s_and_b64 vcc, exec, s[42:43]
	s_waitcnt lgkmcnt(0)
	v_add_f32_e32 v115, v114, v115
	v_add_f32_e32 v114, v117, v116
	v_add_f32_e32 v114, v132, v114
	v_add_f32_e32 v114, v133, v114
	v_add_f32_e32 v114, v136, v114
	v_add_f32_e32 v114, v137, v114
	v_add_f32_e32 v114, v138, v114
	v_add_f32_e32 v114, v139, v114
	v_mov_b32_e32 v116, v114
	s_nop 1
	v_permlane16_swap_b32_e32 v116, v114
	s_waitcnt lgkmcnt(0)
	v_add_f32_e32 v114, v114, v116
	v_mov_b32_e32 v116, v1
	s_nop 0
	v_mbcnt_lo_u32_b32 v116, -1, v116
	v_mbcnt_hi_u32_b32 v116, -1, v116
	v_lshlrev_b32_e32 v116, 2, v116
	v_xor_b32_e32 v116, 0x80, v116
	ds_bpermute_b32 v116, v116, v114
	s_waitcnt lgkmcnt(0)
	v_add_f32_e32 v117, v114, v116
	s_cbranch_vccz .LBB0_940
	v_add_f32_e32 v114, v115, v117
	v_fmamk_f32 v114, v114, 0x3c800000, v228
	v_rsq_f32_e32 v114, v114
	s_mov_b64 s[36:37], 0

.LBB0_965:
	v_pk_mul_f32 v[98:99], v[110:111], v[110:111]
	v_pk_mul_f32 v[100:101], v[116:117], v[116:117]
	v_add_f32_e32 v98, v99, v98
	v_add_f32_e32 v98, v100, v98
	v_pk_mul_f32 v[136:137], v[112:113], v[112:113]
	v_add_f32_e32 v98, v101, v98
	v_add_f32_e32 v98, v136, v98
	v_pk_mul_f32 v[138:139], v[132:133], v[132:133]
	v_add_f32_e32 v98, v137, v98
	v_add_f32_e32 v98, v138, v98
	v_add_f32_e32 v98, v139, v98
	v_mov_b32_e32 v99, v98
	s_nop 1
	v_permlane16_swap_b32_e32 v99, v98
	v_pk_mul_f32 v[100:101], v[102:103], v[102:103]
	v_pk_mul_f32 v[136:137], v[106:107], v[106:107]
	v_pk_mul_f32 v[138:139], v[104:105], v[104:105]
	v_pk_mul_f32 v[140:141], v[108:109], v[108:109]
	s_waitcnt lgkmcnt(0)
	v_add_f32_e32 v98, v98, v99
	v_mov_b32_e32 v99, v1
	s_mov_b64 s[42:43], -1
	v_mbcnt_lo_u32_b32 v99, -1, v99
	v_mbcnt_hi_u32_b32 v99, -1, v99
	v_lshlrev_b32_e32 v99, 2, v99
	v_xor_b32_e32 v99, 0x80, v99
	ds_bpermute_b32 v99, v99, v98
	s_and_b64 vcc, exec, s[10:11]
	s_waitcnt lgkmcnt(0)
	v_add_f32_e32 v99, v98, v99
	v_add_f32_e32 v98, v101, v100
	v_add_f32_e32 v98, v136, v98
	v_add_f32_e32 v98, v137, v98
	v_add_f32_e32 v98, v138, v98
	v_add_f32_e32 v98, v139, v98
	v_add_f32_e32 v98, v140, v98
	v_add_f32_e32 v98, v141, v98
	v_mov_b32_e32 v100, v98
	s_nop 1
	v_permlane16_swap_b32_e32 v100, v98
	s_waitcnt lgkmcnt(0)
	v_add_f32_e32 v98, v98, v100
	v_mov_b32_e32 v100, v1
	s_nop 0
	v_mbcnt_lo_u32_b32 v100, -1, v100
	v_mbcnt_hi_u32_b32 v100, -1, v100
	v_lshlrev_b32_e32 v100, 2, v100
	v_xor_b32_e32 v100, 0x80, v100
	ds_bpermute_b32 v100, v100, v98
	s_waitcnt lgkmcnt(0)
	v_add_f32_e32 v101, v98, v100
	s_cbranch_vccnz .LBB0_967
	v_add_f32_e32 v98, v99, v101
	v_fmamk_f32 v98, v98, 0x3c800000, v228
	v_rsq_f32_e32 v98, v98
	s_mov_b64 s[42:43], 0

.LBB0_991:
	v_pk_mul_f32 v[82:83], v[94:95], v[94:95]
	v_pk_mul_f32 v[84:85], v[100:101], v[100:101]
	v_add_f32_e32 v82, v83, v82
	v_add_f32_e32 v82, v84, v82
	v_pk_mul_f32 v[104:105], v[96:97], v[96:97]
	v_add_f32_e32 v82, v85, v82
	v_add_f32_e32 v82, v104, v82
	v_pk_mul_f32 v[106:107], v[102:103], v[102:103]
	v_add_f32_e32 v82, v105, v82
	v_add_f32_e32 v82, v106, v82
	v_add_f32_e32 v82, v107, v82
	v_mov_b32_e32 v83, v82
	s_nop 1
	v_permlane16_swap_b32_e32 v83, v82
	v_pk_mul_f32 v[84:85], v[86:87], v[86:87]
	v_pk_mul_f32 v[104:105], v[90:91], v[90:91]
	v_pk_mul_f32 v[106:107], v[88:89], v[88:89]
	v_pk_mul_f32 v[108:109], v[92:93], v[92:93]
	s_waitcnt lgkmcnt(0)
	v_add_f32_e32 v82, v82, v83
	v_mov_b32_e32 v83, v1
	s_mov_b64 s[42:43], -1
	v_mbcnt_lo_u32_b32 v83, -1, v83
	v_mbcnt_hi_u32_b32 v83, -1, v83
	v_lshlrev_b32_e32 v83, 2, v83
	v_xor_b32_e32 v83, 0x80, v83
	ds_bpermute_b32 v83, v83, v82
	s_and_b64 vcc, exec, s[10:11]
	s_waitcnt lgkmcnt(0)
	v_add_f32_e32 v83, v82, v83
	v_add_f32_e32 v82, v85, v84
	v_add_f32_e32 v82, v104, v82
	v_add_f32_e32 v82, v105, v82
	v_add_f32_e32 v82, v106, v82
	v_add_f32_e32 v82, v107, v82
	v_add_f32_e32 v82, v108, v82
	v_add_f32_e32 v82, v109, v82
	v_mov_b32_e32 v84, v82
	s_nop 1
	v_permlane16_swap_b32_e32 v84, v82
	s_waitcnt lgkmcnt(0)
	v_add_f32_e32 v82, v82, v84
	v_mov_b32_e32 v84, v1
	s_nop 0
	v_mbcnt_lo_u32_b32 v84, -1, v84
	v_mbcnt_hi_u32_b32 v84, -1, v84
	v_lshlrev_b32_e32 v84, 2, v84
	v_xor_b32_e32 v84, 0x80, v84
	ds_bpermute_b32 v84, v84, v82
	s_waitcnt lgkmcnt(0)
	v_add_f32_e32 v85, v82, v84
	s_cbranch_vccnz .LBB0_993
	v_add_f32_e32 v82, v83, v85
	v_fmamk_f32 v82, v82, 0x3c800000, v228
	v_rsq_f32_e32 v82, v82
	s_mov_b64 s[42:43], 0

.LBB0_1017:
	v_pk_mul_f32 v[66:67], v[78:79], v[78:79]
	v_pk_mul_f32 v[68:69], v[84:85], v[84:85]
	v_add_f32_e32 v66, v67, v66
	v_add_f32_e32 v66, v68, v66
	v_pk_mul_f32 v[88:89], v[80:81], v[80:81]
	v_add_f32_e32 v66, v69, v66
	v_add_f32_e32 v66, v88, v66
	v_pk_mul_f32 v[90:91], v[86:87], v[86:87]
	v_add_f32_e32 v66, v89, v66
	v_add_f32_e32 v66, v90, v66
	v_add_f32_e32 v66, v91, v66
	v_mov_b32_e32 v67, v66
	s_nop 1
	v_permlane16_swap_b32_e32 v67, v66
	v_pk_mul_f32 v[68:69], v[70:71], v[70:71]
	v_pk_mul_f32 v[88:89], v[74:75], v[74:75]
	v_pk_mul_f32 v[90:91], v[72:73], v[72:73]
	v_pk_mul_f32 v[92:93], v[76:77], v[76:77]
	s_waitcnt lgkmcnt(0)
	v_add_f32_e32 v66, v66, v67
	v_mov_b32_e32 v67, v1
	s_mov_b64 s[42:43], -1
	v_mbcnt_lo_u32_b32 v67, -1, v67
	v_mbcnt_hi_u32_b32 v67, -1, v67
	v_lshlrev_b32_e32 v67, 2, v67
	v_xor_b32_e32 v67, 0x80, v67
	ds_bpermute_b32 v67, v67, v66
	s_and_b64 vcc, exec, s[10:11]
	s_waitcnt lgkmcnt(0)
	v_add_f32_e32 v67, v66, v67
	v_add_f32_e32 v66, v69, v68
	v_add_f32_e32 v66, v88, v66
	v_add_f32_e32 v66, v89, v66
	v_add_f32_e32 v66, v90, v66
	v_add_f32_e32 v66, v91, v66
	v_add_f32_e32 v66, v92, v66
	v_add_f32_e32 v66, v93, v66
	v_mov_b32_e32 v68, v66
	s_nop 1
	v_permlane16_swap_b32_e32 v68, v66
	s_waitcnt lgkmcnt(0)
	v_add_f32_e32 v66, v66, v68
	v_mov_b32_e32 v68, v1
	s_nop 0
	v_mbcnt_lo_u32_b32 v68, -1, v68
	v_mbcnt_hi_u32_b32 v68, -1, v68
	v_lshlrev_b32_e32 v68, 2, v68
	v_xor_b32_e32 v68, 0x80, v68
	ds_bpermute_b32 v68, v68, v66
	s_waitcnt lgkmcnt(0)
	v_add_f32_e32 v69, v66, v68
	s_cbranch_vccnz .LBB0_1019
	v_add_f32_e32 v66, v67, v69
	v_fmamk_f32 v66, v66, 0x3c800000, v228
	v_rsq_f32_e32 v66, v66
	s_mov_b64 s[42:43], 0

.LBB0_1043:
	v_pk_mul_f32 v[50:51], v[62:63], v[62:63]
	v_pk_mul_f32 v[52:53], v[68:69], v[68:69]
	v_add_f32_e32 v50, v51, v50
	v_add_f32_e32 v50, v52, v50
	v_pk_mul_f32 v[72:73], v[64:65], v[64:65]
	v_add_f32_e32 v50, v53, v50
	v_add_f32_e32 v50, v72, v50
	v_pk_mul_f32 v[74:75], v[70:71], v[70:71]
	v_add_f32_e32 v50, v73, v50
	v_add_f32_e32 v50, v74, v50
	v_add_f32_e32 v50, v75, v50
	v_mov_b32_e32 v51, v50
	s_nop 1
	v_permlane16_swap_b32_e32 v51, v50
	v_pk_mul_f32 v[52:53], v[54:55], v[54:55]
	v_pk_mul_f32 v[72:73], v[58:59], v[58:59]
	v_pk_mul_f32 v[74:75], v[56:57], v[56:57]
	v_pk_mul_f32 v[76:77], v[60:61], v[60:61]
	s_waitcnt lgkmcnt(0)
	v_add_f32_e32 v50, v50, v51
	v_mov_b32_e32 v51, v1
	s_mov_b64 s[42:43], -1
	v_mbcnt_lo_u32_b32 v51, -1, v51
	v_mbcnt_hi_u32_b32 v51, -1, v51
	v_lshlrev_b32_e32 v51, 2, v51
	v_xor_b32_e32 v51, 0x80, v51
	ds_bpermute_b32 v51, v51, v50
	s_and_b64 vcc, exec, s[10:11]
	s_waitcnt lgkmcnt(0)
	v_add_f32_e32 v51, v50, v51
	v_add_f32_e32 v50, v53, v52
	v_add_f32_e32 v50, v72, v50
	v_add_f32_e32 v50, v73, v50
	v_add_f32_e32 v50, v74, v50
	v_add_f32_e32 v50, v75, v50
	v_add_f32_e32 v50, v76, v50
	v_add_f32_e32 v50, v77, v50
	v_mov_b32_e32 v52, v50
	s_nop 1
	v_permlane16_swap_b32_e32 v52, v50
	s_waitcnt lgkmcnt(0)
	v_add_f32_e32 v50, v50, v52
	v_mov_b32_e32 v52, v1
	s_nop 0
	v_mbcnt_lo_u32_b32 v52, -1, v52
	v_mbcnt_hi_u32_b32 v52, -1, v52
	v_lshlrev_b32_e32 v52, 2, v52
	v_xor_b32_e32 v52, 0x80, v52
	ds_bpermute_b32 v52, v52, v50
	s_waitcnt lgkmcnt(0)
	v_add_f32_e32 v53, v50, v52
	s_cbranch_vccnz .LBB0_1045
	v_add_f32_e32 v50, v51, v53
	v_fmamk_f32 v50, v50, 0x3c800000, v228
	v_rsq_f32_e32 v50, v50
	s_mov_b64 s[42:43], 0

.LBB0_1069:
	v_pk_mul_f32 v[34:35], v[46:47], v[46:47]
	v_pk_mul_f32 v[36:37], v[52:53], v[52:53]
	v_add_f32_e32 v34, v35, v34
	v_add_f32_e32 v34, v36, v34
	v_pk_mul_f32 v[56:57], v[48:49], v[48:49]
	v_add_f32_e32 v34, v37, v34
	v_add_f32_e32 v34, v56, v34
	v_pk_mul_f32 v[58:59], v[54:55], v[54:55]
	v_add_f32_e32 v34, v57, v34
	v_add_f32_e32 v34, v58, v34
	v_add_f32_e32 v34, v59, v34
	v_mov_b32_e32 v35, v34
	s_nop 1
	v_permlane16_swap_b32_e32 v35, v34
	v_pk_mul_f32 v[36:37], v[38:39], v[38:39]
	v_pk_mul_f32 v[56:57], v[42:43], v[42:43]
	v_pk_mul_f32 v[58:59], v[40:41], v[40:41]
	v_pk_mul_f32 v[60:61], v[44:45], v[44:45]
	s_waitcnt lgkmcnt(0)
	v_add_f32_e32 v34, v34, v35
	v_mov_b32_e32 v35, v1
	s_mov_b64 s[42:43], -1
	v_mbcnt_lo_u32_b32 v35, -1, v35
	v_mbcnt_hi_u32_b32 v35, -1, v35
	v_lshlrev_b32_e32 v35, 2, v35
	v_xor_b32_e32 v35, 0x80, v35
	ds_bpermute_b32 v35, v35, v34
	s_and_b64 vcc, exec, s[10:11]
	s_waitcnt lgkmcnt(0)
	v_add_f32_e32 v35, v34, v35
	v_add_f32_e32 v34, v37, v36
	v_add_f32_e32 v34, v56, v34
	v_add_f32_e32 v34, v57, v34
	v_add_f32_e32 v34, v58, v34
	v_add_f32_e32 v34, v59, v34
	v_add_f32_e32 v34, v60, v34
	v_add_f32_e32 v34, v61, v34
	v_mov_b32_e32 v36, v34
	s_nop 1
	v_permlane16_swap_b32_e32 v36, v34
	s_waitcnt lgkmcnt(0)
	v_add_f32_e32 v34, v34, v36
	v_mov_b32_e32 v36, v1
	s_nop 0
	v_mbcnt_lo_u32_b32 v36, -1, v36
	v_mbcnt_hi_u32_b32 v36, -1, v36
	v_lshlrev_b32_e32 v36, 2, v36
	v_xor_b32_e32 v36, 0x80, v36
	ds_bpermute_b32 v36, v36, v34
	s_waitcnt lgkmcnt(0)
	v_add_f32_e32 v37, v34, v36
	s_cbranch_vccnz .LBB0_1071
	v_add_f32_e32 v34, v35, v37
	v_fmamk_f32 v34, v34, 0x3c800000, v228
	v_rsq_f32_e32 v34, v34
	s_mov_b64 s[42:43], 0

.LBB0_1095:
	v_pk_mul_f32 v[18:19], v[30:31], v[30:31]
	v_pk_mul_f32 v[20:21], v[36:37], v[36:37]
	v_add_f32_e32 v18, v19, v18
	v_add_f32_e32 v18, v20, v18
	v_pk_mul_f32 v[40:41], v[32:33], v[32:33]
	v_add_f32_e32 v18, v21, v18
	v_add_f32_e32 v18, v40, v18
	v_pk_mul_f32 v[42:43], v[38:39], v[38:39]
	v_add_f32_e32 v18, v41, v18
	v_add_f32_e32 v18, v42, v18
	v_add_f32_e32 v18, v43, v18
	v_mov_b32_e32 v19, v18
	s_nop 1
	v_permlane16_swap_b32_e32 v19, v18
	v_pk_mul_f32 v[20:21], v[22:23], v[22:23]
	v_pk_mul_f32 v[40:41], v[26:27], v[26:27]
	v_pk_mul_f32 v[42:43], v[24:25], v[24:25]
	v_pk_mul_f32 v[44:45], v[28:29], v[28:29]
	s_waitcnt lgkmcnt(0)
	v_add_f32_e32 v18, v18, v19
	v_mov_b32_e32 v19, v1
	s_mov_b64 s[42:43], -1
	v_mbcnt_lo_u32_b32 v19, -1, v19
	v_mbcnt_hi_u32_b32 v19, -1, v19
	v_lshlrev_b32_e32 v19, 2, v19
	v_xor_b32_e32 v19, 0x80, v19
	ds_bpermute_b32 v19, v19, v18
	s_and_b64 vcc, exec, s[10:11]
	s_waitcnt lgkmcnt(0)
	v_add_f32_e32 v19, v18, v19
	v_add_f32_e32 v18, v21, v20
	v_add_f32_e32 v18, v40, v18
	v_add_f32_e32 v18, v41, v18
	v_add_f32_e32 v18, v42, v18
	v_add_f32_e32 v18, v43, v18
	v_add_f32_e32 v18, v44, v18
	v_add_f32_e32 v18, v45, v18
	v_mov_b32_e32 v20, v18
	s_nop 1
	v_permlane16_swap_b32_e32 v20, v18
	s_waitcnt lgkmcnt(0)
	v_add_f32_e32 v18, v18, v20
	v_mov_b32_e32 v20, v1
	s_nop 0
	v_mbcnt_lo_u32_b32 v20, -1, v20
	v_mbcnt_hi_u32_b32 v20, -1, v20
	v_lshlrev_b32_e32 v20, 2, v20
	v_xor_b32_e32 v20, 0x80, v20
	ds_bpermute_b32 v20, v20, v18
	s_waitcnt lgkmcnt(0)
	v_add_f32_e32 v21, v18, v20
	s_cbranch_vccnz .LBB0_1097
	v_add_f32_e32 v18, v19, v21
	v_fmamk_f32 v18, v18, 0x3c800000, v228
	v_rsq_f32_e32 v18, v18
	s_mov_b64 s[42:43], 0

.LBB0_1121:
	v_pk_mul_f32 v[2:3], v[14:15], v[14:15]
	v_pk_mul_f32 v[4:5], v[20:21], v[20:21]
	v_add_f32_e32 v2, v3, v2
	v_add_f32_e32 v2, v4, v2
	v_mov_b32_e32 v3, v1
	v_pk_mul_f32 v[24:25], v[16:17], v[16:17]
	v_add_f32_e32 v2, v5, v2
	v_add_f32_e32 v2, v24, v2
	v_mbcnt_lo_u32_b32 v3, -1, v3
	v_pk_mul_f32 v[26:27], v[22:23], v[22:23]
	v_add_f32_e32 v2, v25, v2
	v_mbcnt_hi_u32_b32 v3, -1, v3
	v_add_f32_e32 v2, v26, v2
	v_lshlrev_b32_e32 v3, 2, v3
	v_add_f32_e32 v2, v27, v2
	v_xor_b32_e32 v3, 64, v3
	ds_bpermute_b32 v3, v3, v2
	v_pk_mul_f32 v[4:5], v[10:11], v[10:11]
	v_pk_mul_f32 v[24:25], v[8:9], v[8:9]
	v_pk_mul_f32 v[26:27], v[12:13], v[12:13]
	s_and_b64 vcc, exec, s[10:11]
	s_waitcnt lgkmcnt(0)
	v_add_f32_e32 v28, v2, v3
	v_mov_b32_e32 v2, v1
	s_mov_b64 s[6:7], -1
	v_mbcnt_lo_u32_b32 v29, -1, v2
	v_pk_mul_f32 v[2:3], v[6:7], v[6:7]
	s_nop 0
	v_add_f32_e32 v2, v3, v2
	v_add_f32_e32 v2, v4, v2
	v_add_f32_e32 v2, v5, v2
	v_add_f32_e32 v2, v24, v2
	v_add_f32_e32 v2, v25, v2
	v_add_f32_e32 v2, v26, v2
	v_add_f32_e32 v2, v27, v2
	v_mov_b32_e32 v3, v2
	s_nop 1
	v_permlane16_swap_b32_e32 v3, v2
	v_mbcnt_hi_u32_b32 v4, -1, v29
	v_lshlrev_b32_e32 v4, 2, v4
	v_xor_b32_e32 v4, 0x80, v4
	ds_bpermute_b32 v4, v4, v28
	s_waitcnt lgkmcnt(1)
	v_add_f32_e32 v2, v2, v3
	v_mov_b32_e32 v3, v1
	s_waitcnt lgkmcnt(0)
	v_add_f32_e32 v5, v28, v4
	v_mbcnt_lo_u32_b32 v3, -1, v3
	v_mbcnt_hi_u32_b32 v3, -1, v3
	v_lshlrev_b32_e32 v3, 2, v3
	v_xor_b32_e32 v3, 0x80, v3
	ds_bpermute_b32 v3, v3, v2
	s_waitcnt lgkmcnt(0)
	v_add_f32_e32 v3, v2, v3
	s_cbranch_vccnz .LBB0_1123
	v_add_f32_e32 v2, v5, v3
	v_fmamk_f32 v2, v2, 0x3c800000, v228
	v_rsq_f32_e32 v2, v2
	s_mov_b64 s[6:7], 0

.LBB0_1990:
	s_ashr_i32 s23, s22, 31
	s_lshl_b64 s[22:23], s[22:23], 8
	v_lshl_or_b32 v138, s20, 8, v155
	v_lshl_add_u64 v[140:141], s[22:23], 0, v[132:133]
	s_mov_b32 s13, s33
	v_ashrrev_i32_e32 v139, 31, v138
	v_lshlrev_b64 v[146:147], 11, v[140:141]
	v_lshl_add_u64 v[142:143], s[26:27], 0, v[146:147]
	v_lshlrev_b64 v[148:149], 1, v[138:139]
	s_mov_b32 s13, s33
	v_lshl_add_u64 v[142:143], v[142:143], 0, v[148:149]
	global_load_dwordx2 v[158:159], v[142:143], off
	global_load_dwordx2 v[160:161], v[142:143], off offset:32
	global_load_dwordx2 v[162:163], v[142:143], off offset:256
	global_load_dwordx2 v[164:165], v[142:143], off offset:288
	v_mov_b32_e32 v142, s13
	ds_read2_b32 v[166:167], v142 offset1:1
	v_lshl_add_u64 v[142:143], s[26:27], 0, v[148:149]
	v_lshl_add_u64 v[144:145], v[142:143], 0, v[146:147]
	v_add_co_u32_e32 v168, vcc, s54, v144
	v_lshl_add_u64 v[146:147], s[24:25], 0, v[146:147]
	s_nop 0
	v_addc_co_u32_e32 v169, vcc, 0, v145, vcc
	v_lshl_add_u64 v[170:171], v[146:147], 0, v[148:149]
	global_load_dwordx2 v[152:153], v[168:169], off
	global_load_dwordx2 v[150:151], v[168:169], off offset:32
	global_load_dwordx2 v[148:149], v[168:169], off offset:256
	global_load_dwordx2 v[146:147], v[168:169], off offset:288
	s_waitcnt lgkmcnt(0)
	v_readfirstlane_b32 s13, v166
	v_readfirstlane_b32 s15, v167
	s_lshl_b32 s20, s20, 2
	s_ashr_i32 s21, s20, 31
	s_lshl_b64 s[20:21], s[20:21], 2
	s_add_u32 s13, s13, s20
	s_addc_u32 s15, s15, s21
	s_add_u32 s13, s13, s48
	s_addc_u32 s15, s15, 0
	s_add_u32 s20, s13, 0x10380000
	s_addc_u32 s21, s15, 0
	s_waitcnt vmcnt(0)
	v_cvt_f32_f16_e32 v166, v158
	v_cvt_f32_f16_sdwa v167, v158 dst_sel:DWORD dst_unused:UNUSED_PAD src0_sel:WORD_1
	v_cvt_f32_f16_e32 v158, v159
	v_cvt_f32_f16_sdwa v159, v159 dst_sel:DWORD dst_unused:UNUSED_PAD src0_sel:WORD_1
	v_cvt_f32_f16_e32 v168, v160
	v_cvt_f32_f16_sdwa v169, v160 dst_sel:DWORD dst_unused:UNUSED_PAD src0_sel:WORD_1
	v_cvt_f32_f16_e32 v160, v161
	v_cvt_f32_f16_sdwa v161, v161 dst_sel:DWORD dst_unused:UNUSED_PAD src0_sel:WORD_1
	v_cvt_f32_f16_e32 v172, v162
	v_cvt_f32_f16_sdwa v173, v162 dst_sel:DWORD dst_unused:UNUSED_PAD src0_sel:WORD_1
	v_cvt_f32_f16_e32 v162, v163
	v_cvt_f32_f16_sdwa v163, v163 dst_sel:DWORD dst_unused:UNUSED_PAD src0_sel:WORD_1
	v_cvt_f32_f16_e32 v174, v164
	v_cvt_f32_f16_sdwa v175, v164 dst_sel:DWORD dst_unused:UNUSED_PAD src0_sel:WORD_1
	v_cvt_f32_f16_e32 v164, v165
	v_cvt_f32_f16_sdwa v165, v165 dst_sel:DWORD dst_unused:UNUSED_PAD src0_sel:WORD_1
	v_pk_add_f32 v[128:129], v[128:129], v[158:159]
	v_pk_add_f32 v[126:127], v[126:127], v[166:167]
	v_pk_add_f32 v[124:125], v[124:125], v[160:161]
	v_pk_add_f32 v[122:123], v[122:123], v[168:169]
	v_pk_add_f32 v[120:121], v[120:121], v[162:163]
	v_pk_add_f32 v[118:119], v[118:119], v[172:173]
	v_cvt_f16_f32_e32 v157, v126
	v_cvt_f16_f32_sdwa v158, v127 dst_sel:WORD_1 dst_unused:UNUSED_PAD src0_sel:DWORD
	v_cvt_f16_f32_e32 v159, v128
	v_cvt_f16_f32_sdwa v160, v129 dst_sel:WORD_1 dst_unused:UNUSED_PAD src0_sel:DWORD
	v_pk_add_f32 v[116:117], v[116:117], v[164:165]
	v_mul_f32_e32 v127, v127, v127
	v_mul_f32_e32 v129, v129, v129
	v_cvt_f16_f32_e32 v161, v122
	v_cvt_f16_f32_sdwa v162, v123 dst_sel:WORD_1 dst_unused:UNUSED_PAD src0_sel:DWORD
	v_cvt_f16_f32_e32 v163, v124
	v_cvt_f16_f32_sdwa v164, v125 dst_sel:WORD_1 dst_unused:UNUSED_PAD src0_sel:DWORD
	v_mul_f32_e32 v123, v123, v123
	v_mul_f32_e32 v125, v125, v125
	v_cvt_f16_f32_e32 v165, v118
	v_cvt_f16_f32_sdwa v166, v119 dst_sel:WORD_1 dst_unused:UNUSED_PAD src0_sel:DWORD
	v_cvt_f16_f32_e32 v167, v120
	v_cvt_f16_f32_sdwa v168, v121 dst_sel:WORD_1 dst_unused:UNUSED_PAD src0_sel:DWORD
	v_mul_f32_e32 v169, v119, v119
	v_fmac_f32_e32 v127, v126, v126
	v_fmac_f32_e32 v129, v128, v128
	v_fmac_f32_e32 v123, v122, v122
	v_fmac_f32_e32 v125, v124, v124
	v_fmac_f32_e32 v169, v118, v118
	v_add_f32_e32 v118, v127, v129
	v_add_f32_e32 v119, v123, v125
	v_pk_add_f32 v[114:115], v[114:115], v[174:175]
	v_mul_f32_e32 v172, v121, v121
	v_add_f32_e32 v124, v118, v119
	v_or_b32_e32 v118, v158, v157
	v_or_b32_e32 v119, v160, v159
	v_cvt_f16_f32_e32 v173, v114
	v_cvt_f16_f32_sdwa v174, v115 dst_sel:WORD_1 dst_unused:UNUSED_PAD src0_sel:DWORD
	v_cvt_f16_f32_e32 v175, v116
	v_fmac_f32_e32 v172, v120, v120
	v_or_b32_e32 v120, v162, v161
	v_or_b32_e32 v121, v164, v163
	v_or_b32_e32 v122, v166, v165
	v_or_b32_e32 v123, v168, v167
	global_store_dwordx2 v[170:171], v[118:119], off
	global_store_dwordx2 v[170:171], v[120:121], off offset:32
	global_store_dwordx2 v[170:171], v[122:123], off offset:256
	v_cvt_f16_f32_sdwa v119, v117 dst_sel:WORD_1 dst_unused:UNUSED_PAD src0_sel:DWORD
	v_mul_f32_e32 v115, v115, v115
	v_fmac_f32_e32 v115, v114, v114
	v_mul_f32_e32 v114, v117, v117
	v_add_f32_e32 v118, v169, v172
	v_fmac_f32_e32 v114, v116, v116
	v_add_f32_e32 v120, v124, v118
	v_or_b32_e32 v118, v174, v173
	v_or_b32_e32 v119, v119, v175
	v_add_f32_e32 v114, v115, v114
	global_store_dwordx2 v[170:171], v[118:119], off offset:288
	v_add_f32_e32 v114, v120, v114
	v_mov_b32_e32 v115, v114
	s_nop 1
	v_permlane16_swap_b32_e32 v115, v114
	s_waitcnt lgkmcnt(0)
	v_add_f32_e32 v114, v114, v115
	v_mov_b32_e32 v115, v1
	s_nop 0
	v_mbcnt_lo_u32_b32 v115, -1, v115
	v_mbcnt_hi_u32_b32 v115, -1, v115
	v_lshlrev_b32_e32 v115, 2, v115
	v_xor_b32_e32 v115, 0x80, v115
	ds_bpermute_b32 v115, v115, v114
	s_and_saveexec_b64 s[22:23], s[0:1]
	s_cbranch_execz .LBB0_1992
	v_lshlrev_b64 v[116:117], 6, v[140:141]
	v_lshl_add_u64 v[116:117], s[20:21], 0, v[116:117]
	s_waitcnt lgkmcnt(0)
	v_add_f32_e32 v114, v114, v115
	global_store_dword v[116:117], v114, off
.LBB0_1992:
	s_or_b64 exec, exec, s[22:23]
	v_cvt_f32_f16_sdwa v117, v152 dst_sel:DWORD dst_unused:UNUSED_PAD src0_sel:WORD_1
	v_cvt_f32_f16_e32 v116, v152
	v_cvt_f32_f16_sdwa v119, v153 dst_sel:DWORD dst_unused:UNUSED_PAD src0_sel:WORD_1
	v_cvt_f32_f16_e32 v118, v153
	s_mov_b32 s13, 0x10000
	v_cvt_f32_f16_sdwa v129, v146 dst_sel:DWORD dst_unused:UNUSED_PAD src0_sel:WORD_1
	v_cvt_f32_f16_e32 v128, v146
	v_add_co_u32_e32 v146, vcc, s13, v144
	v_cvt_f32_f16_sdwa v125, v148 dst_sel:DWORD dst_unused:UNUSED_PAD src0_sel:WORD_1
	v_cvt_f32_f16_e32 v124, v148
	v_cvt_f32_f16_sdwa v127, v149 dst_sel:DWORD dst_unused:UNUSED_PAD src0_sel:WORD_1
	v_cvt_f32_f16_e32 v126, v149
	v_cvt_f32_f16_sdwa v149, v147 dst_sel:DWORD dst_unused:UNUSED_PAD src0_sel:WORD_1
	v_cvt_f32_f16_e32 v148, v147
	v_addc_co_u32_e32 v147, vcc, 0, v145, vcc
	v_cvt_f32_f16_sdwa v121, v150 dst_sel:DWORD dst_unused:UNUSED_PAD src0_sel:WORD_1
	v_cvt_f32_f16_e32 v120, v150
	v_cvt_f32_f16_sdwa v123, v151 dst_sel:DWORD dst_unused:UNUSED_PAD src0_sel:WORD_1
	v_cvt_f32_f16_e32 v122, v151
	v_pk_add_f32 v[150:151], v[112:113], v[118:119]
	v_pk_add_f32 v[152:153], v[110:111], v[116:117]
	global_load_dwordx2 v[118:119], v[146:147], off
	global_load_dwordx2 v[116:117], v[146:147], off offset:32
	global_load_dwordx2 v[112:113], v[146:147], off offset:256
	global_load_dwordx2 v[110:111], v[146:147], off offset:288
	v_cvt_f16_f32_e32 v157, v152
	v_cvt_f16_f32_sdwa v158, v153 dst_sel:WORD_1 dst_unused:UNUSED_PAD src0_sel:DWORD
	v_cvt_f16_f32_e32 v159, v150
	v_cvt_f16_f32_sdwa v160, v151 dst_sel:WORD_1 dst_unused:UNUSED_PAD src0_sel:DWORD
	v_pk_add_f32 v[108:109], v[108:109], v[122:123]
	v_pk_add_f32 v[106:107], v[106:107], v[120:121]
	v_cvt_f16_f32_e32 v122, v108
	v_cvt_f16_f32_e32 v120, v106
	v_cvt_f16_f32_sdwa v121, v107 dst_sel:WORD_1 dst_unused:UNUSED_PAD src0_sel:DWORD
	v_cvt_f16_f32_sdwa v123, v109 dst_sel:WORD_1 dst_unused:UNUSED_PAD src0_sel:DWORD
	v_or_b32_e32 v114, 16, v140
	s_waitcnt lgkmcnt(0)
	v_mov_b32_e32 v115, v141
	v_or_b32_e32 v146, v158, v157
	v_or_b32_e32 v147, v160, v159
	v_lshlrev_b64 v[158:159], 11, v[114:115]
	v_lshl_add_u64 v[158:159], s[24:25], 0, v[158:159]
	v_mul_f32_e32 v107, v107, v107
	v_lshl_add_u64 v[158:159], v[138:139], 1, v[158:159]
	v_or_b32_e32 v120, v121, v120
	v_or_b32_e32 v121, v123, v122
	v_fmac_f32_e32 v107, v106, v106
	v_mul_f32_e32 v106, v109, v109
	v_pk_add_f32 v[104:105], v[104:105], v[126:127]
	v_pk_add_f32 v[102:103], v[102:103], v[124:125]
	global_store_dwordx2 v[158:159], v[120:121], off offset:32
	v_fmac_f32_e32 v106, v108, v108
	v_cvt_f16_f32_e32 v108, v102
	v_cvt_f16_f32_sdwa v109, v103 dst_sel:WORD_1 dst_unused:UNUSED_PAD src0_sel:DWORD
	v_cvt_f16_f32_e32 v120, v104
	v_cvt_f16_f32_sdwa v121, v105 dst_sel:WORD_1 dst_unused:UNUSED_PAD src0_sel:DWORD
	global_store_dwordx2 v[158:159], v[146:147], off
	v_mul_f32_e32 v146, v153, v153
	v_mul_f32_e32 v147, v151, v151
	v_fmac_f32_e32 v146, v152, v152
	v_fmac_f32_e32 v147, v150, v150
	v_add_f32_e32 v146, v146, v147
	v_add_f32_e32 v106, v107, v106
	v_mul_f32_e32 v103, v103, v103
	v_add_f32_e32 v122, v146, v106
	v_or_b32_e32 v106, v109, v108
	v_or_b32_e32 v107, v121, v120
	v_fmac_f32_e32 v103, v102, v102
	v_mul_f32_e32 v102, v105, v105
	v_pk_add_f32 v[100:101], v[100:101], v[148:149]
	v_pk_add_f32 v[98:99], v[98:99], v[128:129]
	global_store_dwordx2 v[158:159], v[106:107], off offset:256
	v_fmac_f32_e32 v102, v104, v104
	v_cvt_f16_f32_e32 v104, v98
	v_cvt_f16_f32_sdwa v105, v99 dst_sel:WORD_1 dst_unused:UNUSED_PAD src0_sel:DWORD
	v_cvt_f16_f32_e32 v106, v100
	v_cvt_f16_f32_sdwa v107, v101 dst_sel:WORD_1 dst_unused:UNUSED_PAD src0_sel:DWORD
	v_mul_f32_e32 v99, v99, v99
	v_fmac_f32_e32 v99, v98, v98
	v_mul_f32_e32 v98, v101, v101
	v_add_f32_e32 v102, v103, v102
	v_fmac_f32_e32 v98, v100, v100
	v_add_f32_e32 v108, v122, v102
	v_or_b32_e32 v102, v105, v104
	v_or_b32_e32 v103, v107, v106
	v_add_f32_e32 v98, v99, v98
	global_store_dwordx2 v[158:159], v[102:103], off offset:288
	v_add_f32_e32 v98, v108, v98
	v_mov_b32_e32 v99, v98
	s_nop 1
	v_permlane16_swap_b32_e32 v99, v98
	s_waitcnt lgkmcnt(0)
	v_add_f32_e32 v98, v98, v99
	v_mov_b32_e32 v99, v1
	s_nop 0
	v_mbcnt_lo_u32_b32 v99, -1, v99
	v_mbcnt_hi_u32_b32 v99, -1, v99
	v_lshlrev_b32_e32 v99, 2, v99
	v_xor_b32_e32 v99, 0x80, v99
	ds_bpermute_b32 v99, v99, v98
	s_and_saveexec_b64 s[22:23], s[0:1]
	s_movk_i32 s53, 0x5ff
	s_cbranch_execz .LBB0_1994
	v_lshlrev_b64 v[100:101], 6, v[114:115]
	v_lshl_add_u64 v[100:101], s[20:21], 0, v[100:101]
	s_waitcnt lgkmcnt(0)
	v_add_f32_e32 v98, v98, v99
	global_store_dword v[100:101], v98, off
.LBB0_1994:
	s_or_b64 exec, exec, s[22:23]
	s_waitcnt vmcnt(7)
	v_cvt_f32_f16_sdwa v101, v118 dst_sel:DWORD dst_unused:UNUSED_PAD src0_sel:WORD_1
	v_cvt_f32_f16_e32 v100, v118
	v_cvt_f32_f16_sdwa v103, v119 dst_sel:DWORD dst_unused:UNUSED_PAD src0_sel:WORD_1
	v_cvt_f32_f16_e32 v102, v119
	s_mov_b32 s13, 0x18000
	s_waitcnt vmcnt(5)
	v_cvt_f32_f16_sdwa v109, v112 dst_sel:DWORD dst_unused:UNUSED_PAD src0_sel:WORD_1
	v_cvt_f32_f16_e32 v108, v112
	v_cvt_f32_f16_sdwa v115, v113 dst_sel:DWORD dst_unused:UNUSED_PAD src0_sel:WORD_1
	v_cvt_f32_f16_e32 v114, v113
	s_waitcnt vmcnt(4)
	v_cvt_f32_f16_sdwa v113, v110 dst_sel:DWORD dst_unused:UNUSED_PAD src0_sel:WORD_1
	v_cvt_f32_f16_e32 v112, v110
	v_add_co_u32_e32 v110, vcc, s13, v144
	v_cvt_f32_f16_sdwa v105, v116 dst_sel:DWORD dst_unused:UNUSED_PAD src0_sel:WORD_1
	v_cvt_f32_f16_e32 v104, v116
	v_cvt_f32_f16_sdwa v107, v117 dst_sel:DWORD dst_unused:UNUSED_PAD src0_sel:WORD_1
	v_cvt_f32_f16_e32 v106, v117
	v_cvt_f32_f16_sdwa v117, v111 dst_sel:DWORD dst_unused:UNUSED_PAD src0_sel:WORD_1
	v_cvt_f32_f16_e32 v116, v111
	v_addc_co_u32_e32 v111, vcc, 0, v145, vcc
	v_pk_add_f32 v[118:119], v[96:97], v[102:103]
	v_pk_add_f32 v[120:121], v[94:95], v[100:101]
	global_load_dwordx2 v[102:103], v[110:111], off
	global_load_dwordx2 v[100:101], v[110:111], off offset:32
	global_load_dwordx2 v[96:97], v[110:111], off offset:256
	global_load_dwordx2 v[94:95], v[110:111], off offset:288
	v_cvt_f16_f32_e32 v122, v120
	v_cvt_f16_f32_sdwa v123, v121 dst_sel:WORD_1 dst_unused:UNUSED_PAD src0_sel:DWORD
	v_pk_add_f32 v[92:93], v[92:93], v[106:107]
	v_pk_add_f32 v[90:91], v[90:91], v[104:105]
	v_cvt_f16_f32_e32 v106, v92
	v_cvt_f16_f32_e32 v104, v90
	v_cvt_f16_f32_sdwa v105, v91 dst_sel:WORD_1 dst_unused:UNUSED_PAD src0_sel:DWORD
	v_cvt_f16_f32_sdwa v107, v93 dst_sel:WORD_1 dst_unused:UNUSED_PAD src0_sel:DWORD
	v_or_b32_e32 v98, 32, v140
	s_waitcnt lgkmcnt(0)
	v_mov_b32_e32 v99, v141
	v_cvt_f16_f32_e32 v124, v118
	v_cvt_f16_f32_sdwa v125, v119 dst_sel:WORD_1 dst_unused:UNUSED_PAD src0_sel:DWORD
	v_or_b32_e32 v110, v123, v122
	v_lshlrev_b64 v[122:123], 11, v[98:99]
	v_lshl_add_u64 v[122:123], s[24:25], 0, v[122:123]
	v_mul_f32_e32 v91, v91, v91
	v_lshl_add_u64 v[122:123], v[138:139], 1, v[122:123]
	v_or_b32_e32 v104, v105, v104
	v_or_b32_e32 v105, v107, v106
	v_fmac_f32_e32 v91, v90, v90
	v_mul_f32_e32 v90, v93, v93
	v_pk_add_f32 v[88:89], v[88:89], v[114:115]
	v_pk_add_f32 v[86:87], v[86:87], v[108:109]
	v_or_b32_e32 v111, v125, v124
	global_store_dwordx2 v[122:123], v[104:105], off offset:32
	v_fmac_f32_e32 v90, v92, v92
	v_cvt_f16_f32_e32 v92, v86
	v_cvt_f16_f32_sdwa v93, v87 dst_sel:WORD_1 dst_unused:UNUSED_PAD src0_sel:DWORD
	v_cvt_f16_f32_e32 v104, v88
	v_cvt_f16_f32_sdwa v105, v89 dst_sel:WORD_1 dst_unused:UNUSED_PAD src0_sel:DWORD
	global_store_dwordx2 v[122:123], v[110:111], off
	v_mul_f32_e32 v110, v121, v121
	v_mul_f32_e32 v111, v119, v119
	v_fmac_f32_e32 v110, v120, v120
	v_fmac_f32_e32 v111, v118, v118
	v_add_f32_e32 v110, v110, v111
	v_add_f32_e32 v90, v91, v90
	v_mul_f32_e32 v87, v87, v87
	v_add_f32_e32 v106, v110, v90
	v_or_b32_e32 v90, v93, v92
	v_or_b32_e32 v91, v105, v104
	v_fmac_f32_e32 v87, v86, v86
	v_mul_f32_e32 v86, v89, v89
	v_pk_add_f32 v[84:85], v[84:85], v[116:117]
	v_pk_add_f32 v[82:83], v[82:83], v[112:113]
	global_store_dwordx2 v[122:123], v[90:91], off offset:256
	v_fmac_f32_e32 v86, v88, v88
	v_cvt_f16_f32_e32 v88, v82
	v_cvt_f16_f32_sdwa v89, v83 dst_sel:WORD_1 dst_unused:UNUSED_PAD src0_sel:DWORD
	v_cvt_f16_f32_e32 v90, v84
	v_cvt_f16_f32_sdwa v91, v85 dst_sel:WORD_1 dst_unused:UNUSED_PAD src0_sel:DWORD
	v_mul_f32_e32 v83, v83, v83
	v_fmac_f32_e32 v83, v82, v82
	v_mul_f32_e32 v82, v85, v85
	v_add_f32_e32 v86, v87, v86
	v_fmac_f32_e32 v82, v84, v84
	v_add_f32_e32 v92, v106, v86
	v_or_b32_e32 v86, v89, v88
	v_or_b32_e32 v87, v91, v90
	v_add_f32_e32 v82, v83, v82
	global_store_dwordx2 v[122:123], v[86:87], off offset:288
	v_add_f32_e32 v82, v92, v82
	v_mov_b32_e32 v83, v82
	s_nop 1
	v_permlane16_swap_b32_e32 v83, v82
	s_waitcnt lgkmcnt(0)
	v_add_f32_e32 v82, v82, v83
	v_mov_b32_e32 v83, v1
	s_nop 0
	v_mbcnt_lo_u32_b32 v83, -1, v83
	v_mbcnt_hi_u32_b32 v83, -1, v83
	v_lshlrev_b32_e32 v83, 2, v83
	v_xor_b32_e32 v83, 0x80, v83
	ds_bpermute_b32 v83, v83, v82
	s_and_saveexec_b64 s[22:23], s[0:1]
	s_cbranch_execz .LBB0_1996
	v_lshlrev_b64 v[84:85], 6, v[98:99]
	v_lshl_add_u64 v[84:85], s[20:21], 0, v[84:85]
	s_waitcnt lgkmcnt(0)
	v_add_f32_e32 v82, v82, v83
	global_store_dword v[84:85], v82, off
.LBB0_1996:
	s_or_b64 exec, exec, s[22:23]
	s_waitcnt vmcnt(7)
	v_cvt_f32_f16_sdwa v85, v102 dst_sel:DWORD dst_unused:UNUSED_PAD src0_sel:WORD_1
	v_cvt_f32_f16_e32 v84, v102
	v_cvt_f32_f16_sdwa v87, v103 dst_sel:DWORD dst_unused:UNUSED_PAD src0_sel:WORD_1
	v_cvt_f32_f16_e32 v86, v103
	s_mov_b32 s13, 0x40000
	s_waitcnt vmcnt(5)
	v_cvt_f32_f16_sdwa v93, v96 dst_sel:DWORD dst_unused:UNUSED_PAD src0_sel:WORD_1
	v_cvt_f32_f16_e32 v92, v96
	v_cvt_f32_f16_sdwa v99, v97 dst_sel:DWORD dst_unused:UNUSED_PAD src0_sel:WORD_1
	v_cvt_f32_f16_e32 v98, v97
	s_waitcnt vmcnt(4)
	v_cvt_f32_f16_sdwa v97, v94 dst_sel:DWORD dst_unused:UNUSED_PAD src0_sel:WORD_1
	v_cvt_f32_f16_e32 v96, v94
	v_add_co_u32_e32 v94, vcc, s13, v144
	v_cvt_f32_f16_sdwa v89, v100 dst_sel:DWORD dst_unused:UNUSED_PAD src0_sel:WORD_1
	v_cvt_f32_f16_e32 v88, v100
	v_cvt_f32_f16_sdwa v91, v101 dst_sel:DWORD dst_unused:UNUSED_PAD src0_sel:WORD_1
	v_cvt_f32_f16_e32 v90, v101
	v_cvt_f32_f16_sdwa v101, v95 dst_sel:DWORD dst_unused:UNUSED_PAD src0_sel:WORD_1
	v_cvt_f32_f16_e32 v100, v95
	v_addc_co_u32_e32 v95, vcc, 0, v145, vcc
	v_pk_add_f32 v[102:103], v[80:81], v[86:87]
	v_pk_add_f32 v[104:105], v[78:79], v[84:85]
	global_load_dwordx2 v[86:87], v[94:95], off
	global_load_dwordx2 v[84:85], v[94:95], off offset:32
	global_load_dwordx2 v[80:81], v[94:95], off offset:256
	global_load_dwordx2 v[78:79], v[94:95], off offset:288
	v_cvt_f16_f32_e32 v106, v104
	v_cvt_f16_f32_sdwa v107, v105 dst_sel:WORD_1 dst_unused:UNUSED_PAD src0_sel:DWORD
	v_pk_add_f32 v[76:77], v[76:77], v[90:91]
	v_pk_add_f32 v[74:75], v[74:75], v[88:89]
	v_cvt_f16_f32_e32 v90, v76
	v_cvt_f16_f32_e32 v88, v74
	v_cvt_f16_f32_sdwa v89, v75 dst_sel:WORD_1 dst_unused:UNUSED_PAD src0_sel:DWORD
	v_cvt_f16_f32_sdwa v91, v77 dst_sel:WORD_1 dst_unused:UNUSED_PAD src0_sel:DWORD
	v_or_b32_e32 v82, 48, v140
	s_waitcnt lgkmcnt(0)
	v_mov_b32_e32 v83, v141
	v_cvt_f16_f32_e32 v108, v102
	v_cvt_f16_f32_sdwa v109, v103 dst_sel:WORD_1 dst_unused:UNUSED_PAD src0_sel:DWORD
	v_or_b32_e32 v94, v107, v106
	v_lshlrev_b64 v[106:107], 11, v[82:83]
	v_lshl_add_u64 v[106:107], s[24:25], 0, v[106:107]
	v_mul_f32_e32 v75, v75, v75
	v_lshl_add_u64 v[106:107], v[138:139], 1, v[106:107]
	v_or_b32_e32 v88, v89, v88
	v_or_b32_e32 v89, v91, v90
	v_fmac_f32_e32 v75, v74, v74
	v_mul_f32_e32 v74, v77, v77
	v_pk_add_f32 v[72:73], v[72:73], v[98:99]
	v_pk_add_f32 v[70:71], v[70:71], v[92:93]
	v_or_b32_e32 v95, v109, v108
	global_store_dwordx2 v[106:107], v[88:89], off offset:32
	v_fmac_f32_e32 v74, v76, v76
	v_cvt_f16_f32_e32 v76, v70
	v_cvt_f16_f32_sdwa v77, v71 dst_sel:WORD_1 dst_unused:UNUSED_PAD src0_sel:DWORD
	v_cvt_f16_f32_e32 v88, v72
	v_cvt_f16_f32_sdwa v89, v73 dst_sel:WORD_1 dst_unused:UNUSED_PAD src0_sel:DWORD
	global_store_dwordx2 v[106:107], v[94:95], off
	v_mul_f32_e32 v94, v105, v105
	v_mul_f32_e32 v95, v103, v103
	v_fmac_f32_e32 v94, v104, v104
	v_fmac_f32_e32 v95, v102, v102
	v_add_f32_e32 v94, v94, v95
	v_add_f32_e32 v74, v75, v74
	v_mul_f32_e32 v71, v71, v71
	v_add_f32_e32 v90, v94, v74
	v_or_b32_e32 v74, v77, v76
	v_or_b32_e32 v75, v89, v88
	v_fmac_f32_e32 v71, v70, v70
	v_mul_f32_e32 v70, v73, v73
	v_pk_add_f32 v[68:69], v[68:69], v[100:101]
	v_pk_add_f32 v[66:67], v[66:67], v[96:97]
	global_store_dwordx2 v[106:107], v[74:75], off offset:256
	v_fmac_f32_e32 v70, v72, v72
	v_cvt_f16_f32_e32 v72, v66
	v_cvt_f16_f32_sdwa v73, v67 dst_sel:WORD_1 dst_unused:UNUSED_PAD src0_sel:DWORD
	v_cvt_f16_f32_e32 v74, v68
	v_cvt_f16_f32_sdwa v75, v69 dst_sel:WORD_1 dst_unused:UNUSED_PAD src0_sel:DWORD
	v_mul_f32_e32 v67, v67, v67
	v_fmac_f32_e32 v67, v66, v66
	v_mul_f32_e32 v66, v69, v69
	v_add_f32_e32 v70, v71, v70
	v_fmac_f32_e32 v66, v68, v68
	v_add_f32_e32 v76, v90, v70
	v_or_b32_e32 v70, v73, v72
	v_or_b32_e32 v71, v75, v74
	v_add_f32_e32 v66, v67, v66
	global_store_dwordx2 v[106:107], v[70:71], off offset:288
	v_add_f32_e32 v66, v76, v66
	v_mov_b32_e32 v67, v66
	s_nop 1
	v_permlane16_swap_b32_e32 v67, v66
	s_waitcnt lgkmcnt(0)
	v_add_f32_e32 v66, v66, v67
	v_mov_b32_e32 v67, v1
	s_nop 0
	v_mbcnt_lo_u32_b32 v67, -1, v67
	v_mbcnt_hi_u32_b32 v67, -1, v67
	v_lshlrev_b32_e32 v67, 2, v67
	v_xor_b32_e32 v67, 0x80, v67
	ds_bpermute_b32 v67, v67, v66
	s_and_saveexec_b64 s[22:23], s[0:1]
	s_cbranch_execz .LBB0_1998
	v_lshlrev_b64 v[68:69], 6, v[82:83]
	v_lshl_add_u64 v[68:69], s[20:21], 0, v[68:69]
	s_waitcnt lgkmcnt(0)
	v_add_f32_e32 v66, v66, v67
	global_store_dword v[68:69], v66, off
.LBB0_1998:
	s_or_b64 exec, exec, s[22:23]
	s_waitcnt vmcnt(7)
	v_cvt_f32_f16_sdwa v71, v86 dst_sel:DWORD dst_unused:UNUSED_PAD src0_sel:WORD_1
	v_cvt_f32_f16_e32 v70, v86
	v_cvt_f32_f16_sdwa v73, v87 dst_sel:DWORD dst_unused:UNUSED_PAD src0_sel:WORD_1
	v_cvt_f32_f16_e32 v72, v87
	v_lshl_add_u64 v[68:69], v[140:141], 0, s[96:97]
	s_waitcnt lgkmcnt(0)
	v_lshlrev_b64 v[66:67], 11, v[68:69]
	v_or_b32_e32 v88, 0x8000, v66
	v_mov_b32_e32 v89, v67
	v_lshl_add_u64 v[88:89], v[142:143], 0, v[88:89]
	v_pk_add_f32 v[90:91], v[64:65], v[72:73]
	v_pk_add_f32 v[92:93], v[62:63], v[70:71]
	global_load_dwordx2 v[72:73], v[88:89], off
	global_load_dwordx2 v[70:71], v[88:89], off offset:32
	global_load_dwordx2 v[64:65], v[88:89], off offset:256
	global_load_dwordx2 v[62:63], v[88:89], off offset:288
	s_waitcnt vmcnt(10)
	v_cvt_f32_f16_sdwa v75, v84 dst_sel:DWORD dst_unused:UNUSED_PAD src0_sel:WORD_1
	v_cvt_f32_f16_e32 v74, v84
	v_cvt_f32_f16_sdwa v77, v85 dst_sel:DWORD dst_unused:UNUSED_PAD src0_sel:WORD_1
	v_cvt_f32_f16_e32 v76, v85
	s_waitcnt vmcnt(9)
	v_cvt_f32_f16_sdwa v83, v80 dst_sel:DWORD dst_unused:UNUSED_PAD src0_sel:WORD_1
	v_pk_add_f32 v[58:59], v[58:59], v[74:75]
	v_cvt_f32_f16_e32 v82, v80
	v_pk_add_f32 v[60:61], v[60:61], v[76:77]
	v_cvt_f32_f16_sdwa v85, v81 dst_sel:DWORD dst_unused:UNUSED_PAD src0_sel:WORD_1
	v_cvt_f32_f16_e32 v84, v81
	v_cvt_f16_f32_e32 v74, v58
	v_cvt_f16_f32_sdwa v75, v59 dst_sel:WORD_1 dst_unused:UNUSED_PAD src0_sel:DWORD
	v_cvt_f16_f32_e32 v76, v60
	v_cvt_f16_f32_sdwa v77, v61 dst_sel:WORD_1 dst_unused:UNUSED_PAD src0_sel:DWORD
	s_waitcnt vmcnt(8)
	v_cvt_f32_f16_sdwa v81, v78 dst_sel:DWORD dst_unused:UNUSED_PAD src0_sel:WORD_1
	v_cvt_f32_f16_e32 v80, v78
	v_cvt_f16_f32_e32 v78, v92
	v_cvt_f16_f32_sdwa v94, v93 dst_sel:WORD_1 dst_unused:UNUSED_PAD src0_sel:DWORD
	v_cvt_f16_f32_e32 v95, v90
	v_cvt_f16_f32_sdwa v96, v91 dst_sel:WORD_1 dst_unused:UNUSED_PAD src0_sel:DWORD
	v_lshl_add_u64 v[88:89], s[24:25], 0, v[66:67]
	v_mul_f32_e32 v59, v59, v59
	v_lshl_add_u64 v[88:89], v[138:139], 1, v[88:89]
	v_or_b32_e32 v74, v75, v74
	v_or_b32_e32 v75, v77, v76
	v_fmac_f32_e32 v59, v58, v58
	v_mul_f32_e32 v58, v61, v61
	v_pk_add_f32 v[56:57], v[56:57], v[84:85]
	v_pk_add_f32 v[54:55], v[54:55], v[82:83]
	v_cvt_f32_f16_sdwa v87, v79 dst_sel:DWORD dst_unused:UNUSED_PAD src0_sel:WORD_1
	v_cvt_f32_f16_e32 v86, v79
	v_or_b32_e32 v78, v94, v78
	v_or_b32_e32 v79, v96, v95
	global_store_dwordx2 v[88:89], v[74:75], off offset:32
	v_fmac_f32_e32 v58, v60, v60
	v_cvt_f16_f32_e32 v60, v54
	v_cvt_f16_f32_sdwa v61, v55 dst_sel:WORD_1 dst_unused:UNUSED_PAD src0_sel:DWORD
	v_cvt_f16_f32_e32 v74, v56
	v_cvt_f16_f32_sdwa v75, v57 dst_sel:WORD_1 dst_unused:UNUSED_PAD src0_sel:DWORD
	global_store_dwordx2 v[88:89], v[78:79], off
	v_mul_f32_e32 v78, v93, v93
	v_mul_f32_e32 v79, v91, v91
	v_fmac_f32_e32 v78, v92, v92
	v_fmac_f32_e32 v79, v90, v90
	v_add_f32_e32 v78, v78, v79
	v_add_f32_e32 v58, v59, v58
	v_mul_f32_e32 v55, v55, v55
	v_add_f32_e32 v76, v78, v58
	v_or_b32_e32 v58, v61, v60
	v_or_b32_e32 v59, v75, v74
	v_fmac_f32_e32 v55, v54, v54
	v_mul_f32_e32 v54, v57, v57
	v_pk_add_f32 v[52:53], v[52:53], v[86:87]
	v_pk_add_f32 v[50:51], v[50:51], v[80:81]
	global_store_dwordx2 v[88:89], v[58:59], off offset:256
	v_fmac_f32_e32 v54, v56, v56
	v_cvt_f16_f32_e32 v56, v50
	v_cvt_f16_f32_sdwa v57, v51 dst_sel:WORD_1 dst_unused:UNUSED_PAD src0_sel:DWORD
	v_cvt_f16_f32_e32 v58, v52
	v_cvt_f16_f32_sdwa v59, v53 dst_sel:WORD_1 dst_unused:UNUSED_PAD src0_sel:DWORD
	v_mul_f32_e32 v51, v51, v51
	v_fmac_f32_e32 v51, v50, v50
	v_mul_f32_e32 v50, v53, v53
	v_add_f32_e32 v54, v55, v54
	v_fmac_f32_e32 v50, v52, v52
	v_add_f32_e32 v60, v76, v54
	v_or_b32_e32 v54, v57, v56
	v_or_b32_e32 v55, v59, v58
	v_add_f32_e32 v50, v51, v50
	global_store_dwordx2 v[88:89], v[54:55], off offset:288
	v_add_f32_e32 v50, v60, v50
	v_mov_b32_e32 v51, v50
	s_nop 1
	v_permlane16_swap_b32_e32 v51, v50
	s_waitcnt lgkmcnt(0)
	v_add_f32_e32 v50, v50, v51
	v_mov_b32_e32 v51, v1
	s_nop 0
	v_mbcnt_lo_u32_b32 v51, -1, v51
	v_mbcnt_hi_u32_b32 v51, -1, v51
	v_lshlrev_b32_e32 v51, 2, v51
	v_xor_b32_e32 v51, 0x80, v51
	ds_bpermute_b32 v51, v51, v50
	s_and_saveexec_b64 s[22:23], s[0:1]
	s_cbranch_execz .LBB0_2000
	v_lshlrev_b64 v[52:53], 6, v[68:69]
	v_lshl_add_u64 v[52:53], s[20:21], 0, v[52:53]
	s_waitcnt lgkmcnt(0)
	v_add_f32_e32 v50, v50, v51
	global_store_dword v[52:53], v50, off
.LBB0_2000:
	s_or_b64 exec, exec, s[22:23]
	s_waitcnt vmcnt(7)
	v_cvt_f32_f16_sdwa v53, v72 dst_sel:DWORD dst_unused:UNUSED_PAD src0_sel:WORD_1
	v_cvt_f32_f16_e32 v52, v72
	v_cvt_f32_f16_sdwa v55, v73 dst_sel:DWORD dst_unused:UNUSED_PAD src0_sel:WORD_1
	v_cvt_f32_f16_e32 v54, v73
	s_waitcnt vmcnt(6)
	v_cvt_f32_f16_sdwa v57, v70 dst_sel:DWORD dst_unused:UNUSED_PAD src0_sel:WORD_1
	v_cvt_f32_f16_e32 v56, v70
	v_cvt_f32_f16_sdwa v59, v71 dst_sel:DWORD dst_unused:UNUSED_PAD src0_sel:WORD_1
	v_cvt_f32_f16_e32 v58, v71
	s_waitcnt vmcnt(5)
	v_cvt_f32_f16_sdwa v61, v64 dst_sel:DWORD dst_unused:UNUSED_PAD src0_sel:WORD_1
	v_cvt_f32_f16_e32 v60, v64
	v_cvt_f32_f16_sdwa v69, v65 dst_sel:DWORD dst_unused:UNUSED_PAD src0_sel:WORD_1
	v_cvt_f32_f16_e32 v68, v65
	s_waitcnt vmcnt(4)
	v_cvt_f32_f16_sdwa v65, v62 dst_sel:DWORD dst_unused:UNUSED_PAD src0_sel:WORD_1
	v_cvt_f32_f16_e32 v64, v62
	v_cvt_f32_f16_sdwa v71, v63 dst_sel:DWORD dst_unused:UNUSED_PAD src0_sel:WORD_1
	v_cvt_f32_f16_e32 v70, v63
	v_or_b32_e32 v62, 0x10000, v66
	v_mov_b32_e32 v63, v67
	v_lshl_add_u64 v[62:63], v[142:143], 0, v[62:63]
	v_pk_add_f32 v[72:73], v[48:49], v[54:55]
	v_pk_add_f32 v[74:75], v[46:47], v[52:53]
	global_load_dwordx2 v[54:55], v[62:63], off
	global_load_dwordx2 v[52:53], v[62:63], off offset:32
	global_load_dwordx2 v[48:49], v[62:63], off offset:256
	global_load_dwordx2 v[46:47], v[62:63], off offset:288
	v_cvt_f16_f32_e32 v76, v74
	v_cvt_f16_f32_sdwa v77, v75 dst_sel:WORD_1 dst_unused:UNUSED_PAD src0_sel:DWORD
	v_pk_add_f32 v[44:45], v[44:45], v[58:59]
	v_pk_add_f32 v[42:43], v[42:43], v[56:57]
	s_mov_b64 s[22:23], 0x90
	v_cvt_f16_f32_e32 v56, v42
	v_cvt_f16_f32_sdwa v57, v43 dst_sel:WORD_1 dst_unused:UNUSED_PAD src0_sel:DWORD
	v_cvt_f16_f32_e32 v58, v44
	v_cvt_f16_f32_sdwa v59, v45 dst_sel:WORD_1 dst_unused:UNUSED_PAD src0_sel:DWORD
	s_waitcnt lgkmcnt(0)
	v_lshl_add_u64 v[50:51], v[140:141], 0, s[22:23]
	v_cvt_f16_f32_e32 v78, v72
	v_cvt_f16_f32_sdwa v79, v73 dst_sel:WORD_1 dst_unused:UNUSED_PAD src0_sel:DWORD
	v_or_b32_e32 v62, v77, v76
	v_lshlrev_b64 v[76:77], 11, v[50:51]
	v_lshl_add_u64 v[76:77], s[24:25], 0, v[76:77]
	v_mul_f32_e32 v43, v43, v43
	v_lshl_add_u64 v[76:77], v[138:139], 1, v[76:77]
	v_or_b32_e32 v56, v57, v56
	v_or_b32_e32 v57, v59, v58
	v_fmac_f32_e32 v43, v42, v42
	v_mul_f32_e32 v42, v45, v45
	v_pk_add_f32 v[40:41], v[40:41], v[68:69]
	v_pk_add_f32 v[38:39], v[38:39], v[60:61]
	v_or_b32_e32 v63, v79, v78
	global_store_dwordx2 v[76:77], v[56:57], off offset:32
	v_fmac_f32_e32 v42, v44, v44
	v_cvt_f16_f32_e32 v44, v38
	v_cvt_f16_f32_sdwa v45, v39 dst_sel:WORD_1 dst_unused:UNUSED_PAD src0_sel:DWORD
	v_cvt_f16_f32_e32 v56, v40
	v_cvt_f16_f32_sdwa v57, v41 dst_sel:WORD_1 dst_unused:UNUSED_PAD src0_sel:DWORD
	global_store_dwordx2 v[76:77], v[62:63], off
	v_mul_f32_e32 v62, v75, v75
	v_mul_f32_e32 v63, v73, v73
	v_fmac_f32_e32 v62, v74, v74
	v_fmac_f32_e32 v63, v72, v72
	v_add_f32_e32 v62, v62, v63
	v_add_f32_e32 v42, v43, v42
	v_mul_f32_e32 v39, v39, v39
	v_add_f32_e32 v58, v62, v42
	v_or_b32_e32 v42, v45, v44
	v_or_b32_e32 v43, v57, v56
	v_fmac_f32_e32 v39, v38, v38
	v_mul_f32_e32 v38, v41, v41
	v_pk_add_f32 v[36:37], v[36:37], v[70:71]
	v_pk_add_f32 v[34:35], v[34:35], v[64:65]
	global_store_dwordx2 v[76:77], v[42:43], off offset:256
	v_fmac_f32_e32 v38, v40, v40
	v_cvt_f16_f32_e32 v40, v34
	v_cvt_f16_f32_sdwa v41, v35 dst_sel:WORD_1 dst_unused:UNUSED_PAD src0_sel:DWORD
	v_cvt_f16_f32_e32 v42, v36
	v_cvt_f16_f32_sdwa v43, v37 dst_sel:WORD_1 dst_unused:UNUSED_PAD src0_sel:DWORD
	v_mul_f32_e32 v35, v35, v35
	v_fmac_f32_e32 v35, v34, v34
	v_mul_f32_e32 v34, v37, v37
	v_add_f32_e32 v38, v39, v38
	v_fmac_f32_e32 v34, v36, v36
	v_add_f32_e32 v44, v58, v38
	v_or_b32_e32 v38, v41, v40
	v_or_b32_e32 v39, v43, v42
	v_add_f32_e32 v34, v35, v34
	global_store_dwordx2 v[76:77], v[38:39], off offset:288
	v_add_f32_e32 v34, v44, v34
	v_mov_b32_e32 v35, v34
	s_nop 1
	v_permlane16_swap_b32_e32 v35, v34
	s_waitcnt lgkmcnt(0)
	v_add_f32_e32 v34, v34, v35
	v_mov_b32_e32 v35, v1
	s_nop 0
	v_mbcnt_lo_u32_b32 v35, -1, v35
	v_mbcnt_hi_u32_b32 v35, -1, v35
	v_lshlrev_b32_e32 v35, 2, v35
	v_xor_b32_e32 v35, 0x80, v35
	ds_bpermute_b32 v35, v35, v34
	s_and_saveexec_b64 s[22:23], s[0:1]
	s_cbranch_execz .LBB0_2002
	v_lshlrev_b64 v[36:37], 6, v[50:51]
	v_lshl_add_u64 v[36:37], s[20:21], 0, v[36:37]
	s_waitcnt lgkmcnt(0)
	v_add_f32_e32 v34, v34, v35
	global_store_dword v[36:37], v34, off
.LBB0_2002:
	s_or_b64 exec, exec, s[22:23]
	s_waitcnt vmcnt(7)
	v_cvt_f32_f16_sdwa v37, v54 dst_sel:DWORD dst_unused:UNUSED_PAD src0_sel:WORD_1
	v_cvt_f32_f16_e32 v36, v54
	v_cvt_f32_f16_sdwa v39, v55 dst_sel:DWORD dst_unused:UNUSED_PAD src0_sel:WORD_1
	v_cvt_f32_f16_e32 v38, v55
	v_or_b32_e32 v66, 0x18000, v66
	s_waitcnt vmcnt(6)
	v_cvt_f32_f16_sdwa v41, v52 dst_sel:DWORD dst_unused:UNUSED_PAD src0_sel:WORD_1
	v_cvt_f32_f16_e32 v40, v52
	v_cvt_f32_f16_sdwa v43, v53 dst_sel:DWORD dst_unused:UNUSED_PAD src0_sel:WORD_1
	v_cvt_f32_f16_e32 v42, v53
	s_waitcnt vmcnt(5)
	v_cvt_f32_f16_sdwa v45, v48 dst_sel:DWORD dst_unused:UNUSED_PAD src0_sel:WORD_1
	v_cvt_f32_f16_e32 v44, v48
	v_cvt_f32_f16_sdwa v51, v49 dst_sel:DWORD dst_unused:UNUSED_PAD src0_sel:WORD_1
	v_cvt_f32_f16_e32 v50, v49
	s_waitcnt vmcnt(4)
	v_cvt_f32_f16_sdwa v49, v46 dst_sel:DWORD dst_unused:UNUSED_PAD src0_sel:WORD_1
	v_cvt_f32_f16_e32 v48, v46
	v_cvt_f32_f16_sdwa v53, v47 dst_sel:DWORD dst_unused:UNUSED_PAD src0_sel:WORD_1
	v_cvt_f32_f16_e32 v52, v47
	v_lshl_add_u64 v[46:47], v[142:143], 0, v[66:67]
	v_pk_add_f32 v[54:55], v[32:33], v[38:39]
	v_pk_add_f32 v[56:57], v[30:31], v[36:37]
	global_load_dwordx2 v[38:39], v[46:47], off
	global_load_dwordx2 v[36:37], v[46:47], off offset:32
	global_load_dwordx2 v[32:33], v[46:47], off offset:256
	global_load_dwordx2 v[30:31], v[46:47], off offset:288
	v_cvt_f16_f32_e32 v58, v56
	v_cvt_f16_f32_sdwa v59, v57 dst_sel:WORD_1 dst_unused:UNUSED_PAD src0_sel:DWORD
	v_pk_add_f32 v[28:29], v[28:29], v[42:43]
	v_pk_add_f32 v[26:27], v[26:27], v[40:41]
	s_mov_b64 s[22:23], 0xa0
	v_cvt_f16_f32_e32 v40, v26
	v_cvt_f16_f32_sdwa v41, v27 dst_sel:WORD_1 dst_unused:UNUSED_PAD src0_sel:DWORD
	v_cvt_f16_f32_e32 v42, v28
	v_cvt_f16_f32_sdwa v43, v29 dst_sel:WORD_1 dst_unused:UNUSED_PAD src0_sel:DWORD
	s_waitcnt lgkmcnt(0)
	v_lshl_add_u64 v[34:35], v[140:141], 0, s[22:23]
	v_cvt_f16_f32_e32 v60, v54
	v_cvt_f16_f32_sdwa v61, v55 dst_sel:WORD_1 dst_unused:UNUSED_PAD src0_sel:DWORD
	v_or_b32_e32 v46, v59, v58
	v_lshlrev_b64 v[58:59], 11, v[34:35]
	v_lshl_add_u64 v[58:59], s[24:25], 0, v[58:59]
	v_mul_f32_e32 v27, v27, v27
	v_lshl_add_u64 v[58:59], v[138:139], 1, v[58:59]
	v_or_b32_e32 v40, v41, v40
	v_or_b32_e32 v41, v43, v42
	v_fmac_f32_e32 v27, v26, v26
	v_mul_f32_e32 v26, v29, v29
	v_pk_add_f32 v[24:25], v[24:25], v[50:51]
	v_pk_add_f32 v[22:23], v[22:23], v[44:45]
	v_or_b32_e32 v47, v61, v60
	global_store_dwordx2 v[58:59], v[40:41], off offset:32
	v_fmac_f32_e32 v26, v28, v28
	v_cvt_f16_f32_e32 v28, v22
	v_cvt_f16_f32_sdwa v29, v23 dst_sel:WORD_1 dst_unused:UNUSED_PAD src0_sel:DWORD
	v_cvt_f16_f32_e32 v40, v24
	v_cvt_f16_f32_sdwa v41, v25 dst_sel:WORD_1 dst_unused:UNUSED_PAD src0_sel:DWORD
	global_store_dwordx2 v[58:59], v[46:47], off
	v_mul_f32_e32 v46, v57, v57
	v_mul_f32_e32 v47, v55, v55
	v_fmac_f32_e32 v46, v56, v56
	v_fmac_f32_e32 v47, v54, v54
	v_add_f32_e32 v46, v46, v47
	v_add_f32_e32 v26, v27, v26
	v_mul_f32_e32 v23, v23, v23
	v_add_f32_e32 v42, v46, v26
	v_or_b32_e32 v26, v29, v28
	v_or_b32_e32 v27, v41, v40
	v_fmac_f32_e32 v23, v22, v22
	v_mul_f32_e32 v22, v25, v25
	v_pk_add_f32 v[20:21], v[20:21], v[52:53]
	v_pk_add_f32 v[18:19], v[18:19], v[48:49]
	global_store_dwordx2 v[58:59], v[26:27], off offset:256
	v_fmac_f32_e32 v22, v24, v24
	v_cvt_f16_f32_e32 v24, v18
	v_cvt_f16_f32_sdwa v25, v19 dst_sel:WORD_1 dst_unused:UNUSED_PAD src0_sel:DWORD
	v_cvt_f16_f32_e32 v26, v20
	v_cvt_f16_f32_sdwa v27, v21 dst_sel:WORD_1 dst_unused:UNUSED_PAD src0_sel:DWORD
	v_mul_f32_e32 v19, v19, v19
	v_fmac_f32_e32 v19, v18, v18
	v_mul_f32_e32 v18, v21, v21
	v_add_f32_e32 v22, v23, v22
	v_fmac_f32_e32 v18, v20, v20
	v_add_f32_e32 v28, v42, v22
	v_or_b32_e32 v22, v25, v24
	v_or_b32_e32 v23, v27, v26
	v_add_f32_e32 v18, v19, v18
	global_store_dwordx2 v[58:59], v[22:23], off offset:288
	v_add_f32_e32 v18, v28, v18
	v_mov_b32_e32 v19, v18
	s_nop 1
	v_permlane16_swap_b32_e32 v19, v18
	s_waitcnt lgkmcnt(0)
	v_add_f32_e32 v18, v18, v19
	v_mov_b32_e32 v19, v1
	s_nop 0
	v_mbcnt_lo_u32_b32 v19, -1, v19
	v_mbcnt_hi_u32_b32 v19, -1, v19
	v_lshlrev_b32_e32 v19, 2, v19
	v_xor_b32_e32 v19, 0x80, v19
	ds_bpermute_b32 v19, v19, v18
	s_and_saveexec_b64 s[22:23], s[0:1]
	s_cbranch_execz .LBB0_2004
	v_lshlrev_b64 v[20:21], 6, v[34:35]
	v_lshl_add_u64 v[20:21], s[20:21], 0, v[20:21]
	s_waitcnt lgkmcnt(0)
	v_add_f32_e32 v18, v18, v19
	global_store_dword v[20:21], v18, off
.LBB0_2004:
	s_or_b64 exec, exec, s[22:23]
	s_waitcnt vmcnt(7)
	v_cvt_f32_f16_sdwa v21, v38 dst_sel:DWORD dst_unused:UNUSED_PAD src0_sel:WORD_1
	v_cvt_f32_f16_e32 v20, v38
	v_cvt_f32_f16_sdwa v23, v39 dst_sel:DWORD dst_unused:UNUSED_PAD src0_sel:WORD_1
	v_cvt_f32_f16_e32 v22, v39
	s_waitcnt vmcnt(6)
	v_cvt_f32_f16_sdwa v25, v36 dst_sel:DWORD dst_unused:UNUSED_PAD src0_sel:WORD_1
	v_cvt_f32_f16_e32 v24, v36
	v_pk_add_f32 v[14:15], v[14:15], v[20:21]
	v_cvt_f32_f16_sdwa v27, v37 dst_sel:DWORD dst_unused:UNUSED_PAD src0_sel:WORD_1
	v_cvt_f32_f16_e32 v26, v37
	v_cvt_f16_f32_e32 v20, v14
	v_cvt_f16_f32_sdwa v21, v15 dst_sel:WORD_1 dst_unused:UNUSED_PAD src0_sel:DWORD
	v_pk_add_f32 v[16:17], v[16:17], v[22:23]
	v_mul_f32_e32 v15, v15, v15
	v_fmac_f32_e32 v15, v14, v14
	v_mul_f32_e32 v14, v17, v17
	s_waitcnt vmcnt(5)
	v_cvt_f32_f16_sdwa v29, v32 dst_sel:DWORD dst_unused:UNUSED_PAD src0_sel:WORD_1
	v_cvt_f32_f16_e32 v28, v32
	v_fmac_f32_e32 v14, v16, v16
	v_pk_add_f32 v[10:11], v[10:11], v[24:25]
	v_cvt_f32_f16_sdwa v35, v33 dst_sel:DWORD dst_unused:UNUSED_PAD src0_sel:WORD_1
	v_cvt_f32_f16_e32 v34, v33
	v_or_b32_e32 v20, v21, v20
	v_cvt_f16_f32_e32 v21, v16
	v_add_f32_e32 v16, v15, v14
	v_pk_add_f32 v[12:13], v[12:13], v[26:27]
	v_cvt_f16_f32_e32 v14, v10
	v_cvt_f16_f32_sdwa v15, v11 dst_sel:WORD_1 dst_unused:UNUSED_PAD src0_sel:DWORD
	v_mul_f32_e32 v11, v11, v11
	v_fmac_f32_e32 v11, v10, v10
	v_mul_f32_e32 v10, v13, v13
	v_fmac_f32_e32 v10, v12, v12
	s_waitcnt vmcnt(4)
	v_cvt_f32_f16_sdwa v33, v30 dst_sel:DWORD dst_unused:UNUSED_PAD src0_sel:WORD_1
	v_cvt_f32_f16_e32 v32, v30
	v_add_f32_e32 v10, v11, v10
	v_pk_add_f32 v[6:7], v[6:7], v[28:29]
	v_or_b32_e32 v14, v15, v14
	v_cvt_f16_f32_e32 v15, v12
	v_add_f32_e32 v12, v16, v10
	v_pk_add_f32 v[8:9], v[8:9], v[34:35]
	v_cvt_f16_f32_e32 v10, v6
	v_cvt_f16_f32_sdwa v11, v7 dst_sel:WORD_1 dst_unused:UNUSED_PAD src0_sel:DWORD
	v_mul_f32_e32 v7, v7, v7
	v_fmac_f32_e32 v7, v6, v6
	v_mul_f32_e32 v6, v9, v9
	v_fmac_f32_e32 v6, v8, v8
	v_cvt_f32_f16_sdwa v37, v31 dst_sel:DWORD dst_unused:UNUSED_PAD src0_sel:WORD_1
	v_cvt_f32_f16_e32 v36, v31
	v_add_f32_e32 v6, v7, v6
	v_pk_add_f32 v[2:3], v[2:3], v[32:33]
	v_or_b32_e32 v10, v11, v10
	v_cvt_f16_f32_e32 v11, v8
	v_add_f32_e32 v8, v12, v6
	v_cvt_f16_f32_e32 v6, v2
	v_cvt_f16_f32_sdwa v7, v3 dst_sel:WORD_1 dst_unused:UNUSED_PAD src0_sel:DWORD
	v_cvt_f16_f32_sdwa v22, v17 dst_sel:WORD_1 dst_unused:UNUSED_PAD src0_sel:DWORD
	v_pk_add_f32 v[4:5], v[4:5], v[36:37]
	s_mov_b64 s[22:23], 0xb0
	v_cvt_f16_f32_sdwa v17, v13 dst_sel:WORD_1 dst_unused:UNUSED_PAD src0_sel:DWORD
	v_cvt_f16_f32_sdwa v13, v9 dst_sel:WORD_1 dst_unused:UNUSED_PAD src0_sel:DWORD
	v_or_b32_e32 v6, v7, v6
	v_cvt_f16_f32_e32 v7, v4
	v_cvt_f16_f32_sdwa v9, v5 dst_sel:WORD_1 dst_unused:UNUSED_PAD src0_sel:DWORD
	s_waitcnt lgkmcnt(0)
	v_lshl_add_u64 v[18:19], v[140:141], 0, s[22:23]
	v_mul_f32_e32 v3, v3, v3
	v_or_b32_e32 v21, v22, v21
	v_lshlrev_b64 v[22:23], 11, v[18:19]
	v_fmac_f32_e32 v3, v2, v2
	v_mul_f32_e32 v2, v5, v5
	v_lshl_add_u64 v[22:23], s[24:25], 0, v[22:23]
	v_fmac_f32_e32 v2, v4, v4
	v_lshl_add_u64 v[22:23], v[138:139], 1, v[22:23]
	v_or_b32_e32 v15, v17, v15
	v_or_b32_e32 v11, v13, v11
	v_or_b32_e32 v7, v9, v7
	v_add_f32_e32 v2, v3, v2
	global_store_dwordx2 v[22:23], v[20:21], off
	global_store_dwordx2 v[22:23], v[14:15], off offset:32
	global_store_dwordx2 v[22:23], v[10:11], off offset:256
	global_store_dwordx2 v[22:23], v[6:7], off offset:288
	v_add_f32_e32 v2, v8, v2
	v_mov_b32_e32 v3, v2
	s_nop 1
	v_permlane16_swap_b32_e32 v3, v2
	s_waitcnt lgkmcnt(0)
	v_add_f32_e32 v2, v2, v3
	v_mov_b32_e32 v3, v1
	s_nop 0
	v_mbcnt_lo_u32_b32 v3, -1, v3
	v_mbcnt_hi_u32_b32 v3, -1, v3
	v_lshlrev_b32_e32 v3, 2, v3
	v_xor_b32_e32 v3, 0x80, v3
	ds_bpermute_b32 v3, v3, v2
	s_and_saveexec_b64 s[22:23], s[0:1]
	s_cbranch_execz .LBB0_2006
	v_lshlrev_b64 v[4:5], 6, v[18:19]
	v_lshl_add_u64 v[4:5], s[20:21], 0, v[4:5]
	s_waitcnt lgkmcnt(0)
	v_add_f32_e32 v2, v2, v3
	global_store_dword v[4:5], v2, off

.LBB0_2078:
	s_mov_b32 s13, s33
	v_lshl_or_b32 v190, s21, 7, v175
	v_mov_b32_e32 v130, s13
	ds_read2_b32 v[130:131], v130 offset1:1
	s_ashr_i32 s21, s20, 31
	s_lshl_b64 s[20:21], s[20:21], 8
	v_lshl_add_u64 v[170:171], s[20:21], 0, v[158:159]
	v_lshlrev_b64 v[132:133], 6, v[170:171]
	s_waitcnt lgkmcnt(0)
	v_readfirstlane_b32 s13, v130
	v_readfirstlane_b32 s15, v131
	v_mov_b32_e32 v186, s13
	s_mov_b32 s13, s33
	v_mov_b32_e32 v187, s15
	v_mov_b32_e32 v130, s13
	ds_read2_b32 v[130:131], v130 offset1:1
	v_ashrrev_i32_e32 v191, 31, v190
	v_mov_b64_e32 v[226:227], v[240:241]
	s_waitcnt lgkmcnt(0)
	v_readfirstlane_b32 s22, v130
	v_readfirstlane_b32 s23, v131
	s_nop 1
	v_lshl_add_u64 v[130:131], s[22:23], 0, v[0:1]
	v_lshl_add_u64 v[130:131], v[130:131], 0, v[132:133]
	v_add_co_u32_e32 v134, vcc, s58, v130
	s_mov_b64 s[22:23], 0x10380000
	s_nop 0
	v_addc_co_u32_e32 v135, vcc, 0, v131, vcc
	v_lshl_add_u64 v[132:133], v[130:131], 0, s[22:23]
	global_load_dwordx4 v[176:179], v[134:135], off
	global_load_dwordx4 v[180:183], v[132:133], off offset:1024
	global_load_dwordx4 v[192:195], v[132:133], off offset:2048
	global_load_dwordx4 v[146:149], v[132:133], off offset:3072
	v_add_co_u32_e32 v130, vcc, s59, v130
	s_mov_b64 s[22:23], 0xaa00000
	s_nop 0
	v_addc_co_u32_e32 v131, vcc, 0, v131, vcc
	global_load_dwordx4 v[142:145], v[130:131], off
	global_load_dwordx4 v[138:141], v[130:131], off offset:1024
	global_load_dwordx4 v[134:137], v[130:131], off offset:2048
	s_nop 0
	global_load_dwordx4 v[130:133], v[130:131], off offset:3072
	s_andn2_b64 vcc, exec, s[0:1]
	s_waitcnt vmcnt(0)
	v_mov_b32_e32 v188, v177
	v_mov_b32_e32 v189, v178
	v_mov_b32_e32 v177, v179
	v_pk_add_f32 v[176:177], v[188:189], v[176:177]
	s_nop 0
	v_add_f32_e32 v172, v176, v177
	v_mov_b32_e32 v174, v172
	s_nop 1
	v_permlane16_swap_b32_e32 v174, v172
	v_mov_b32_e32 v176, v181
	v_mov_b32_e32 v177, v182
	v_mov_b32_e32 v181, v183
	v_pk_add_f32 v[176:177], v[176:177], v[180:181]
	s_waitcnt lgkmcnt(0)
	v_add_f32_e32 v172, v172, v174
	s_nop 0
	v_mov_b32_e32 v174, v172
	s_nop 1
	v_permlane32_swap_b32_e32 v174, v172
	s_waitcnt lgkmcnt(0)
	v_add_f32_e32 v172, v172, v174
	v_fmamk_f32 v172, v172, 0x3a800000, v228
	v_rsq_f32_e32 v188, v172
	v_add_f32_e32 v172, v176, v177
	v_mov_b32_e32 v174, v172
	s_nop 1
	v_permlane16_swap_b32_e32 v174, v172
	v_mov_b32_e32 v176, v193
	v_mov_b32_e32 v177, v194
	v_mov_b32_e32 v193, v195
	v_pk_add_f32 v[176:177], v[176:177], v[192:193]
	s_waitcnt lgkmcnt(0)
	v_add_f32_e32 v172, v172, v174
	v_pk_mul_f32 v[126:127], v[126:127], v[188:189] op_sel_hi:[1,0]
	v_mov_b32_e32 v174, v172
	s_nop 1
	v_permlane32_swap_b32_e32 v174, v172
	v_pk_mul_f32 v[122:123], v[122:123], v[188:189] op_sel_hi:[1,0]
	v_pk_mul_f32 v[124:125], v[124:125], v[188:189] op_sel_hi:[1,0]
	v_pk_mul_f32 v[118:119], v[118:119], v[188:189] op_sel_hi:[1,0]
	v_pk_mul_f32 v[114:115], v[114:115], v[188:189] op_sel_hi:[1,0]
	s_waitcnt lgkmcnt(0)
	v_add_f32_e32 v172, v172, v174
	v_fmamk_f32 v172, v172, 0x3a800000, v228
	v_rsq_f32_e32 v174, v172
	v_add_f32_e32 v172, v176, v177
	v_mov_b32_e32 v177, v148
	v_mov_b32_e32 v176, v172
	s_nop 1
	v_permlane16_swap_b32_e32 v176, v172
	v_mov_b32_e32 v148, v143
	v_mov_b32_e32 v143, v145
	v_mov_b32_e32 v145, v140
	v_mov_b32_e32 v140, v135
	s_waitcnt lgkmcnt(0)
	v_add_f32_e32 v172, v172, v176
	v_mov_b32_e32 v135, v137
	v_mov_b32_e32 v176, v172
	s_nop 1
	v_permlane32_swap_b32_e32 v176, v172
	v_mov_b32_e32 v137, v132
	v_pk_mul_f32 v[116:117], v[116:117], v[188:189] op_sel_hi:[1,0]
	v_pk_mul_f32 v[110:111], v[110:111], v[174:175] op_sel_hi:[1,0]
	v_pk_mul_f32 v[106:107], v[106:107], v[174:175] op_sel_hi:[1,0]
	s_waitcnt lgkmcnt(0)
	v_add_f32_e32 v172, v172, v176
	v_mov_b32_e32 v176, v147
	v_mov_b32_e32 v147, v149
	v_pk_add_f32 v[146:147], v[176:177], v[146:147]
	v_mov_b32_e32 v149, v144
	v_add_f32_e32 v146, v146, v147
	v_pk_add_f32 v[142:143], v[148:149], v[142:143]
	v_mov_b32_e32 v147, v146
	s_nop 1
	v_permlane16_swap_b32_e32 v147, v146
	v_add_f32_e32 v142, v142, v143
	v_mov_b32_e32 v144, v139
	v_mov_b32_e32 v139, v141
	s_waitcnt lgkmcnt(0)
	v_add_f32_e32 v146, v146, v147
	v_mov_b32_e32 v147, v1
	v_mov_b32_e32 v141, v136
	v_mov_b32_e32 v143, v142
	s_nop 1
	v_permlane16_swap_b32_e32 v143, v142
	v_mov_b32_e32 v136, v131
	v_mov_b32_e32 v131, v133
	v_mul_f32_e32 v133, 0xbfb8aa3b, v126
	v_exp_f32_e32 v133, v133
	v_pk_add_f32 v[138:139], v[144:145], v[138:139]
	s_waitcnt lgkmcnt(0)
	v_add_f32_e32 v142, v142, v143
	v_mov_b32_e32 v143, v1
	v_add_f32_e32 v138, v138, v139
	v_add_f32_e32 v133, 1.0, v133
	v_pk_add_f32 v[130:131], v[136:137], v[130:131]
	v_rcp_f32_e32 v136, v133
	v_mul_f32_e32 v133, 0xbfb8aa3b, v127
	v_exp_f32_e32 v133, v133
	v_mov_b32_e32 v139, v138
	s_nop 1
	v_permlane16_swap_b32_e32 v139, v138
	v_add_f32_e32 v133, 1.0, v133
	v_rcp_f32_e32 v137, v133
	v_pk_add_f32 v[134:135], v[140:141], v[134:135]
	v_add_f32_e32 v130, v130, v131
	s_waitcnt lgkmcnt(0)
	v_add_f32_e32 v138, v138, v139
	v_mov_b32_e32 v139, v1
	v_add_f32_e32 v134, v134, v135
	v_pk_mul_f32 v[126:127], v[126:127], v[136:137]
	v_pk_mul_f32 v[122:123], v[122:123], v[126:127]
	v_pk_mul_f32 v[126:127], v[128:129], v[188:189] op_sel_hi:[1,0]
	v_mul_f32_e32 v128, 0xbfb8aa3b, v126
	v_mul_f32_e32 v129, 0xbfb8aa3b, v127
	v_exp_f32_e32 v128, v128
	v_exp_f32_e32 v129, v129
	v_mov_b32_e32 v135, v134
	s_nop 1
	v_permlane16_swap_b32_e32 v135, v134
	v_add_f32_e32 v128, 1.0, v128
	v_add_f32_e32 v129, 1.0, v129
	v_rcp_f32_e32 v128, v128
	v_rcp_f32_e32 v129, v129
	s_waitcnt lgkmcnt(0)
	v_add_f32_e32 v134, v134, v135
	v_mov_b32_e32 v135, v1
	v_pk_mul_f32 v[126:127], v[126:127], v[128:129]
	v_pk_mul_f32 v[124:125], v[124:125], v[126:127]
	v_mul_f32_e32 v126, 0xbfb8aa3b, v118
	v_mul_f32_e32 v127, 0xbfb8aa3b, v119
	v_exp_f32_e32 v126, v126
	v_exp_f32_e32 v127, v127
	v_mov_b32_e32 v131, v130
	s_nop 1
	v_permlane16_swap_b32_e32 v131, v130
	v_add_f32_e32 v126, 1.0, v126
	v_add_f32_e32 v127, 1.0, v127
	v_rcp_f32_e32 v126, v126
	v_rcp_f32_e32 v127, v127
	s_waitcnt lgkmcnt(0)
	v_add_f32_e32 v130, v130, v131
	v_pk_mul_f32 v[118:119], v[118:119], v[126:127]
	v_pk_mul_f32 v[118:119], v[114:115], v[118:119]
	v_pk_mul_f32 v[114:115], v[120:121], v[188:189] op_sel_hi:[1,0]
	v_mul_f32_e32 v120, 0xbfb8aa3b, v114
	v_mul_f32_e32 v121, 0xbfb8aa3b, v115
	v_exp_f32_e32 v120, v120
	v_exp_f32_e32 v121, v121
	v_mov_b32_e32 v131, v130
	s_nop 1
	v_permlane32_swap_b32_e32 v131, v130
	v_pk_mul_f32 v[108:109], v[108:109], v[174:175] op_sel_hi:[1,0]
	v_add_f32_e32 v120, 1.0, v120
	v_add_f32_e32 v121, 1.0, v121
	v_rcp_f32_e32 v120, v120
	v_rcp_f32_e32 v121, v121
	s_waitcnt lgkmcnt(0)
	v_add_f32_e32 v130, v130, v131
	v_fmamk_f32 v130, v130, 0x3a800000, v228
	v_rsq_f32_e32 v132, v130
	v_lshl_add_u64 v[130:131], v[190:191], 1, v[186:187]
	v_lshl_add_u64 v[130:131], v[130:131], 0, s[22:23]
	v_pk_mul_f32 v[114:115], v[114:115], v[120:121]
	v_pk_mul_f32 v[102:103], v[102:103], v[174:175] op_sel_hi:[1,0]
	v_pk_mul_f32 v[120:121], v[116:117], v[114:115]
	v_cvt_pk_bf16_f32 v116, v118, v119
	v_mad_u64_u32 v[118:119], s[22:23], v170, s89, v[130:131]
	v_cvt_pk_bf16_f32 v117, v120, v121
	v_mov_b32_e32 v120, v119
	v_mad_u64_u32 v[120:121], s[22:23], v171, s89, v[120:121]
	v_cvt_pk_bf16_f32 v114, v122, v123
	v_cvt_pk_bf16_f32 v115, v124, v125
	v_mov_b32_e32 v119, v120
	global_store_dwordx4 v[118:119], v[114:117], off sc1
	v_pk_mul_f32 v[98:99], v[98:99], v[174:175] op_sel_hi:[1,0]
	v_fmamk_f32 v172, v172, 0x3a800000, v228
	v_mul_f32_e32 v114, 0xbfb8aa3b, v110
	v_mul_f32_e32 v115, 0xbfb8aa3b, v111
	v_exp_f32_e32 v114, v114
	v_exp_f32_e32 v115, v115
	v_rsq_f32_e32 v172, v172
	v_pk_mul_f32 v[100:101], v[100:101], v[174:175] op_sel_hi:[1,0]
	v_add_f32_e32 v114, 1.0, v114
	v_add_f32_e32 v115, 1.0, v115
	v_rcp_f32_e32 v114, v114
	v_rcp_f32_e32 v115, v115
	v_pk_mul_f32 v[94:95], v[94:95], v[172:173] op_sel_hi:[1,0]
	v_pk_mul_f32 v[90:91], v[90:91], v[172:173] op_sel_hi:[1,0]
	v_pk_mul_f32 v[92:93], v[92:93], v[172:173] op_sel_hi:[1,0]
	v_pk_mul_f32 v[110:111], v[110:111], v[114:115]
	v_pk_mul_f32 v[86:87], v[86:87], v[172:173] op_sel_hi:[1,0]
	v_pk_mul_f32 v[106:107], v[106:107], v[110:111]
	v_pk_mul_f32 v[110:111], v[112:113], v[174:175] op_sel_hi:[1,0]
	v_pk_mul_f32 v[82:83], v[82:83], v[172:173] op_sel_hi:[1,0]
	v_mul_f32_e32 v112, 0xbfb8aa3b, v110
	v_mul_f32_e32 v113, 0xbfb8aa3b, v111
	v_exp_f32_e32 v112, v112
	v_exp_f32_e32 v113, v113
	v_mbcnt_lo_u32_b32 v147, -1, v147
	v_mbcnt_hi_u32_b32 v147, -1, v147
	v_add_f32_e32 v112, 1.0, v112
	v_add_f32_e32 v113, 1.0, v113
	v_rcp_f32_e32 v112, v112
	v_rcp_f32_e32 v113, v113
	v_lshlrev_b32_e32 v147, 2, v147
	v_xor_b32_e32 v147, 0x80, v147
	ds_bpermute_b32 v147, v147, v146
	v_pk_mul_f32 v[110:111], v[110:111], v[112:113]
	v_pk_mul_f32 v[84:85], v[84:85], v[172:173] op_sel_hi:[1,0]
	v_pk_mul_f32 v[108:109], v[108:109], v[110:111]
	v_mul_f32_e32 v110, 0xbfb8aa3b, v102
	v_mul_f32_e32 v111, 0xbfb8aa3b, v103
	v_exp_f32_e32 v110, v110
	v_exp_f32_e32 v111, v111
	s_waitcnt lgkmcnt(0)
	v_add_f32_e32 v146, v146, v147
	v_fmamk_f32 v146, v146, 0x3a800000, v228
	v_add_f32_e32 v110, 1.0, v110
	v_add_f32_e32 v111, 1.0, v111
	v_rcp_f32_e32 v110, v110
	v_rcp_f32_e32 v111, v111
	v_rsq_f32_e32 v146, v146
	v_mbcnt_lo_u32_b32 v143, -1, v143
	v_mbcnt_hi_u32_b32 v143, -1, v143
	v_pk_mul_f32 v[102:103], v[102:103], v[110:111]
	v_lshl_add_u64 v[110:111], v[160:161], 0, s[20:21]
	v_pk_mul_f32 v[102:103], v[98:99], v[102:103]
	v_pk_mul_f32 v[98:99], v[104:105], v[174:175] op_sel_hi:[1,0]
	v_pk_mul_f32 v[78:79], v[78:79], v[146:147] op_sel_hi:[1,0]
	v_mul_f32_e32 v104, 0xbfb8aa3b, v98
	v_mul_f32_e32 v105, 0xbfb8aa3b, v99
	v_exp_f32_e32 v104, v104
	v_exp_f32_e32 v105, v105
	v_pk_mul_f32 v[74:75], v[74:75], v[146:147] op_sel_hi:[1,0]
	v_pk_mul_f32 v[76:77], v[76:77], v[146:147] op_sel_hi:[1,0]
	v_add_f32_e32 v104, 1.0, v104
	v_add_f32_e32 v105, 1.0, v105
	v_rcp_f32_e32 v104, v104
	v_rcp_f32_e32 v105, v105
	v_pk_mul_f32 v[70:71], v[70:71], v[146:147] op_sel_hi:[1,0]
	v_pk_mul_f32 v[66:67], v[66:67], v[146:147] op_sel_hi:[1,0]
	v_lshlrev_b32_e32 v143, 2, v143
	v_pk_mul_f32 v[98:99], v[98:99], v[104:105]
	v_xor_b32_e32 v143, 0x80, v143
	v_pk_mul_f32 v[104:105], v[100:101], v[98:99]
	v_cvt_pk_bf16_f32 v100, v102, v103
	v_mad_u64_u32 v[102:103], s[22:23], v110, s89, v[130:131]
	v_cvt_pk_bf16_f32 v101, v104, v105
	v_mov_b32_e32 v104, v103
	v_mad_u64_u32 v[104:105], s[22:23], v111, s89, v[104:105]
	v_cvt_pk_bf16_f32 v98, v106, v107
	v_cvt_pk_bf16_f32 v99, v108, v109
	v_mov_b32_e32 v103, v104
	global_store_dwordx4 v[102:103], v[98:101], off sc1
	ds_bpermute_b32 v143, v143, v142
	v_pk_mul_f32 v[68:69], v[68:69], v[146:147] op_sel_hi:[1,0]
	v_mul_f32_e32 v98, 0xbfb8aa3b, v94
	v_mul_f32_e32 v99, 0xbfb8aa3b, v95
	v_exp_f32_e32 v98, v98
	v_exp_f32_e32 v99, v99
	s_waitcnt lgkmcnt(0)
	v_add_f32_e32 v142, v142, v143
	v_fmamk_f32 v142, v142, 0x3a800000, v228
	v_add_f32_e32 v98, 1.0, v98
	v_add_f32_e32 v99, 1.0, v99
	v_rcp_f32_e32 v98, v98
	v_rcp_f32_e32 v99, v99
	v_rsq_f32_e32 v142, v142
	v_mbcnt_lo_u32_b32 v139, -1, v139
	v_mbcnt_hi_u32_b32 v139, -1, v139
	v_pk_mul_f32 v[94:95], v[94:95], v[98:99]
	v_pk_mul_f32 v[62:63], v[62:63], v[142:143] op_sel_hi:[1,0]
	v_pk_mul_f32 v[90:91], v[90:91], v[94:95]
	v_pk_mul_f32 v[94:95], v[96:97], v[172:173] op_sel_hi:[1,0]
	v_pk_mul_f32 v[58:59], v[58:59], v[142:143] op_sel_hi:[1,0]
	v_mul_f32_e32 v96, 0xbfb8aa3b, v94
	v_mul_f32_e32 v97, 0xbfb8aa3b, v95
	v_exp_f32_e32 v96, v96
	v_exp_f32_e32 v97, v97
	v_pk_mul_f32 v[60:61], v[60:61], v[142:143] op_sel_hi:[1,0]
	v_pk_mul_f32 v[54:55], v[54:55], v[142:143] op_sel_hi:[1,0]
	v_add_f32_e32 v96, 1.0, v96
	v_add_f32_e32 v97, 1.0, v97
	v_rcp_f32_e32 v96, v96
	v_rcp_f32_e32 v97, v97
	v_pk_mul_f32 v[50:51], v[50:51], v[142:143] op_sel_hi:[1,0]
	v_lshlrev_b32_e32 v139, 2, v139
	v_xor_b32_e32 v139, 0x80, v139
	v_pk_mul_f32 v[94:95], v[94:95], v[96:97]
	ds_bpermute_b32 v139, v139, v138
	v_pk_mul_f32 v[92:93], v[92:93], v[94:95]
	v_mul_f32_e32 v94, 0xbfb8aa3b, v86
	v_mul_f32_e32 v95, 0xbfb8aa3b, v87
	v_exp_f32_e32 v94, v94
	v_exp_f32_e32 v95, v95
	s_waitcnt lgkmcnt(0)
	v_add_f32_e32 v138, v138, v139
	v_fmamk_f32 v138, v138, 0x3a800000, v228
	v_add_f32_e32 v94, 1.0, v94
	v_add_f32_e32 v95, 1.0, v95
	v_rcp_f32_e32 v94, v94
	v_rcp_f32_e32 v95, v95
	v_rsq_f32_e32 v138, v138
	v_pk_mul_f32 v[52:53], v[52:53], v[142:143] op_sel_hi:[1,0]
	v_mbcnt_lo_u32_b32 v135, -1, v135
	v_pk_mul_f32 v[86:87], v[86:87], v[94:95]
	v_lshl_add_u64 v[94:95], v[162:163], 0, s[20:21]
	v_pk_mul_f32 v[86:87], v[82:83], v[86:87]
	v_pk_mul_f32 v[82:83], v[88:89], v[172:173] op_sel_hi:[1,0]
	v_pk_mul_f32 v[46:47], v[46:47], v[138:139] op_sel_hi:[1,0]
	v_mul_f32_e32 v88, 0xbfb8aa3b, v82
	v_mul_f32_e32 v89, 0xbfb8aa3b, v83
	v_exp_f32_e32 v88, v88
	v_exp_f32_e32 v89, v89
	v_pk_mul_f32 v[42:43], v[42:43], v[138:139] op_sel_hi:[1,0]
	v_pk_mul_f32 v[44:45], v[44:45], v[138:139] op_sel_hi:[1,0]
	v_add_f32_e32 v88, 1.0, v88
	v_add_f32_e32 v89, 1.0, v89
	v_rcp_f32_e32 v88, v88
	v_rcp_f32_e32 v89, v89
	v_pk_mul_f32 v[38:39], v[38:39], v[138:139] op_sel_hi:[1,0]
	v_pk_mul_f32 v[34:35], v[34:35], v[138:139] op_sel_hi:[1,0]
	v_mbcnt_hi_u32_b32 v135, -1, v135
	v_pk_mul_f32 v[82:83], v[82:83], v[88:89]
	v_lshlrev_b32_e32 v135, 2, v135
	v_pk_mul_f32 v[88:89], v[84:85], v[82:83]
	v_cvt_pk_bf16_f32 v84, v86, v87
	v_mad_u64_u32 v[86:87], s[22:23], v94, s89, v[130:131]
	v_cvt_pk_bf16_f32 v85, v88, v89
	v_mov_b32_e32 v88, v87
	v_mad_u64_u32 v[88:89], s[22:23], v95, s89, v[88:89]
	v_cvt_pk_bf16_f32 v82, v90, v91
	v_cvt_pk_bf16_f32 v83, v92, v93
	v_mov_b32_e32 v87, v88
	global_store_dwordx4 v[86:87], v[82:85], off sc1
	v_xor_b32_e32 v135, 0x80, v135
	ds_bpermute_b32 v135, v135, v134
	v_mul_f32_e32 v82, 0xbfb8aa3b, v78
	v_mul_f32_e32 v83, 0xbfb8aa3b, v79
	v_exp_f32_e32 v82, v82
	v_exp_f32_e32 v83, v83
	s_waitcnt lgkmcnt(0)
	v_add_f32_e32 v134, v134, v135
	v_fmamk_f32 v134, v134, 0x3a800000, v228
	v_add_f32_e32 v82, 1.0, v82
	v_add_f32_e32 v83, 1.0, v83
	v_rcp_f32_e32 v82, v82
	v_rcp_f32_e32 v83, v83
	v_rsq_f32_e32 v134, v134
	v_pk_mul_f32 v[36:37], v[36:37], v[138:139] op_sel_hi:[1,0]
	v_pk_mul_f32 v[14:15], v[14:15], v[132:133] op_sel_hi:[1,0]
	v_pk_mul_f32 v[78:79], v[78:79], v[82:83]
	v_pk_mul_f32 v[30:31], v[30:31], v[134:135] op_sel_hi:[1,0]
	v_pk_mul_f32 v[74:75], v[74:75], v[78:79]
	v_pk_mul_f32 v[78:79], v[80:81], v[146:147] op_sel_hi:[1,0]
	v_pk_mul_f32 v[26:27], v[26:27], v[134:135] op_sel_hi:[1,0]
	v_mul_f32_e32 v80, 0xbfb8aa3b, v78
	v_mul_f32_e32 v81, 0xbfb8aa3b, v79
	v_exp_f32_e32 v80, v80
	v_exp_f32_e32 v81, v81
	v_pk_mul_f32 v[28:29], v[28:29], v[134:135] op_sel_hi:[1,0]
	v_pk_mul_f32 v[22:23], v[22:23], v[134:135] op_sel_hi:[1,0]
	v_add_f32_e32 v80, 1.0, v80
	v_add_f32_e32 v81, 1.0, v81
	v_rcp_f32_e32 v80, v80
	v_rcp_f32_e32 v81, v81
	v_pk_mul_f32 v[18:19], v[18:19], v[134:135] op_sel_hi:[1,0]
	v_pk_mul_f32 v[20:21], v[20:21], v[134:135] op_sel_hi:[1,0]
	v_pk_mul_f32 v[10:11], v[10:11], v[132:133] op_sel_hi:[1,0]
	v_pk_mul_f32 v[78:79], v[78:79], v[80:81]
	v_pk_mul_f32 v[12:13], v[12:13], v[132:133] op_sel_hi:[1,0]
	v_pk_mul_f32 v[76:77], v[76:77], v[78:79]
	v_mul_f32_e32 v78, 0xbfb8aa3b, v70
	v_mul_f32_e32 v79, 0xbfb8aa3b, v71
	v_exp_f32_e32 v78, v78
	v_exp_f32_e32 v79, v79
	v_pk_mul_f32 v[6:7], v[6:7], v[132:133] op_sel_hi:[1,0]
	v_pk_mul_f32 v[2:3], v[2:3], v[132:133] op_sel_hi:[1,0]
	v_add_f32_e32 v78, 1.0, v78
	v_add_f32_e32 v79, 1.0, v79
	v_rcp_f32_e32 v78, v78
	v_rcp_f32_e32 v79, v79
	v_pk_mul_f32 v[4:5], v[4:5], v[132:133] op_sel_hi:[1,0]
	v_pk_mul_f32 v[70:71], v[70:71], v[78:79]
	s_nop 0
	v_pk_mul_f32 v[70:71], v[66:67], v[70:71]
	v_pk_mul_f32 v[66:67], v[72:73], v[146:147] op_sel_hi:[1,0]
	v_lshl_add_u64 v[78:79], v[164:165], 0, s[20:21]
	v_mul_f32_e32 v72, 0xbfb8aa3b, v66
	v_mul_f32_e32 v73, 0xbfb8aa3b, v67
	v_exp_f32_e32 v72, v72
	v_exp_f32_e32 v73, v73
	v_add_f32_e32 v72, 1.0, v72
	v_add_f32_e32 v73, 1.0, v73
	v_rcp_f32_e32 v72, v72
	v_rcp_f32_e32 v73, v73
	s_nop 0
	v_pk_mul_f32 v[66:67], v[66:67], v[72:73]
	s_nop 0
	v_pk_mul_f32 v[72:73], v[68:69], v[66:67]
	v_cvt_pk_bf16_f32 v68, v70, v71
	v_mad_u64_u32 v[70:71], s[20:21], v78, s89, v[130:131]
	v_cvt_pk_bf16_f32 v69, v72, v73
	v_mov_b32_e32 v72, v71
	v_mad_u64_u32 v[72:73], s[20:21], v79, s89, v[72:73]
	v_cvt_pk_bf16_f32 v66, v74, v75
	v_cvt_pk_bf16_f32 v67, v76, v77
	v_mov_b32_e32 v71, v72
	global_store_dwordx4 v[70:71], v[66:69], off sc1
	s_nop 1
	v_mul_f32_e32 v66, 0xbfb8aa3b, v62
	v_mul_f32_e32 v67, 0xbfb8aa3b, v63
	v_exp_f32_e32 v66, v66
	v_exp_f32_e32 v67, v67
	v_add_f32_e32 v66, 1.0, v66
	v_add_f32_e32 v67, 1.0, v67
	v_rcp_f32_e32 v66, v66
	v_rcp_f32_e32 v67, v67
	s_nop 0
	v_pk_mul_f32 v[62:63], v[62:63], v[66:67]
	s_nop 0
	v_pk_mul_f32 v[58:59], v[58:59], v[62:63]
	v_pk_mul_f32 v[62:63], v[64:65], v[142:143] op_sel_hi:[1,0]
	s_nop 0
	v_mul_f32_e32 v64, 0xbfb8aa3b, v62
	v_mul_f32_e32 v65, 0xbfb8aa3b, v63
	v_exp_f32_e32 v64, v64
	v_exp_f32_e32 v65, v65
	v_add_f32_e32 v64, 1.0, v64
	v_add_f32_e32 v65, 1.0, v65
	v_rcp_f32_e32 v64, v64
	v_rcp_f32_e32 v65, v65
	s_nop 0
	v_pk_mul_f32 v[62:63], v[62:63], v[64:65]
	s_nop 0
	v_pk_mul_f32 v[60:61], v[60:61], v[62:63]
	v_mul_f32_e32 v62, 0xbfb8aa3b, v54
	v_mul_f32_e32 v63, 0xbfb8aa3b, v55
	v_exp_f32_e32 v62, v62
	v_exp_f32_e32 v63, v63
	v_add_f32_e32 v62, 1.0, v62
	v_add_f32_e32 v63, 1.0, v63
	v_rcp_f32_e32 v62, v62
	v_rcp_f32_e32 v63, v63
	s_nop 0
	v_pk_mul_f32 v[54:55], v[54:55], v[62:63]
	s_nop 0
	v_pk_mul_f32 v[54:55], v[50:51], v[54:55]
	v_pk_mul_f32 v[50:51], v[56:57], v[142:143] op_sel_hi:[1,0]
	v_lshl_add_u64 v[62:63], v[170:171], 0, s[96:97]
	v_mul_f32_e32 v56, 0xbfb8aa3b, v50
	v_mul_f32_e32 v57, 0xbfb8aa3b, v51
	v_exp_f32_e32 v56, v56
	v_exp_f32_e32 v57, v57
	v_add_f32_e32 v56, 1.0, v56
	v_add_f32_e32 v57, 1.0, v57
	v_rcp_f32_e32 v56, v56
	v_rcp_f32_e32 v57, v57
	s_nop 0
	v_pk_mul_f32 v[50:51], v[50:51], v[56:57]
	s_nop 0
	v_pk_mul_f32 v[56:57], v[52:53], v[50:51]
	v_cvt_pk_bf16_f32 v52, v54, v55
	v_mad_u64_u32 v[54:55], s[20:21], v62, s89, v[130:131]
	v_cvt_pk_bf16_f32 v53, v56, v57
	v_mov_b32_e32 v56, v55
	v_mad_u64_u32 v[56:57], s[20:21], v63, s89, v[56:57]
	v_cvt_pk_bf16_f32 v50, v58, v59
	v_cvt_pk_bf16_f32 v51, v60, v61
	v_mov_b32_e32 v55, v56
	global_store_dwordx4 v[54:55], v[50:53], off sc1
	s_mov_b64 s[20:21], 0x90
	s_nop 0
	v_mul_f32_e32 v50, 0xbfb8aa3b, v46
	v_mul_f32_e32 v51, 0xbfb8aa3b, v47
	v_exp_f32_e32 v50, v50
	v_exp_f32_e32 v51, v51
	v_add_f32_e32 v50, 1.0, v50
	v_add_f32_e32 v51, 1.0, v51
	v_rcp_f32_e32 v50, v50
	v_rcp_f32_e32 v51, v51
	s_nop 0
	v_pk_mul_f32 v[46:47], v[46:47], v[50:51]
	s_nop 0
	v_pk_mul_f32 v[42:43], v[42:43], v[46:47]
	v_pk_mul_f32 v[46:47], v[48:49], v[138:139] op_sel_hi:[1,0]
	s_nop 0
	v_mul_f32_e32 v48, 0xbfb8aa3b, v46
	v_mul_f32_e32 v49, 0xbfb8aa3b, v47
	v_exp_f32_e32 v48, v48
	v_exp_f32_e32 v49, v49
	v_add_f32_e32 v48, 1.0, v48
	v_add_f32_e32 v49, 1.0, v49
	v_rcp_f32_e32 v48, v48
	v_rcp_f32_e32 v49, v49
	s_nop 0
	v_pk_mul_f32 v[46:47], v[46:47], v[48:49]
	s_nop 0
	v_pk_mul_f32 v[44:45], v[44:45], v[46:47]
	v_mul_f32_e32 v46, 0xbfb8aa3b, v38
	v_mul_f32_e32 v47, 0xbfb8aa3b, v39
	v_exp_f32_e32 v46, v46
	v_exp_f32_e32 v47, v47
	v_add_f32_e32 v46, 1.0, v46
	v_add_f32_e32 v47, 1.0, v47
	v_rcp_f32_e32 v46, v46
	v_rcp_f32_e32 v47, v47
	s_nop 0
	v_pk_mul_f32 v[38:39], v[38:39], v[46:47]
	s_nop 0
	v_pk_mul_f32 v[38:39], v[34:35], v[38:39]
	v_pk_mul_f32 v[34:35], v[40:41], v[138:139] op_sel_hi:[1,0]
	v_lshl_add_u64 v[46:47], v[170:171], 0, s[20:21]
	v_mul_f32_e32 v40, 0xbfb8aa3b, v34
	v_mul_f32_e32 v41, 0xbfb8aa3b, v35
	v_exp_f32_e32 v40, v40
	v_exp_f32_e32 v41, v41
	v_add_f32_e32 v40, 1.0, v40
	v_add_f32_e32 v41, 1.0, v41
	v_rcp_f32_e32 v40, v40
	v_rcp_f32_e32 v41, v41
	s_nop 0
	v_pk_mul_f32 v[34:35], v[34:35], v[40:41]
	s_nop 0
	v_pk_mul_f32 v[40:41], v[36:37], v[34:35]
	v_cvt_pk_bf16_f32 v36, v38, v39
	v_mad_u64_u32 v[38:39], s[20:21], v46, s89, v[130:131]
	v_cvt_pk_bf16_f32 v37, v40, v41
	v_mov_b32_e32 v40, v39
	v_mad_u64_u32 v[40:41], s[20:21], v47, s89, v[40:41]
	v_cvt_pk_bf16_f32 v34, v42, v43
	v_cvt_pk_bf16_f32 v35, v44, v45
	v_mov_b32_e32 v39, v40
	global_store_dwordx4 v[38:39], v[34:37], off sc1
	s_mov_b64 s[20:21], 0xa0
	s_nop 0
	v_mul_f32_e32 v34, 0xbfb8aa3b, v30
	v_mul_f32_e32 v35, 0xbfb8aa3b, v31
	v_exp_f32_e32 v34, v34
	v_exp_f32_e32 v35, v35
	v_add_f32_e32 v34, 1.0, v34
	v_add_f32_e32 v35, 1.0, v35
	v_rcp_f32_e32 v34, v34
	v_rcp_f32_e32 v35, v35
	s_nop 0
	v_pk_mul_f32 v[30:31], v[30:31], v[34:35]
	s_nop 0
	v_pk_mul_f32 v[26:27], v[26:27], v[30:31]
	v_pk_mul_f32 v[30:31], v[32:33], v[134:135] op_sel_hi:[1,0]
	s_nop 0
	v_mul_f32_e32 v32, 0xbfb8aa3b, v30
	v_mul_f32_e32 v33, 0xbfb8aa3b, v31
	v_exp_f32_e32 v32, v32
	v_exp_f32_e32 v33, v33
	v_add_f32_e32 v32, 1.0, v32
	v_add_f32_e32 v33, 1.0, v33
	v_rcp_f32_e32 v32, v32
	v_rcp_f32_e32 v33, v33
	s_nop 0
	v_pk_mul_f32 v[30:31], v[30:31], v[32:33]
	s_nop 0
	v_pk_mul_f32 v[28:29], v[28:29], v[30:31]
	v_mul_f32_e32 v30, 0xbfb8aa3b, v22
	v_mul_f32_e32 v31, 0xbfb8aa3b, v23
	v_exp_f32_e32 v30, v30
	v_exp_f32_e32 v31, v31
	v_add_f32_e32 v30, 1.0, v30
	v_add_f32_e32 v31, 1.0, v31
	v_rcp_f32_e32 v30, v30
	v_rcp_f32_e32 v31, v31
	s_nop 0
	v_pk_mul_f32 v[22:23], v[22:23], v[30:31]
	s_nop 0
	v_pk_mul_f32 v[22:23], v[18:19], v[22:23]
	v_pk_mul_f32 v[18:19], v[24:25], v[134:135] op_sel_hi:[1,0]
	v_lshl_add_u64 v[30:31], v[170:171], 0, s[20:21]
	v_mul_f32_e32 v24, 0xbfb8aa3b, v18
	v_mul_f32_e32 v25, 0xbfb8aa3b, v19
	v_exp_f32_e32 v24, v24
	v_exp_f32_e32 v25, v25
	v_add_f32_e32 v24, 1.0, v24
	v_add_f32_e32 v25, 1.0, v25
	v_rcp_f32_e32 v24, v24
	v_rcp_f32_e32 v25, v25
	s_nop 0
	v_pk_mul_f32 v[18:19], v[18:19], v[24:25]
	s_nop 0
	v_pk_mul_f32 v[24:25], v[20:21], v[18:19]
	v_cvt_pk_bf16_f32 v20, v22, v23
	v_mad_u64_u32 v[22:23], s[20:21], v30, s89, v[130:131]
	v_cvt_pk_bf16_f32 v21, v24, v25
	v_mov_b32_e32 v24, v23
	v_mad_u64_u32 v[24:25], s[20:21], v31, s89, v[24:25]
	v_cvt_pk_bf16_f32 v18, v26, v27
	v_cvt_pk_bf16_f32 v19, v28, v29
	v_mov_b32_e32 v23, v24
	global_store_dwordx4 v[22:23], v[18:21], off sc1
	s_mov_b64 s[20:21], 0xb0
	s_nop 0
	v_mul_f32_e32 v18, 0xbfb8aa3b, v14
	v_mul_f32_e32 v19, 0xbfb8aa3b, v15
	v_exp_f32_e32 v18, v18
	v_exp_f32_e32 v19, v19
	v_add_f32_e32 v18, 1.0, v18
	v_add_f32_e32 v19, 1.0, v19
	v_rcp_f32_e32 v18, v18
	v_rcp_f32_e32 v19, v19
	s_nop 0
	v_pk_mul_f32 v[14:15], v[14:15], v[18:19]
	s_nop 0
	v_pk_mul_f32 v[10:11], v[10:11], v[14:15]
	v_pk_mul_f32 v[14:15], v[16:17], v[132:133] op_sel_hi:[1,0]
	s_nop 0
	v_mul_f32_e32 v16, 0xbfb8aa3b, v14
	v_mul_f32_e32 v17, 0xbfb8aa3b, v15
	v_exp_f32_e32 v16, v16
	v_exp_f32_e32 v17, v17
	v_add_f32_e32 v16, 1.0, v16
	v_add_f32_e32 v17, 1.0, v17
	v_rcp_f32_e32 v16, v16
	v_rcp_f32_e32 v17, v17
	s_nop 0
	v_pk_mul_f32 v[14:15], v[14:15], v[16:17]
	s_nop 0
	v_pk_mul_f32 v[12:13], v[12:13], v[14:15]
	v_mul_f32_e32 v14, 0xbfb8aa3b, v6
	v_mul_f32_e32 v15, 0xbfb8aa3b, v7
	v_exp_f32_e32 v14, v14
	v_exp_f32_e32 v15, v15
	v_add_f32_e32 v14, 1.0, v14
	v_add_f32_e32 v15, 1.0, v15
	v_rcp_f32_e32 v14, v14
	v_rcp_f32_e32 v15, v15
	s_nop 0
	v_pk_mul_f32 v[6:7], v[6:7], v[14:15]
	s_nop 0
	v_pk_mul_f32 v[6:7], v[2:3], v[6:7]
	v_pk_mul_f32 v[2:3], v[8:9], v[132:133] op_sel_hi:[1,0]
	v_lshl_add_u64 v[14:15], v[170:171], 0, s[20:21]
	v_mul_f32_e32 v8, 0xbfb8aa3b, v2
	v_mul_f32_e32 v9, 0xbfb8aa3b, v3
	v_exp_f32_e32 v8, v8
	v_exp_f32_e32 v9, v9
	v_add_f32_e32 v8, 1.0, v8
	v_add_f32_e32 v9, 1.0, v9
	v_rcp_f32_e32 v8, v8
	v_rcp_f32_e32 v9, v9
	s_nop 0
	v_pk_mul_f32 v[2:3], v[2:3], v[8:9]
	s_nop 0
	v_pk_mul_f32 v[8:9], v[4:5], v[2:3]
	v_cvt_pk_bf16_f32 v4, v6, v7
	v_mad_u64_u32 v[6:7], s[20:21], v14, s89, v[130:131]
	v_cvt_pk_bf16_f32 v5, v8, v9
	v_mov_b32_e32 v8, v7
	v_mad_u64_u32 v[8:9], s[20:21], v15, s89, v[8:9]
	v_cvt_pk_bf16_f32 v2, v10, v11
	v_cvt_pk_bf16_f32 v3, v12, v13
	v_mov_b32_e32 v7, v8
	s_mov_b64 s[20:21], -1
	global_store_dwordx4 v[6:7], v[2:5], off sc1
	s_cbranch_vccnz .LBB0_2071
	s_andn2_b64 vcc, exec, s[4:5]
	s_cbranch_vccnz .LBB0_2070
	s_barrier
	s_branch .LBB0_2070
